# chain-ordered MFMA pairs + mid-block setprio flips removed + redundant post-barrier lgkmcnt(0) removed in GEMM MMA blocks
# speedup vs baseline: 1.0012x; 1.0012x over previous
.LBB0_254:
	ds_read_b128 v[90:93], v86
	ds_read_b128 v[94:97], v86 offset:1024
	ds_read_b128 v[98:101], v86 offset:2048
	ds_read_b128 v[102:105], v86 offset:3072
	ds_read_b128 v[106:109], v87
	ds_read_b128 v[110:113], v87 offset:1024
	ds_read_b128 v[114:117], v87 offset:2048
	ds_read_b128 v[118:121], v87 offset:3072
	s_add_u32 s38, s36, 0xfff80080
	s_addc_u32 s39, s37, -1
	s_cmp_eq_u32 s59, 28
	s_cselect_b32 s41, s17, s39
	s_cselect_b32 s40, s16, s38
	s_cselect_b32 s39, s2, s58
	s_cselect_b32 s38, s3, s29
	s_mov_b32 m0, s57
	v_lshl_add_u64 v[80:81], s[36:37], 0, v[76:77]
	ds_read_b128 v[122:125], v88
	ds_read_b128 v[126:129], v88 offset:1024
	ds_read_b128 v[130:133], v88 offset:2048
	ds_read_b128 v[134:137], v88 offset:3072
	ds_read_b128 v[138:141], v88 offset:4096
	ds_read_b128 v[142:145], v88 offset:5120
	ds_read_b128 v[146:149], v88 offset:6144
	ds_read_b128 v[150:153], v88 offset:7168
	global_load_lds_dwordx4 v[80:81], off
	v_lshl_add_u64 v[80:81], s[36:37], 0, v[78:79]
	s_add_i32 m0, s19, 0xe000
	s_nop 0
	global_load_lds_dwordx4 v[80:81], off
	s_waitcnt vmcnt(8)
	s_waitcnt lgkmcnt(0)
	s_barrier
	s_setprio 1
	v_mfma_f32_16x16x32_bf16 v[60:63], v[90:93], v[122:125], v[60:63]
	v_mfma_f32_16x16x32_bf16 v[60:63], v[94:97], v[126:129], v[60:63]
	v_mfma_f32_16x16x32_bf16 v[52:55], v[90:93], v[130:133], v[52:55]
	v_mfma_f32_16x16x32_bf16 v[52:55], v[94:97], v[134:137], v[52:55]
	v_mfma_f32_16x16x32_bf16 v[36:39], v[90:93], v[138:141], v[36:39]
	v_mfma_f32_16x16x32_bf16 v[36:39], v[94:97], v[142:145], v[36:39]
	v_mfma_f32_16x16x32_bf16 v[20:23], v[90:93], v[146:149], v[20:23]
	v_mfma_f32_16x16x32_bf16 v[20:23], v[94:97], v[150:153], v[20:23]
	v_mfma_f32_16x16x32_bf16 v[56:59], v[98:101], v[122:125], v[56:59]
	v_mfma_f32_16x16x32_bf16 v[56:59], v[102:105], v[126:129], v[56:59]
	v_mfma_f32_16x16x32_bf16 v[48:51], v[98:101], v[130:133], v[48:51]
	v_mfma_f32_16x16x32_bf16 v[48:51], v[102:105], v[134:137], v[48:51]
	v_mfma_f32_16x16x32_bf16 v[32:35], v[98:101], v[138:141], v[32:35]
	v_mfma_f32_16x16x32_bf16 v[32:35], v[102:105], v[142:145], v[32:35]
	v_mfma_f32_16x16x32_bf16 v[16:19], v[98:101], v[146:149], v[16:19]
	v_mfma_f32_16x16x32_bf16 v[16:19], v[102:105], v[150:153], v[16:19]
	v_mfma_f32_16x16x32_bf16 v[44:47], v[106:109], v[122:125], v[44:47]
	v_mfma_f32_16x16x32_bf16 v[44:47], v[110:113], v[126:129], v[44:47]
	v_mfma_f32_16x16x32_bf16 v[28:31], v[106:109], v[130:133], v[28:31]
	v_mfma_f32_16x16x32_bf16 v[28:31], v[110:113], v[134:137], v[28:31]
	v_mfma_f32_16x16x32_bf16 v[12:15], v[106:109], v[138:141], v[12:15]
	v_mfma_f32_16x16x32_bf16 v[12:15], v[110:113], v[142:145], v[12:15]
	v_mfma_f32_16x16x32_bf16 v[4:7], v[106:109], v[146:149], v[4:7]
	v_mfma_f32_16x16x32_bf16 v[4:7], v[110:113], v[150:153], v[4:7]
	v_mfma_f32_16x16x32_bf16 v[40:43], v[114:117], v[122:125], v[40:43]
	v_mfma_f32_16x16x32_bf16 v[40:43], v[118:121], v[126:129], v[40:43]
	v_mfma_f32_16x16x32_bf16 v[24:27], v[114:117], v[130:133], v[24:27]
	v_mfma_f32_16x16x32_bf16 v[24:27], v[118:121], v[134:137], v[24:27]
	v_mfma_f32_16x16x32_bf16 v[8:11], v[114:117], v[138:141], v[8:11]
	v_mfma_f32_16x16x32_bf16 v[8:11], v[118:121], v[142:145], v[8:11]
	v_mfma_f32_16x16x32_bf16 v[0:3], v[114:117], v[146:149], v[0:3]
	v_mfma_f32_16x16x32_bf16 v[0:3], v[118:121], v[150:153], v[0:3]
	s_setprio 0
	s_barrier
	s_nop 1
	s_add_i32 s60, s55, s48
	v_lshl_add_u64 v[80:81], s[38:39], 0, v[64:65]
	s_mov_b32 m0, s60
	v_lshl_add_u64 v[154:155], s[38:39], 0, v[66:67]
	global_load_lds_dwordx4 v[80:81], off
	s_add_i32 m0, s60, 0x2000
	s_add_u32 s60, s38, 0x80000
	s_addc_u32 s61, s39, 0
	s_add_i32 s62, s56, s48
	global_load_lds_dwordx4 v[154:155], off
	v_lshl_add_u64 v[90:91], s[60:61], 0, v[64:65]
	s_mov_b32 m0, s62
	v_lshl_add_u64 v[156:157], s[40:41], 0, v[64:65]
	global_load_lds_dwordx4 v[90:91], off
	v_lshl_add_u64 v[90:91], s[60:61], 0, v[66:67]
	s_add_i32 m0, s62, 0x2000
	v_lshl_add_u64 v[158:159], s[40:41], 0, v[66:67]
	global_load_lds_dwordx4 v[90:91], off
	s_mov_b32 m0, s19
	s_nop 0
	global_load_lds_dwordx4 v[156:157], off
	s_mov_b32 m0, s49
	s_nop 0
	global_load_lds_dwordx4 v[158:159], off
	s_waitcnt vmcnt(8)
	s_waitcnt lgkmcnt(0)
	s_barrier
	s_setprio 1
	s_setprio 0
	s_setprio 1
	s_setprio 0
	s_barrier
	s_add_i32 s60, 0, 0x18000
	v_add_u32_e32 v89, s60, v84
	s_add_i32 s61, 0, 0x1c000
	ds_read_b128 v[90:93], v89
	ds_read_b128 v[94:97], v89 offset:1024
	ds_read_b128 v[98:101], v89 offset:2048
	ds_read_b128 v[102:105], v89 offset:3072
	v_add_u32_e32 v89, s61, v84
	ds_read_b128 v[106:109], v89
	ds_read_b128 v[110:113], v89 offset:1024
	ds_read_b128 v[114:117], v89 offset:2048
	ds_read_b128 v[118:121], v89 offset:3072
	s_add_u32 s40, s40, 0x80000
	s_addc_u32 s41, s41, 0
	s_mov_b32 m0, s50
	v_lshl_add_u64 v[160:161], s[40:41], 0, v[64:65]
	ds_read_b128 v[122:125], v88 offset:32768
	ds_read_b128 v[126:129], v88 offset:33792
	ds_read_b128 v[130:133], v88 offset:34816
	ds_read_b128 v[134:137], v88 offset:35840
	ds_read_b128 v[138:141], v88 offset:36864
	ds_read_b128 v[142:145], v88 offset:37888
	ds_read_b128 v[146:149], v88 offset:38912
	ds_read_b128 v[150:153], v88 offset:39936
	global_load_lds_dwordx4 v[160:161], off
	v_lshl_add_u64 v[160:161], s[40:41], 0, v[66:67]
	s_mov_b32 m0, s51
	s_nop 0
	global_load_lds_dwordx4 v[160:161], off
	s_waitcnt vmcnt(8)
	s_waitcnt lgkmcnt(0)
	s_barrier
	s_setprio 1
	v_mfma_f32_16x16x32_bf16 v[60:63], v[90:93], v[122:125], v[60:63]
	v_mfma_f32_16x16x32_bf16 v[60:63], v[94:97], v[126:129], v[60:63]
	v_mfma_f32_16x16x32_bf16 v[52:55], v[90:93], v[130:133], v[52:55]
	v_mfma_f32_16x16x32_bf16 v[52:55], v[94:97], v[134:137], v[52:55]
	v_mfma_f32_16x16x32_bf16 v[36:39], v[90:93], v[138:141], v[36:39]
	v_mfma_f32_16x16x32_bf16 v[36:39], v[94:97], v[142:145], v[36:39]
	v_mfma_f32_16x16x32_bf16 v[20:23], v[90:93], v[146:149], v[20:23]
	v_mfma_f32_16x16x32_bf16 v[20:23], v[94:97], v[150:153], v[20:23]
	v_mfma_f32_16x16x32_bf16 v[56:59], v[98:101], v[122:125], v[56:59]
	v_mfma_f32_16x16x32_bf16 v[56:59], v[102:105], v[126:129], v[56:59]
	v_mfma_f32_16x16x32_bf16 v[48:51], v[98:101], v[130:133], v[48:51]
	v_mfma_f32_16x16x32_bf16 v[48:51], v[102:105], v[134:137], v[48:51]
	v_mfma_f32_16x16x32_bf16 v[32:35], v[98:101], v[138:141], v[32:35]
	v_mfma_f32_16x16x32_bf16 v[32:35], v[102:105], v[142:145], v[32:35]
	v_mfma_f32_16x16x32_bf16 v[16:19], v[98:101], v[146:149], v[16:19]
	v_mfma_f32_16x16x32_bf16 v[16:19], v[102:105], v[150:153], v[16:19]
	v_mfma_f32_16x16x32_bf16 v[44:47], v[106:109], v[122:125], v[44:47]
	v_mfma_f32_16x16x32_bf16 v[44:47], v[110:113], v[126:129], v[44:47]
	v_mfma_f32_16x16x32_bf16 v[28:31], v[106:109], v[130:133], v[28:31]
	v_mfma_f32_16x16x32_bf16 v[28:31], v[110:113], v[134:137], v[28:31]
	v_mfma_f32_16x16x32_bf16 v[12:15], v[106:109], v[138:141], v[12:15]
	v_mfma_f32_16x16x32_bf16 v[12:15], v[110:113], v[142:145], v[12:15]
	v_mfma_f32_16x16x32_bf16 v[4:7], v[106:109], v[146:149], v[4:7]
	v_mfma_f32_16x16x32_bf16 v[4:7], v[110:113], v[150:153], v[4:7]
	v_mfma_f32_16x16x32_bf16 v[40:43], v[114:117], v[122:125], v[40:43]
	v_mfma_f32_16x16x32_bf16 v[40:43], v[118:121], v[126:129], v[40:43]
	v_mfma_f32_16x16x32_bf16 v[24:27], v[114:117], v[130:133], v[24:27]
	v_mfma_f32_16x16x32_bf16 v[24:27], v[118:121], v[134:137], v[24:27]
	v_mfma_f32_16x16x32_bf16 v[8:11], v[114:117], v[138:141], v[8:11]
	v_mfma_f32_16x16x32_bf16 v[8:11], v[118:121], v[142:145], v[8:11]
	v_mfma_f32_16x16x32_bf16 v[0:3], v[114:117], v[146:149], v[0:3]
	v_mfma_f32_16x16x32_bf16 v[0:3], v[118:121], v[150:153], v[0:3]
	s_setprio 0
	s_barrier
	s_nop 1
	s_add_i32 s40, s60, s48
	v_lshl_add_u64 v[80:81], v[80:81], 0, s[22:23]
	s_mov_b32 m0, s40
	s_nop 0
	global_load_lds_dwordx4 v[80:81], off
	s_add_i32 m0, s40, 0x2000
	s_add_u32 s38, s38, 0x80080
	v_lshl_add_u64 v[80:81], v[154:155], 0, s[22:23]
	s_addc_u32 s39, s39, 0
	s_add_i32 s40, s61, s48
	global_load_lds_dwordx4 v[80:81], off
	v_lshl_add_u64 v[80:81], s[38:39], 0, v[64:65]
	s_mov_b32 m0, s40
	s_nop 0
	global_load_lds_dwordx4 v[80:81], off
	v_lshl_add_u64 v[80:81], s[38:39], 0, v[66:67]
	s_add_i32 m0, s40, 0x2000
	s_nop 0
	global_load_lds_dwordx4 v[80:81], off
	v_lshl_add_u64 v[80:81], v[156:157], 0, s[22:23]
	s_mov_b32 m0, s53
	s_nop 0
	global_load_lds_dwordx4 v[80:81], off
	v_lshl_add_u64 v[80:81], v[158:159], 0, s[22:23]
	s_mov_b32 m0, s54
	s_nop 0
	global_load_lds_dwordx4 v[80:81], off
	s_waitcnt vmcnt(8)
	s_waitcnt lgkmcnt(0)
	s_barrier
	s_setprio 1
	s_setprio 0
	s_setprio 1
	s_setprio 0
	s_barrier
	s_add_i32 s59, s59, 2
	s_add_u32 s36, s36, 0x100
	s_addc_u32 s37, s37, 0
	s_add_u32 s29, s29, 0x100
	s_addc_u32 s58, s58, 0
	s_cmp_gt_u32 s59, 29
	s_cbranch_scc0 .LBB0_254
	s_and_b64 vcc, exec, s[24:25]
	s_cbranch_vccz .LBB0_261
	s_barrier
	v_lshl_or_b32 v80, s18, 8, v85
	v_ashrrev_i32_e32 v81, 31, v80
	s_and_saveexec_b64 s[2:3], s[10:11]
	s_cbranch_execnz .LBB0_262

.LBB0_370:
	s_add_u32 s26, s18, 0x100
	s_addc_u32 s27, s19, 0
	s_cmp_eq_u32 s5, 30
	s_cselect_b32 s31, s40, s27
	s_cselect_b32 s30, s41, s26
	s_cselect_b32 s29, s57, s75
	s_cselect_b32 s28, s4, s15
	s_add_i32 s2, 0, 0x10000
	v_add_u32_e32 v152, s2, v154
	s_add_i32 vcc_lo, 0, 0x14000
	ds_read_b128 v[140:143], v152
	ds_read_b128 v[144:147], v152 offset:1024
	ds_read_b128 v[148:151], v152 offset:2048
	ds_read_b128 v[156:159], v152 offset:3072
	v_add_u32_e32 v152, vcc_lo, v154
	ds_read_b128 v[160:163], v152
	ds_read_b128 v[164:167], v152 offset:1024
	ds_read_b128 v[168:171], v152 offset:2048
	ds_read_b128 v[172:175], v152 offset:3072
	v_lshl_add_u64 v[152:153], s[18:19], 0, v[136:137]
	s_add_i32 m0, s63, 0xc000
	ds_read_b128 v[176:179], v155
	ds_read_b128 v[180:183], v155 offset:1024
	ds_read_b128 v[184:187], v155 offset:2048
	ds_read_b128 v[188:191], v155 offset:3072
	ds_read_b128 v[192:195], v155 offset:4096
	ds_read_b128 v[196:199], v155 offset:5120
	ds_read_b128 v[200:203], v155 offset:6144
	ds_read_b128 v[204:207], v155 offset:7168
	global_load_lds_dwordx4 v[152:153], off
	v_lshl_add_u64 v[152:153], s[18:19], 0, v[138:139]
	s_add_i32 m0, s63, 0xe000
	s_nop 0
	global_load_lds_dwordx4 v[152:153], off
	s_waitcnt vmcnt(8)
	s_waitcnt lgkmcnt(0)
	s_barrier
	s_setprio 1
	v_mfma_f32_16x16x32_bf16 v[96:99], v[140:143], v[176:179], v[96:99]
	v_mfma_f32_16x16x32_bf16 v[96:99], v[144:147], v[180:183], v[96:99]
	v_mfma_f32_16x16x32_bf16 v[124:127], v[140:143], v[184:187], v[124:127]
	v_mfma_f32_16x16x32_bf16 v[124:127], v[144:147], v[188:191], v[124:127]
	v_mfma_f32_16x16x32_bf16 v[120:123], v[140:143], v[192:195], v[120:123]
	v_mfma_f32_16x16x32_bf16 v[120:123], v[144:147], v[196:199], v[120:123]
	v_mfma_f32_16x16x32_bf16 v[84:87], v[140:143], v[200:203], v[84:87]
	v_mfma_f32_16x16x32_bf16 v[84:87], v[144:147], v[204:207], v[84:87]
	v_mfma_f32_16x16x32_bf16 v[56:59], v[148:151], v[176:179], v[56:59]
	v_mfma_f32_16x16x32_bf16 v[56:59], v[156:159], v[180:183], v[56:59]
	v_mfma_f32_16x16x32_bf16 v[116:119], v[148:151], v[184:187], v[116:119]
	v_mfma_f32_16x16x32_bf16 v[116:119], v[156:159], v[188:191], v[116:119]
	v_mfma_f32_16x16x32_bf16 v[112:115], v[148:151], v[192:195], v[112:115]
	v_mfma_f32_16x16x32_bf16 v[112:115], v[156:159], v[196:199], v[112:115]
	v_mfma_f32_16x16x32_bf16 v[48:51], v[148:151], v[200:203], v[48:51]
	v_mfma_f32_16x16x32_bf16 v[48:51], v[156:159], v[204:207], v[48:51]
	v_mfma_f32_16x16x32_bf16 v[100:103], v[160:163], v[176:179], v[100:103]
	v_mfma_f32_16x16x32_bf16 v[100:103], v[164:167], v[180:183], v[100:103]
	v_mfma_f32_16x16x32_bf16 v[88:91], v[160:163], v[184:187], v[88:91]
	v_mfma_f32_16x16x32_bf16 v[88:91], v[164:167], v[188:191], v[88:91]
	v_mfma_f32_16x16x32_bf16 v[72:75], v[160:163], v[192:195], v[72:75]
	v_mfma_f32_16x16x32_bf16 v[72:75], v[164:167], v[196:199], v[72:75]
	v_mfma_f32_16x16x32_bf16 v[64:67], v[160:163], v[200:203], v[64:67]
	v_mfma_f32_16x16x32_bf16 v[64:67], v[164:167], v[204:207], v[64:67]
	v_mfma_f32_16x16x32_bf16 v[60:63], v[168:171], v[176:179], v[60:63]
	v_mfma_f32_16x16x32_bf16 v[60:63], v[172:175], v[180:183], v[60:63]
	v_mfma_f32_16x16x32_bf16 v[44:47], v[168:171], v[184:187], v[44:47]
	v_mfma_f32_16x16x32_bf16 v[44:47], v[172:175], v[188:191], v[44:47]
	v_mfma_f32_16x16x32_bf16 v[32:35], v[168:171], v[192:195], v[32:35]
	v_mfma_f32_16x16x32_bf16 v[32:35], v[172:175], v[196:199], v[32:35]
	v_mfma_f32_16x16x32_bf16 v[24:27], v[168:171], v[200:203], v[24:27]
	v_mfma_f32_16x16x32_bf16 v[24:27], v[172:175], v[204:207], v[24:27]
	s_setprio 0
	s_barrier
	s_nop 1
	s_add_i32 s2, s2, s69
	v_lshl_add_u64 v[152:153], s[28:29], 0, v[130:131]
	s_mov_b32 m0, s2
	ds_read_b128 v[176:179], v155 offset:16384
	ds_read_b128 v[180:183], v155 offset:17408
	ds_read_b128 v[184:187], v155 offset:18432
	ds_read_b128 v[188:191], v155 offset:19456
	ds_read_b128 v[192:195], v155 offset:20480
	ds_read_b128 v[196:199], v155 offset:21504
	ds_read_b128 v[200:203], v155 offset:22528
	ds_read_b128 v[204:207], v155 offset:23552
	global_load_lds_dwordx4 v[152:153], off
	s_add_i32 m0, s2, 0x2000
	s_add_u32 s2, s28, 0x80000
	v_lshl_add_u64 v[208:209], s[28:29], 0, v[134:135]
	s_addc_u32 s3, s29, 0
	s_add_i32 s18, vcc_lo, s69
	global_load_lds_dwordx4 v[208:209], off
	v_lshl_add_u64 v[210:211], s[2:3], 0, v[130:131]
	s_mov_b32 m0, s18
	v_lshl_add_u64 v[214:215], s[30:31], 0, v[132:133]
	global_load_lds_dwordx4 v[210:211], off
	v_lshl_add_u64 v[210:211], s[2:3], 0, v[134:135]
	s_add_i32 m0, s18, 0x2000
	s_nop 0
	global_load_lds_dwordx4 v[210:211], off
	v_lshl_add_u64 v[210:211], s[30:31], 0, v[128:129]
	s_mov_b32 m0, s63
	s_nop 0
	global_load_lds_dwordx4 v[210:211], off
	s_mov_b32 m0, s70
	s_nop 0
	global_load_lds_dwordx4 v[214:215], off
	s_waitcnt vmcnt(8)
	s_waitcnt lgkmcnt(0)
	s_barrier
	s_setprio 1
	v_mfma_f32_16x16x32_bf16 v[92:95], v[140:143], v[176:179], v[92:95]
	v_mfma_f32_16x16x32_bf16 v[92:95], v[144:147], v[180:183], v[92:95]
	v_mfma_f32_16x16x32_bf16 v[108:111], v[140:143], v[184:187], v[108:111]
	v_mfma_f32_16x16x32_bf16 v[108:111], v[144:147], v[188:191], v[108:111]
	v_mfma_f32_16x16x32_bf16 v[104:107], v[140:143], v[192:195], v[104:107]
	v_mfma_f32_16x16x32_bf16 v[104:107], v[144:147], v[196:199], v[104:107]
	v_mfma_f32_16x16x32_bf16 v[76:79], v[140:143], v[200:203], v[76:79]
	v_mfma_f32_16x16x32_bf16 v[76:79], v[144:147], v[204:207], v[76:79]
	v_mfma_f32_16x16x32_bf16 v[52:55], v[148:151], v[176:179], v[52:55]
	v_mfma_f32_16x16x32_bf16 v[52:55], v[156:159], v[180:183], v[52:55]
	v_mfma_f32_16x16x32_bf16 v[80:83], v[148:151], v[184:187], v[80:83]
	v_mfma_f32_16x16x32_bf16 v[80:83], v[156:159], v[188:191], v[80:83]
	v_mfma_f32_16x16x32_bf16 v[68:71], v[148:151], v[192:195], v[68:71]
	v_mfma_f32_16x16x32_bf16 v[68:71], v[156:159], v[196:199], v[68:71]
	v_mfma_f32_16x16x32_bf16 v[36:39], v[148:151], v[200:203], v[36:39]
	v_mfma_f32_16x16x32_bf16 v[36:39], v[156:159], v[204:207], v[36:39]
	v_mfma_f32_16x16x32_bf16 v[40:43], v[160:163], v[176:179], v[40:43]
	v_mfma_f32_16x16x32_bf16 v[40:43], v[164:167], v[180:183], v[40:43]
	v_mfma_f32_16x16x32_bf16 v[28:31], v[160:163], v[184:187], v[28:31]
	v_mfma_f32_16x16x32_bf16 v[28:31], v[164:167], v[188:191], v[28:31]
	v_mfma_f32_16x16x32_bf16 v[20:23], v[160:163], v[192:195], v[20:23]
	v_mfma_f32_16x16x32_bf16 v[20:23], v[164:167], v[196:199], v[20:23]
	v_mfma_f32_16x16x32_bf16 v[16:19], v[160:163], v[200:203], v[16:19]
	v_mfma_f32_16x16x32_bf16 v[16:19], v[164:167], v[204:207], v[16:19]
	v_mfma_f32_16x16x32_bf16 v[12:15], v[168:171], v[176:179], v[12:15]
	v_mfma_f32_16x16x32_bf16 v[12:15], v[172:175], v[180:183], v[12:15]
	v_mfma_f32_16x16x32_bf16 v[8:11], v[168:171], v[184:187], v[8:11]
	v_mfma_f32_16x16x32_bf16 v[8:11], v[172:175], v[188:191], v[8:11]
	v_mfma_f32_16x16x32_bf16 v[4:7], v[168:171], v[192:195], v[4:7]
	v_mfma_f32_16x16x32_bf16 v[4:7], v[172:175], v[196:199], v[4:7]
	v_mfma_f32_16x16x32_bf16 v[0:3], v[168:171], v[200:203], v[0:3]
	v_mfma_f32_16x16x32_bf16 v[0:3], v[172:175], v[204:207], v[0:3]
	s_setprio 0
	s_barrier
	s_nop 1
	s_add_i32 s18, 0, 0x18000
	s_add_i32 s19, 0, 0x1c000
	v_add_u32_e32 v156, s18, v154
	v_add_u32_e32 v172, s19, v154
	ds_read_b128 v[140:143], v156
	ds_read_b128 v[144:147], v156 offset:1024
	ds_read_b128 v[148:151], v156 offset:2048
	ds_read_b128 v[156:159], v156 offset:3072
	ds_read_b128 v[160:163], v172
	ds_read_b128 v[164:167], v172 offset:1024
	ds_read_b128 v[168:171], v172 offset:2048
	ds_read_b128 v[172:175], v172 offset:3072
	s_add_u32 s2, s30, 0x80000
	s_addc_u32 s3, s31, 0
	s_mov_b32 m0, s71
	v_lshl_add_u64 v[216:217], s[2:3], 0, v[128:129]
	ds_read_b128 v[176:179], v155 offset:32768
	ds_read_b128 v[180:183], v155 offset:33792
	ds_read_b128 v[184:187], v155 offset:34816
	ds_read_b128 v[188:191], v155 offset:35840
	ds_read_b128 v[192:195], v155 offset:36864
	ds_read_b128 v[196:199], v155 offset:37888
	ds_read_b128 v[200:203], v155 offset:38912
	ds_read_b128 v[204:207], v155 offset:39936
	global_load_lds_dwordx4 v[216:217], off
	v_lshl_add_u64 v[216:217], s[2:3], 0, v[132:133]
	s_mov_b32 m0, s76
	s_nop 0
	global_load_lds_dwordx4 v[216:217], off
	s_waitcnt vmcnt(8)
	s_waitcnt lgkmcnt(0)
	s_barrier
	s_setprio 1
	v_mfma_f32_16x16x32_bf16 v[96:99], v[140:143], v[176:179], v[96:99]
	v_mfma_f32_16x16x32_bf16 v[96:99], v[144:147], v[180:183], v[96:99]
	v_mfma_f32_16x16x32_bf16 v[124:127], v[140:143], v[184:187], v[124:127]
	v_mfma_f32_16x16x32_bf16 v[124:127], v[144:147], v[188:191], v[124:127]
	v_mfma_f32_16x16x32_bf16 v[120:123], v[140:143], v[192:195], v[120:123]
	v_mfma_f32_16x16x32_bf16 v[120:123], v[144:147], v[196:199], v[120:123]
	v_mfma_f32_16x16x32_bf16 v[84:87], v[140:143], v[200:203], v[84:87]
	v_mfma_f32_16x16x32_bf16 v[84:87], v[144:147], v[204:207], v[84:87]
	v_mfma_f32_16x16x32_bf16 v[56:59], v[148:151], v[176:179], v[56:59]
	v_mfma_f32_16x16x32_bf16 v[56:59], v[156:159], v[180:183], v[56:59]
	v_mfma_f32_16x16x32_bf16 v[116:119], v[148:151], v[184:187], v[116:119]
	v_mfma_f32_16x16x32_bf16 v[116:119], v[156:159], v[188:191], v[116:119]
	v_mfma_f32_16x16x32_bf16 v[112:115], v[148:151], v[192:195], v[112:115]
	v_mfma_f32_16x16x32_bf16 v[112:115], v[156:159], v[196:199], v[112:115]
	v_mfma_f32_16x16x32_bf16 v[48:51], v[148:151], v[200:203], v[48:51]
	v_mfma_f32_16x16x32_bf16 v[48:51], v[156:159], v[204:207], v[48:51]
	v_mfma_f32_16x16x32_bf16 v[100:103], v[160:163], v[176:179], v[100:103]
	v_mfma_f32_16x16x32_bf16 v[100:103], v[164:167], v[180:183], v[100:103]
	v_mfma_f32_16x16x32_bf16 v[88:91], v[160:163], v[184:187], v[88:91]
	v_mfma_f32_16x16x32_bf16 v[88:91], v[164:167], v[188:191], v[88:91]
	v_mfma_f32_16x16x32_bf16 v[72:75], v[160:163], v[192:195], v[72:75]
	v_mfma_f32_16x16x32_bf16 v[72:75], v[164:167], v[196:199], v[72:75]
	v_mfma_f32_16x16x32_bf16 v[64:67], v[160:163], v[200:203], v[64:67]
	v_mfma_f32_16x16x32_bf16 v[64:67], v[164:167], v[204:207], v[64:67]
	v_mfma_f32_16x16x32_bf16 v[60:63], v[168:171], v[176:179], v[60:63]
	v_mfma_f32_16x16x32_bf16 v[60:63], v[172:175], v[180:183], v[60:63]
	v_mfma_f32_16x16x32_bf16 v[44:47], v[168:171], v[184:187], v[44:47]
	v_mfma_f32_16x16x32_bf16 v[44:47], v[172:175], v[188:191], v[44:47]
	v_mfma_f32_16x16x32_bf16 v[32:35], v[168:171], v[192:195], v[32:35]
	v_mfma_f32_16x16x32_bf16 v[32:35], v[172:175], v[196:199], v[32:35]
	v_mfma_f32_16x16x32_bf16 v[24:27], v[168:171], v[200:203], v[24:27]
	v_mfma_f32_16x16x32_bf16 v[24:27], v[172:175], v[204:207], v[24:27]
	s_setprio 0
	s_barrier
	s_nop 1
	s_add_i32 s2, s18, s69
	v_lshl_add_u64 v[152:153], v[152:153], 0, s[72:73]
	s_mov_b32 m0, s2
	ds_read_b128 v[176:179], v155 offset:49152
	ds_read_b128 v[180:183], v155 offset:50176
	ds_read_b128 v[184:187], v155 offset:51200
	ds_read_b128 v[188:191], v155 offset:52224
	ds_read_b128 v[192:195], v155 offset:53248
	ds_read_b128 v[196:199], v155 offset:54272
	ds_read_b128 v[200:203], v155 offset:55296
	ds_read_b128 v[204:207], v155 offset:56320
	global_load_lds_dwordx4 v[152:153], off
	s_add_i32 m0, s2, 0x2000
	s_add_u32 s2, s28, 0x80080
	v_lshl_add_u64 v[152:153], v[208:209], 0, s[72:73]
	s_addc_u32 s3, s29, 0
	s_add_i32 s18, s19, s69
	global_load_lds_dwordx4 v[152:153], off
	v_lshl_add_u64 v[152:153], s[2:3], 0, v[130:131]
	s_mov_b32 m0, s18
	s_nop 0
	global_load_lds_dwordx4 v[152:153], off
	v_lshl_add_u64 v[152:153], s[2:3], 0, v[134:135]
	s_add_i32 m0, s18, 0x2000
	s_nop 0
	global_load_lds_dwordx4 v[152:153], off
	v_lshl_add_u64 v[152:153], v[210:211], 0, s[72:73]
	s_mov_b32 m0, s87
	s_nop 0
	global_load_lds_dwordx4 v[152:153], off
	v_lshl_add_u64 v[152:153], v[214:215], 0, s[72:73]
	s_mov_b32 m0, s88
	s_nop 0
	global_load_lds_dwordx4 v[152:153], off
	s_waitcnt vmcnt(8)
	s_waitcnt lgkmcnt(0)
	s_barrier
	s_setprio 1
	v_mfma_f32_16x16x32_bf16 v[92:95], v[140:143], v[176:179], v[92:95]
	v_mfma_f32_16x16x32_bf16 v[92:95], v[144:147], v[180:183], v[92:95]
	v_mfma_f32_16x16x32_bf16 v[108:111], v[140:143], v[184:187], v[108:111]
	v_mfma_f32_16x16x32_bf16 v[108:111], v[144:147], v[188:191], v[108:111]
	v_mfma_f32_16x16x32_bf16 v[104:107], v[140:143], v[192:195], v[104:107]
	v_mfma_f32_16x16x32_bf16 v[104:107], v[144:147], v[196:199], v[104:107]
	v_mfma_f32_16x16x32_bf16 v[76:79], v[140:143], v[200:203], v[76:79]
	v_mfma_f32_16x16x32_bf16 v[76:79], v[144:147], v[204:207], v[76:79]
	v_mfma_f32_16x16x32_bf16 v[52:55], v[148:151], v[176:179], v[52:55]
	v_mfma_f32_16x16x32_bf16 v[52:55], v[156:159], v[180:183], v[52:55]
	v_mfma_f32_16x16x32_bf16 v[80:83], v[148:151], v[184:187], v[80:83]
	v_mfma_f32_16x16x32_bf16 v[80:83], v[156:159], v[188:191], v[80:83]
	v_mfma_f32_16x16x32_bf16 v[68:71], v[148:151], v[192:195], v[68:71]
	v_mfma_f32_16x16x32_bf16 v[68:71], v[156:159], v[196:199], v[68:71]
	v_mfma_f32_16x16x32_bf16 v[36:39], v[148:151], v[200:203], v[36:39]
	v_mfma_f32_16x16x32_bf16 v[36:39], v[156:159], v[204:207], v[36:39]
	v_mfma_f32_16x16x32_bf16 v[40:43], v[160:163], v[176:179], v[40:43]
	v_mfma_f32_16x16x32_bf16 v[40:43], v[164:167], v[180:183], v[40:43]
	v_mfma_f32_16x16x32_bf16 v[28:31], v[160:163], v[184:187], v[28:31]
	v_mfma_f32_16x16x32_bf16 v[28:31], v[164:167], v[188:191], v[28:31]
	v_mfma_f32_16x16x32_bf16 v[20:23], v[160:163], v[192:195], v[20:23]
	v_mfma_f32_16x16x32_bf16 v[20:23], v[164:167], v[196:199], v[20:23]
	v_mfma_f32_16x16x32_bf16 v[16:19], v[160:163], v[200:203], v[16:19]
	v_mfma_f32_16x16x32_bf16 v[16:19], v[164:167], v[204:207], v[16:19]
	v_mfma_f32_16x16x32_bf16 v[12:15], v[168:171], v[176:179], v[12:15]
	v_mfma_f32_16x16x32_bf16 v[12:15], v[172:175], v[180:183], v[12:15]
	v_mfma_f32_16x16x32_bf16 v[8:11], v[168:171], v[184:187], v[8:11]
	v_mfma_f32_16x16x32_bf16 v[8:11], v[172:175], v[188:191], v[8:11]
	v_mfma_f32_16x16x32_bf16 v[4:7], v[168:171], v[192:195], v[4:7]
	v_mfma_f32_16x16x32_bf16 v[4:7], v[172:175], v[196:199], v[4:7]
	v_mfma_f32_16x16x32_bf16 v[0:3], v[168:171], v[200:203], v[0:3]
	v_mfma_f32_16x16x32_bf16 v[0:3], v[172:175], v[204:207], v[0:3]
	s_setprio 0
	s_barrier
	s_nop 1
	s_add_i32 s2, s5, 2
	s_add_u32 s15, s15, 0x100
	s_addc_u32 s75, s75, 0
	s_cmp_gt_u32 s5, 29
	s_mov_b64 s[18:19], s[26:27]
	s_mov_b32 s5, s2
	s_cbranch_scc1 .LBB0_384

.LBB0_486:
	s_add_u32 s18, s16, 0xfff80080
	s_addc_u32 s19, s17, -1
	s_add_i32 s46, 0, 0x10000
	s_cmp_eq_u32 s37, 28
	s_cselect_b32 s21, s5, s19
	s_cselect_b32 s20, s4, s18
	v_add_u32_e32 v78, s46, v80
	s_cselect_b32 s19, s3, s36
	s_cselect_b32 s18, s7, s35
	s_add_i32 s49, 0, 0x14000
	ds_read_b128 v[84:87], v78
	ds_read_b128 v[88:91], v78 offset:1024
	ds_read_b128 v[92:95], v78 offset:2048
	ds_read_b128 v[96:99], v78 offset:3072
	v_add_u32_e32 v78, s49, v80
	ds_read_b128 v[100:103], v78
	ds_read_b128 v[104:107], v78 offset:1024
	ds_read_b128 v[108:111], v78 offset:2048
	ds_read_b128 v[112:115], v78 offset:3072
	v_lshl_add_u64 v[78:79], s[16:17], 0, v[74:75]
	s_add_i32 m0, s25, 0xc000
	ds_read_b128 v[116:119], v82
	ds_read_b128 v[120:123], v82 offset:1024
	ds_read_b128 v[124:127], v82 offset:2048
	ds_read_b128 v[128:131], v82 offset:3072
	ds_read_b128 v[132:135], v82 offset:4096
	ds_read_b128 v[136:139], v82 offset:5120
	ds_read_b128 v[140:143], v82 offset:6144
	ds_read_b128 v[144:147], v82 offset:7168
	global_load_lds_dwordx4 v[78:79], off
	v_lshl_add_u64 v[78:79], s[16:17], 0, v[76:77]
	s_add_i32 m0, s25, 0xe000
	s_nop 0
	global_load_lds_dwordx4 v[78:79], off
	s_waitcnt vmcnt(8)
	s_waitcnt lgkmcnt(0)
	s_barrier
	s_setprio 1
	v_mfma_f32_16x16x32_bf16 v[60:63], v[84:87], v[116:119], v[60:63]
	v_mfma_f32_16x16x32_bf16 v[60:63], v[88:91], v[120:123], v[60:63]
	v_mfma_f32_16x16x32_bf16 v[52:55], v[84:87], v[124:127], v[52:55]
	v_mfma_f32_16x16x32_bf16 v[52:55], v[88:91], v[128:131], v[52:55]
	v_mfma_f32_16x16x32_bf16 v[36:39], v[84:87], v[132:135], v[36:39]
	v_mfma_f32_16x16x32_bf16 v[36:39], v[88:91], v[136:139], v[36:39]
	v_mfma_f32_16x16x32_bf16 v[20:23], v[84:87], v[140:143], v[20:23]
	v_mfma_f32_16x16x32_bf16 v[20:23], v[88:91], v[144:147], v[20:23]
	v_mfma_f32_16x16x32_bf16 v[56:59], v[92:95], v[116:119], v[56:59]
	v_mfma_f32_16x16x32_bf16 v[56:59], v[96:99], v[120:123], v[56:59]
	v_mfma_f32_16x16x32_bf16 v[48:51], v[92:95], v[124:127], v[48:51]
	v_mfma_f32_16x16x32_bf16 v[48:51], v[96:99], v[128:131], v[48:51]
	v_mfma_f32_16x16x32_bf16 v[32:35], v[92:95], v[132:135], v[32:35]
	v_mfma_f32_16x16x32_bf16 v[32:35], v[96:99], v[136:139], v[32:35]
	v_mfma_f32_16x16x32_bf16 v[16:19], v[92:95], v[140:143], v[16:19]
	v_mfma_f32_16x16x32_bf16 v[16:19], v[96:99], v[144:147], v[16:19]
	v_mfma_f32_16x16x32_bf16 v[44:47], v[100:103], v[116:119], v[44:47]
	v_mfma_f32_16x16x32_bf16 v[44:47], v[104:107], v[120:123], v[44:47]
	v_mfma_f32_16x16x32_bf16 v[28:31], v[100:103], v[124:127], v[28:31]
	v_mfma_f32_16x16x32_bf16 v[28:31], v[104:107], v[128:131], v[28:31]
	v_mfma_f32_16x16x32_bf16 v[12:15], v[100:103], v[132:135], v[12:15]
	v_mfma_f32_16x16x32_bf16 v[12:15], v[104:107], v[136:139], v[12:15]
	v_mfma_f32_16x16x32_bf16 v[4:7], v[100:103], v[140:143], v[4:7]
	v_mfma_f32_16x16x32_bf16 v[4:7], v[104:107], v[144:147], v[4:7]
	v_mfma_f32_16x16x32_bf16 v[40:43], v[108:111], v[116:119], v[40:43]
	v_mfma_f32_16x16x32_bf16 v[40:43], v[112:115], v[120:123], v[40:43]
	v_mfma_f32_16x16x32_bf16 v[24:27], v[108:111], v[124:127], v[24:27]
	v_mfma_f32_16x16x32_bf16 v[24:27], v[112:115], v[128:131], v[24:27]
	v_mfma_f32_16x16x32_bf16 v[8:11], v[108:111], v[132:135], v[8:11]
	v_mfma_f32_16x16x32_bf16 v[8:11], v[112:115], v[136:139], v[8:11]
	v_mfma_f32_16x16x32_bf16 v[0:3], v[108:111], v[140:143], v[0:3]
	v_mfma_f32_16x16x32_bf16 v[0:3], v[112:115], v[144:147], v[0:3]
	s_setprio 0
	s_barrier
	s_nop 1
	s_add_i32 s46, s46, s24
	v_lshl_add_u64 v[78:79], s[18:19], 0, v[212:213]
	s_mov_b32 m0, s46
	v_lshl_add_u64 v[148:149], s[18:19], 0, v[64:65]
	global_load_lds_dwordx4 v[78:79], off
	s_add_i32 m0, s46, 0x2000
	s_add_u32 s46, s18, 0x80000
	s_addc_u32 s47, s19, 0
	s_add_i32 s49, s49, s24
	global_load_lds_dwordx4 v[148:149], off
	v_lshl_add_u64 v[84:85], s[46:47], 0, v[212:213]
	s_mov_b32 m0, s49
	v_lshl_add_u64 v[150:151], s[20:21], 0, v[212:213]
	global_load_lds_dwordx4 v[84:85], off
	v_lshl_add_u64 v[84:85], s[46:47], 0, v[64:65]
	s_add_i32 m0, s49, 0x2000
	v_lshl_add_u64 v[152:153], s[20:21], 0, v[64:65]
	global_load_lds_dwordx4 v[84:85], off
	s_mov_b32 m0, s25
	s_nop 0
	global_load_lds_dwordx4 v[150:151], off
	s_mov_b32 m0, s28
	s_nop 0
	global_load_lds_dwordx4 v[152:153], off
	s_waitcnt vmcnt(8)
	s_waitcnt lgkmcnt(0)
	s_barrier
	s_setprio 1
	s_setprio 0
	s_setprio 1
	s_setprio 0
	s_barrier
	s_add_i32 s46, 0, 0x18000
	v_add_u32_e32 v83, s46, v80
	s_add_i32 s47, 0, 0x1c000
	ds_read_b128 v[84:87], v83
	ds_read_b128 v[88:91], v83 offset:1024
	ds_read_b128 v[92:95], v83 offset:2048
	ds_read_b128 v[96:99], v83 offset:3072
	v_add_u32_e32 v83, s47, v80
	ds_read_b128 v[100:103], v83
	ds_read_b128 v[104:107], v83 offset:1024
	ds_read_b128 v[108:111], v83 offset:2048
	ds_read_b128 v[112:115], v83 offset:3072
	s_add_u32 s20, s20, 0x80000
	s_addc_u32 s21, s21, 0
	s_mov_b32 m0, s29
	v_lshl_add_u64 v[154:155], s[20:21], 0, v[212:213]
	ds_read_b128 v[116:119], v82 offset:32768
	ds_read_b128 v[120:123], v82 offset:33792
	ds_read_b128 v[124:127], v82 offset:34816
	ds_read_b128 v[128:131], v82 offset:35840
	ds_read_b128 v[132:135], v82 offset:36864
	ds_read_b128 v[136:139], v82 offset:37888
	ds_read_b128 v[140:143], v82 offset:38912
	ds_read_b128 v[144:147], v82 offset:39936
	global_load_lds_dwordx4 v[154:155], off
	v_lshl_add_u64 v[154:155], s[20:21], 0, v[64:65]
	s_mov_b32 m0, s30
	s_nop 0
	global_load_lds_dwordx4 v[154:155], off
	s_waitcnt vmcnt(8)
	s_waitcnt lgkmcnt(0)
	s_barrier
	s_setprio 1
	v_mfma_f32_16x16x32_bf16 v[60:63], v[84:87], v[116:119], v[60:63]
	v_mfma_f32_16x16x32_bf16 v[60:63], v[88:91], v[120:123], v[60:63]
	v_mfma_f32_16x16x32_bf16 v[52:55], v[84:87], v[124:127], v[52:55]
	v_mfma_f32_16x16x32_bf16 v[52:55], v[88:91], v[128:131], v[52:55]
	v_mfma_f32_16x16x32_bf16 v[36:39], v[84:87], v[132:135], v[36:39]
	v_mfma_f32_16x16x32_bf16 v[36:39], v[88:91], v[136:139], v[36:39]
	v_mfma_f32_16x16x32_bf16 v[20:23], v[84:87], v[140:143], v[20:23]
	v_mfma_f32_16x16x32_bf16 v[20:23], v[88:91], v[144:147], v[20:23]
	v_mfma_f32_16x16x32_bf16 v[56:59], v[92:95], v[116:119], v[56:59]
	v_mfma_f32_16x16x32_bf16 v[56:59], v[96:99], v[120:123], v[56:59]
	v_mfma_f32_16x16x32_bf16 v[48:51], v[92:95], v[124:127], v[48:51]
	v_mfma_f32_16x16x32_bf16 v[48:51], v[96:99], v[128:131], v[48:51]
	v_mfma_f32_16x16x32_bf16 v[32:35], v[92:95], v[132:135], v[32:35]
	v_mfma_f32_16x16x32_bf16 v[32:35], v[96:99], v[136:139], v[32:35]
	v_mfma_f32_16x16x32_bf16 v[16:19], v[92:95], v[140:143], v[16:19]
	v_mfma_f32_16x16x32_bf16 v[16:19], v[96:99], v[144:147], v[16:19]
	v_mfma_f32_16x16x32_bf16 v[44:47], v[100:103], v[116:119], v[44:47]
	v_mfma_f32_16x16x32_bf16 v[44:47], v[104:107], v[120:123], v[44:47]
	v_mfma_f32_16x16x32_bf16 v[28:31], v[100:103], v[124:127], v[28:31]
	v_mfma_f32_16x16x32_bf16 v[28:31], v[104:107], v[128:131], v[28:31]
	v_mfma_f32_16x16x32_bf16 v[12:15], v[100:103], v[132:135], v[12:15]
	v_mfma_f32_16x16x32_bf16 v[12:15], v[104:107], v[136:139], v[12:15]
	v_mfma_f32_16x16x32_bf16 v[4:7], v[100:103], v[140:143], v[4:7]
	v_mfma_f32_16x16x32_bf16 v[4:7], v[104:107], v[144:147], v[4:7]
	v_mfma_f32_16x16x32_bf16 v[40:43], v[108:111], v[116:119], v[40:43]
	v_mfma_f32_16x16x32_bf16 v[40:43], v[112:115], v[120:123], v[40:43]
	v_mfma_f32_16x16x32_bf16 v[24:27], v[108:111], v[124:127], v[24:27]
	v_mfma_f32_16x16x32_bf16 v[24:27], v[112:115], v[128:131], v[24:27]
	v_mfma_f32_16x16x32_bf16 v[8:11], v[108:111], v[132:135], v[8:11]
	v_mfma_f32_16x16x32_bf16 v[8:11], v[112:115], v[136:139], v[8:11]
	v_mfma_f32_16x16x32_bf16 v[0:3], v[108:111], v[140:143], v[0:3]
	v_mfma_f32_16x16x32_bf16 v[0:3], v[112:115], v[144:147], v[0:3]
	s_setprio 0
	s_barrier
	s_nop 1
	s_add_i32 s20, s46, s24
	v_lshl_add_u64 v[78:79], v[78:79], 0, s[72:73]
	s_mov_b32 m0, s20
	s_nop 0
	global_load_lds_dwordx4 v[78:79], off
	s_add_i32 m0, s20, 0x2000
	s_add_u32 s18, s18, 0x80080
	v_lshl_add_u64 v[78:79], v[148:149], 0, s[72:73]
	s_addc_u32 s19, s19, 0
	s_add_i32 s20, s47, s24
	global_load_lds_dwordx4 v[78:79], off
	v_lshl_add_u64 v[78:79], s[18:19], 0, v[212:213]
	s_mov_b32 m0, s20
	s_nop 0
	global_load_lds_dwordx4 v[78:79], off
	v_lshl_add_u64 v[78:79], s[18:19], 0, v[64:65]
	s_add_i32 m0, s20, 0x2000
	s_nop 0
	global_load_lds_dwordx4 v[78:79], off
	v_lshl_add_u64 v[78:79], v[150:151], 0, s[72:73]
	s_mov_b32 m0, s31
	s_nop 0
	global_load_lds_dwordx4 v[78:79], off
	v_lshl_add_u64 v[78:79], v[152:153], 0, s[72:73]
	s_mov_b32 m0, s33
	s_nop 0
	global_load_lds_dwordx4 v[78:79], off
	s_waitcnt vmcnt(8)
	s_waitcnt lgkmcnt(0)
	s_barrier
	s_setprio 1
	s_setprio 0
	s_setprio 1
	s_setprio 0
	s_barrier
	s_add_i32 s37, s37, 2
	s_add_u32 s16, s16, 0x100
	s_addc_u32 s17, s17, 0
	s_add_u32 s35, s35, 0x100
	s_addc_u32 s36, s36, 0
	s_cmp_gt_u32 s37, 29
	s_cbranch_scc0 .LBB0_486
	s_and_b64 vcc, exec, s[12:13]
	s_cbranch_vccz .LBB0_493
	s_barrier
	v_lshl_or_b32 v78, s2, 8, v81
	v_ashrrev_i32_e32 v79, 31, v78
	s_and_saveexec_b64 s[2:3], s[38:39]
	s_cbranch_execnz .LBB0_494

.LBB0_659:
	s_add_i32 s2, s41, 2
	s_add_u32 s3, s10, s34
	s_addc_u32 s50, s11, s35
	s_add_u32 s3, s3, 0x100
	s_addc_u32 s50, s50, 0
	s_add_u32 s51, s9, s34
	s_addc_u32 s75, s19, s35
	s_cmp_eq_u32 s45, s41
	s_cselect_b32 s89, s17, s50
	s_cselect_b32 s88, s16, s3
	s_cselect_b32 vcc_hi, s13, s75
	s_cselect_b32 vcc_lo, s12, s51
	s_add_i32 s3, 0, 0x10000
	s_add_i32 s41, 0, 0x14000
	v_add_u32_e32 v136, s3, v220
	v_add_u32_e32 v160, s41, v220
	ds_read_b128 v[108:111], v136
	ds_read_b128 v[120:123], v136 offset:1024
	ds_read_b128 v[132:135], v136 offset:2048
	ds_read_b128 v[136:139], v136 offset:3072
	ds_read_b128 v[140:143], v160
	ds_read_b128 v[144:147], v160 offset:1024
	ds_read_b128 v[148:151], v160 offset:2048
	ds_read_b128 v[160:163], v160 offset:3072
	v_lshl_add_u64 v[196:197], v[96:97], 0, s[34:35]
	s_add_i32 m0, s15, 0xc000
	ds_read_b128 v[164:167], v223
	ds_read_b128 v[168:171], v223 offset:1024
	ds_read_b128 v[172:175], v223 offset:2048
	ds_read_b128 v[176:179], v223 offset:3072
	ds_read_b128 v[180:183], v223 offset:4096
	ds_read_b128 v[184:187], v223 offset:5120
	ds_read_b128 v[188:191], v223 offset:6144
	ds_read_b128 v[192:195], v223 offset:7168
	global_load_lds_dwordx4 v[196:197], off
	v_lshl_add_u64 v[196:197], v[98:99], 0, s[34:35]
	s_add_i32 m0, s15, 0xe000
	s_nop 0
	global_load_lds_dwordx4 v[196:197], off
	s_waitcnt vmcnt(8)
	s_waitcnt lgkmcnt(0)
	s_barrier
	s_setprio 1
	v_mfma_f32_16x16x32_bf16 v[156:159], v[108:111], v[164:167], v[156:159]
	v_mfma_f32_16x16x32_bf16 v[156:159], v[120:123], v[168:171], v[156:159]
	v_mfma_f32_16x16x32_bf16 v[128:131], v[108:111], v[172:175], v[128:131]
	v_mfma_f32_16x16x32_bf16 v[128:131], v[120:123], v[176:179], v[128:131]
	v_mfma_f32_16x16x32_bf16 v[116:119], v[108:111], v[180:183], v[116:119]
	v_mfma_f32_16x16x32_bf16 v[116:119], v[120:123], v[184:187], v[116:119]
	v_mfma_f32_16x16x32_bf16 v[104:107], v[108:111], v[188:191], v[104:107]
	v_mfma_f32_16x16x32_bf16 v[104:107], v[120:123], v[192:195], v[104:107]
	v_mfma_f32_16x16x32_bf16 v[152:155], v[132:135], v[164:167], v[152:155]
	v_mfma_f32_16x16x32_bf16 v[152:155], v[136:139], v[168:171], v[152:155]
	v_mfma_f32_16x16x32_bf16 v[124:127], v[132:135], v[172:175], v[124:127]
	v_mfma_f32_16x16x32_bf16 v[124:127], v[136:139], v[176:179], v[124:127]
	v_mfma_f32_16x16x32_bf16 v[112:115], v[132:135], v[180:183], v[112:115]
	v_mfma_f32_16x16x32_bf16 v[112:115], v[136:139], v[184:187], v[112:115]
	v_mfma_f32_16x16x32_bf16 v[100:103], v[132:135], v[188:191], v[100:103]
	v_mfma_f32_16x16x32_bf16 v[100:103], v[136:139], v[192:195], v[100:103]
	v_mfma_f32_16x16x32_bf16 v[92:95], v[140:143], v[164:167], v[92:95]
	v_mfma_f32_16x16x32_bf16 v[92:95], v[144:147], v[168:171], v[92:95]
	v_mfma_f32_16x16x32_bf16 v[84:87], v[140:143], v[172:175], v[84:87]
	v_mfma_f32_16x16x32_bf16 v[84:87], v[144:147], v[176:179], v[84:87]
	v_mfma_f32_16x16x32_bf16 v[76:79], v[140:143], v[180:183], v[76:79]
	v_mfma_f32_16x16x32_bf16 v[76:79], v[144:147], v[184:187], v[76:79]
	v_mfma_f32_16x16x32_bf16 v[68:71], v[140:143], v[188:191], v[68:71]
	v_mfma_f32_16x16x32_bf16 v[68:71], v[144:147], v[192:195], v[68:71]
	v_mfma_f32_16x16x32_bf16 v[88:91], v[148:151], v[164:167], v[88:91]
	v_mfma_f32_16x16x32_bf16 v[88:91], v[160:163], v[168:171], v[88:91]
	v_mfma_f32_16x16x32_bf16 v[80:83], v[148:151], v[172:175], v[80:83]
	v_mfma_f32_16x16x32_bf16 v[80:83], v[160:163], v[176:179], v[80:83]
	v_mfma_f32_16x16x32_bf16 v[72:75], v[148:151], v[180:183], v[72:75]
	v_mfma_f32_16x16x32_bf16 v[72:75], v[160:163], v[184:187], v[72:75]
	v_mfma_f32_16x16x32_bf16 v[64:67], v[148:151], v[188:191], v[64:67]
	v_mfma_f32_16x16x32_bf16 v[64:67], v[160:163], v[192:195], v[64:67]
	s_setprio 0
	s_barrier
	s_nop 1
	s_add_i32 s3, s3, s64
	v_lshl_add_u64 v[196:197], vcc, 0, v[212:213]
	s_mov_b32 m0, s3
	ds_read_b128 v[164:167], v223 offset:16384
	ds_read_b128 v[168:171], v223 offset:17408
	ds_read_b128 v[172:175], v223 offset:18432
	ds_read_b128 v[176:179], v223 offset:19456
	ds_read_b128 v[180:183], v223 offset:20480
	ds_read_b128 v[184:187], v223 offset:21504
	ds_read_b128 v[188:191], v223 offset:22528
	ds_read_b128 v[192:195], v223 offset:23552
	global_load_lds_dwordx4 v[196:197], off
	s_add_i32 m0, s3, 0x2000
	s_add_u32 s50, vcc_lo, 0x80000
	v_lshl_add_u64 v[198:199], vcc, 0, v[208:209]
	s_addc_u32 s51, vcc_hi, 0
	s_add_i32 s3, s41, s64
	global_load_lds_dwordx4 v[198:199], off
	v_lshl_add_u64 v[200:201], s[50:51], 0, v[212:213]
	s_mov_b32 m0, s3
	v_lshl_add_u64 v[202:203], s[88:89], 0, v[206:207]
	global_load_lds_dwordx4 v[200:201], off
	v_lshl_add_u64 v[200:201], s[50:51], 0, v[208:209]
	s_add_i32 m0, s3, 0x2000
	s_nop 0
	global_load_lds_dwordx4 v[200:201], off
	v_lshl_add_u64 v[200:201], s[88:89], 0, v[204:205]
	s_mov_b32 m0, s15
	s_nop 0
	global_load_lds_dwordx4 v[200:201], off
	s_mov_b32 m0, s43
	s_nop 0
	global_load_lds_dwordx4 v[202:203], off
	s_waitcnt vmcnt(8)
	s_waitcnt lgkmcnt(0)
	s_barrier
	s_setprio 1
	v_mfma_f32_16x16x32_bf16 v[60:63], v[108:111], v[164:167], v[60:63]
	v_mfma_f32_16x16x32_bf16 v[60:63], v[120:123], v[168:171], v[60:63]
	v_mfma_f32_16x16x32_bf16 v[52:55], v[108:111], v[172:175], v[52:55]
	v_mfma_f32_16x16x32_bf16 v[52:55], v[120:123], v[176:179], v[52:55]
	v_mfma_f32_16x16x32_bf16 v[44:47], v[108:111], v[180:183], v[44:47]
	v_mfma_f32_16x16x32_bf16 v[44:47], v[120:123], v[184:187], v[44:47]
	v_mfma_f32_16x16x32_bf16 v[36:39], v[108:111], v[188:191], v[36:39]
	v_mfma_f32_16x16x32_bf16 v[36:39], v[120:123], v[192:195], v[36:39]
	v_mfma_f32_16x16x32_bf16 v[56:59], v[132:135], v[164:167], v[56:59]
	v_mfma_f32_16x16x32_bf16 v[56:59], v[136:139], v[168:171], v[56:59]
	v_mfma_f32_16x16x32_bf16 v[48:51], v[132:135], v[172:175], v[48:51]
	v_mfma_f32_16x16x32_bf16 v[48:51], v[136:139], v[176:179], v[48:51]
	v_mfma_f32_16x16x32_bf16 v[40:43], v[132:135], v[180:183], v[40:43]
	v_mfma_f32_16x16x32_bf16 v[40:43], v[136:139], v[184:187], v[40:43]
	v_mfma_f32_16x16x32_bf16 v[32:35], v[132:135], v[188:191], v[32:35]
	v_mfma_f32_16x16x32_bf16 v[32:35], v[136:139], v[192:195], v[32:35]
	v_mfma_f32_16x16x32_bf16 v[28:31], v[140:143], v[164:167], v[28:31]
	v_mfma_f32_16x16x32_bf16 v[28:31], v[144:147], v[168:171], v[28:31]
	v_mfma_f32_16x16x32_bf16 v[20:23], v[140:143], v[172:175], v[20:23]
	v_mfma_f32_16x16x32_bf16 v[20:23], v[144:147], v[176:179], v[20:23]
	v_mfma_f32_16x16x32_bf16 v[12:15], v[140:143], v[180:183], v[12:15]
	v_mfma_f32_16x16x32_bf16 v[12:15], v[144:147], v[184:187], v[12:15]
	v_mfma_f32_16x16x32_bf16 v[4:7], v[140:143], v[188:191], v[4:7]
	v_mfma_f32_16x16x32_bf16 v[4:7], v[144:147], v[192:195], v[4:7]
	v_mfma_f32_16x16x32_bf16 v[24:27], v[148:151], v[164:167], v[24:27]
	v_mfma_f32_16x16x32_bf16 v[24:27], v[160:163], v[168:171], v[24:27]
	v_mfma_f32_16x16x32_bf16 v[16:19], v[148:151], v[172:175], v[16:19]
	v_mfma_f32_16x16x32_bf16 v[16:19], v[160:163], v[176:179], v[16:19]
	v_mfma_f32_16x16x32_bf16 v[8:11], v[148:151], v[180:183], v[8:11]
	v_mfma_f32_16x16x32_bf16 v[8:11], v[160:163], v[184:187], v[8:11]
	v_mfma_f32_16x16x32_bf16 v[0:3], v[148:151], v[188:191], v[0:3]
	v_mfma_f32_16x16x32_bf16 v[0:3], v[160:163], v[192:195], v[0:3]
	s_setprio 0
	s_barrier
	s_nop 1
	s_add_i32 s3, 0, 0x18000
	s_add_i32 s41, 0, 0x1c000
	v_add_u32_e32 v136, s3, v220
	v_add_u32_e32 v160, s41, v220
	ds_read_b128 v[108:111], v136
	ds_read_b128 v[120:123], v136 offset:1024
	ds_read_b128 v[132:135], v136 offset:2048
	ds_read_b128 v[136:139], v136 offset:3072
	ds_read_b128 v[140:143], v160
	ds_read_b128 v[144:147], v160 offset:1024
	ds_read_b128 v[148:151], v160 offset:2048
	ds_read_b128 v[160:163], v160 offset:3072
	s_add_u32 s50, s88, 0x80000
	s_addc_u32 s51, s89, 0
	s_mov_b32 m0, s69
	v_lshl_add_u64 v[214:215], s[50:51], 0, v[204:205]
	ds_read_b128 v[164:167], v223 offset:32768
	ds_read_b128 v[168:171], v223 offset:33792
	ds_read_b128 v[172:175], v223 offset:34816
	ds_read_b128 v[176:179], v223 offset:35840
	ds_read_b128 v[180:183], v223 offset:36864
	ds_read_b128 v[184:187], v223 offset:37888
	ds_read_b128 v[188:191], v223 offset:38912
	ds_read_b128 v[192:195], v223 offset:39936
	global_load_lds_dwordx4 v[214:215], off
	v_lshl_add_u64 v[214:215], s[50:51], 0, v[206:207]
	s_mov_b32 m0, s70
	s_nop 0
	global_load_lds_dwordx4 v[214:215], off
	s_waitcnt vmcnt(8)
	s_waitcnt lgkmcnt(0)
	s_barrier
	s_setprio 1
	v_mfma_f32_16x16x32_bf16 v[156:159], v[108:111], v[164:167], v[156:159]
	v_mfma_f32_16x16x32_bf16 v[156:159], v[120:123], v[168:171], v[156:159]
	v_mfma_f32_16x16x32_bf16 v[128:131], v[108:111], v[172:175], v[128:131]
	v_mfma_f32_16x16x32_bf16 v[128:131], v[120:123], v[176:179], v[128:131]
	v_mfma_f32_16x16x32_bf16 v[116:119], v[108:111], v[180:183], v[116:119]
	v_mfma_f32_16x16x32_bf16 v[116:119], v[120:123], v[184:187], v[116:119]
	v_mfma_f32_16x16x32_bf16 v[104:107], v[108:111], v[188:191], v[104:107]
	v_mfma_f32_16x16x32_bf16 v[104:107], v[120:123], v[192:195], v[104:107]
	v_mfma_f32_16x16x32_bf16 v[152:155], v[132:135], v[164:167], v[152:155]
	v_mfma_f32_16x16x32_bf16 v[152:155], v[136:139], v[168:171], v[152:155]
	v_mfma_f32_16x16x32_bf16 v[124:127], v[132:135], v[172:175], v[124:127]
	v_mfma_f32_16x16x32_bf16 v[124:127], v[136:139], v[176:179], v[124:127]
	v_mfma_f32_16x16x32_bf16 v[112:115], v[132:135], v[180:183], v[112:115]
	v_mfma_f32_16x16x32_bf16 v[112:115], v[136:139], v[184:187], v[112:115]
	v_mfma_f32_16x16x32_bf16 v[100:103], v[132:135], v[188:191], v[100:103]
	v_mfma_f32_16x16x32_bf16 v[100:103], v[136:139], v[192:195], v[100:103]
	v_mfma_f32_16x16x32_bf16 v[92:95], v[140:143], v[164:167], v[92:95]
	v_mfma_f32_16x16x32_bf16 v[92:95], v[144:147], v[168:171], v[92:95]
	v_mfma_f32_16x16x32_bf16 v[84:87], v[140:143], v[172:175], v[84:87]
	v_mfma_f32_16x16x32_bf16 v[84:87], v[144:147], v[176:179], v[84:87]
	v_mfma_f32_16x16x32_bf16 v[76:79], v[140:143], v[180:183], v[76:79]
	v_mfma_f32_16x16x32_bf16 v[76:79], v[144:147], v[184:187], v[76:79]
	v_mfma_f32_16x16x32_bf16 v[68:71], v[140:143], v[188:191], v[68:71]
	v_mfma_f32_16x16x32_bf16 v[68:71], v[144:147], v[192:195], v[68:71]
	v_mfma_f32_16x16x32_bf16 v[88:91], v[148:151], v[164:167], v[88:91]
	v_mfma_f32_16x16x32_bf16 v[88:91], v[160:163], v[168:171], v[88:91]
	v_mfma_f32_16x16x32_bf16 v[80:83], v[148:151], v[172:175], v[80:83]
	v_mfma_f32_16x16x32_bf16 v[80:83], v[160:163], v[176:179], v[80:83]
	v_mfma_f32_16x16x32_bf16 v[72:75], v[148:151], v[180:183], v[72:75]
	v_mfma_f32_16x16x32_bf16 v[72:75], v[160:163], v[184:187], v[72:75]
	v_mfma_f32_16x16x32_bf16 v[64:67], v[148:151], v[188:191], v[64:67]
	v_mfma_f32_16x16x32_bf16 v[64:67], v[160:163], v[192:195], v[64:67]
	s_setprio 0
	s_barrier
	s_nop 1
	s_add_i32 s3, s3, s64
	v_lshl_add_u64 v[196:197], v[196:197], 0, s[72:73]
	s_mov_b32 m0, s3
	ds_read_b128 v[164:167], v223 offset:49152
	ds_read_b128 v[168:171], v223 offset:50176
	ds_read_b128 v[172:175], v223 offset:51200
	ds_read_b128 v[176:179], v223 offset:52224
	ds_read_b128 v[180:183], v223 offset:53248
	ds_read_b128 v[184:187], v223 offset:54272
	ds_read_b128 v[188:191], v223 offset:55296
	ds_read_b128 v[192:195], v223 offset:56320
	global_load_lds_dwordx4 v[196:197], off
	s_add_i32 m0, s3, 0x2000
	s_add_u32 s50, vcc_lo, 0x80080
	v_lshl_add_u64 v[196:197], v[198:199], 0, s[72:73]
	s_addc_u32 s51, vcc_hi, 0
	s_add_i32 s3, s41, s64
	global_load_lds_dwordx4 v[196:197], off
	v_lshl_add_u64 v[196:197], s[50:51], 0, v[212:213]
	s_mov_b32 m0, s3
	s_nop 0
	global_load_lds_dwordx4 v[196:197], off
	v_lshl_add_u64 v[196:197], s[50:51], 0, v[208:209]
	s_add_i32 m0, s3, 0x2000
	s_nop 0
	global_load_lds_dwordx4 v[196:197], off
	v_lshl_add_u64 v[196:197], v[200:201], 0, s[72:73]
	s_mov_b32 m0, s83
	s_nop 0
	global_load_lds_dwordx4 v[196:197], off
	v_lshl_add_u64 v[196:197], v[202:203], 0, s[72:73]
	s_mov_b32 m0, s84
	s_nop 0
	global_load_lds_dwordx4 v[196:197], off
	s_waitcnt vmcnt(8)
	s_waitcnt lgkmcnt(0)
	s_barrier
	s_setprio 1
	v_mfma_f32_16x16x32_bf16 v[60:63], v[108:111], v[164:167], v[60:63]
	v_mfma_f32_16x16x32_bf16 v[60:63], v[120:123], v[168:171], v[60:63]
	v_mfma_f32_16x16x32_bf16 v[52:55], v[108:111], v[172:175], v[52:55]
	v_mfma_f32_16x16x32_bf16 v[52:55], v[120:123], v[176:179], v[52:55]
	v_mfma_f32_16x16x32_bf16 v[44:47], v[108:111], v[180:183], v[44:47]
	v_mfma_f32_16x16x32_bf16 v[44:47], v[120:123], v[184:187], v[44:47]
	v_mfma_f32_16x16x32_bf16 v[36:39], v[108:111], v[188:191], v[36:39]
	v_mfma_f32_16x16x32_bf16 v[36:39], v[120:123], v[192:195], v[36:39]
	v_mfma_f32_16x16x32_bf16 v[56:59], v[132:135], v[164:167], v[56:59]
	v_mfma_f32_16x16x32_bf16 v[56:59], v[136:139], v[168:171], v[56:59]
	v_mfma_f32_16x16x32_bf16 v[48:51], v[132:135], v[172:175], v[48:51]
	v_mfma_f32_16x16x32_bf16 v[48:51], v[136:139], v[176:179], v[48:51]
	v_mfma_f32_16x16x32_bf16 v[40:43], v[132:135], v[180:183], v[40:43]
	v_mfma_f32_16x16x32_bf16 v[40:43], v[136:139], v[184:187], v[40:43]
	v_mfma_f32_16x16x32_bf16 v[32:35], v[132:135], v[188:191], v[32:35]
	v_mfma_f32_16x16x32_bf16 v[32:35], v[136:139], v[192:195], v[32:35]
	v_mfma_f32_16x16x32_bf16 v[28:31], v[140:143], v[164:167], v[28:31]
	v_mfma_f32_16x16x32_bf16 v[28:31], v[144:147], v[168:171], v[28:31]
	v_mfma_f32_16x16x32_bf16 v[20:23], v[140:143], v[172:175], v[20:23]
	v_mfma_f32_16x16x32_bf16 v[20:23], v[144:147], v[176:179], v[20:23]
	v_mfma_f32_16x16x32_bf16 v[12:15], v[140:143], v[180:183], v[12:15]
	v_mfma_f32_16x16x32_bf16 v[12:15], v[144:147], v[184:187], v[12:15]
	v_mfma_f32_16x16x32_bf16 v[4:7], v[140:143], v[188:191], v[4:7]
	v_mfma_f32_16x16x32_bf16 v[4:7], v[144:147], v[192:195], v[4:7]
	v_mfma_f32_16x16x32_bf16 v[24:27], v[148:151], v[164:167], v[24:27]
	v_mfma_f32_16x16x32_bf16 v[24:27], v[160:163], v[168:171], v[24:27]
	v_mfma_f32_16x16x32_bf16 v[16:19], v[148:151], v[172:175], v[16:19]
	v_mfma_f32_16x16x32_bf16 v[16:19], v[160:163], v[176:179], v[16:19]
	v_mfma_f32_16x16x32_bf16 v[8:11], v[148:151], v[180:183], v[8:11]
	v_mfma_f32_16x16x32_bf16 v[8:11], v[160:163], v[184:187], v[8:11]
	v_mfma_f32_16x16x32_bf16 v[0:3], v[148:151], v[188:191], v[0:3]
	v_mfma_f32_16x16x32_bf16 v[0:3], v[160:163], v[192:195], v[0:3]
	s_setprio 0
	s_barrier
	s_nop 1
	s_add_u32 s34, s34, 0x100
	s_addc_u32 s35, s35, 0
	s_cmp_ge_i32 s2, s21
	s_mov_b32 s41, s2
	s_cbranch_scc1 .LBB0_666

.LBB0_831:
	s_add_u32 s2, s24, 0xfff80080
	s_addc_u32 s3, s25, -1
	s_cmp_eq_u32 s17, 30
	s_cselect_b32 s29, s13, s3
	s_cselect_b32 s28, s63, s2
	s_cselect_b32 s27, s11, s65
	s_cselect_b32 s26, s64, s19
	s_add_i32 s2, 0, 0x10000
	v_add_u32_e32 v138, s2, v140
	s_add_i32 s66, 0, 0x14000
	ds_read_b128 v[142:145], v138
	ds_read_b128 v[146:149], v138 offset:1024
	ds_read_b128 v[150:153], v138 offset:2048
	ds_read_b128 v[154:157], v138 offset:3072
	v_add_u32_e32 v138, s66, v140
	ds_read_b128 v[158:161], v138
	ds_read_b128 v[162:165], v138 offset:1024
	ds_read_b128 v[166:169], v138 offset:2048
	ds_read_b128 v[170:173], v138 offset:3072
	v_lshl_add_u64 v[138:139], s[24:25], 0, v[134:135]
	s_add_i32 m0, s43, 0xc000
	ds_read_b128 v[174:177], v141
	ds_read_b128 v[178:181], v141 offset:1024
	ds_read_b128 v[182:185], v141 offset:2048
	ds_read_b128 v[186:189], v141 offset:3072
	ds_read_b128 v[190:193], v141 offset:4096
	ds_read_b128 v[194:197], v141 offset:5120
	ds_read_b128 v[198:201], v141 offset:6144
	ds_read_b128 v[202:205], v141 offset:7168
	global_load_lds_dwordx4 v[138:139], off
	v_lshl_add_u64 v[138:139], s[24:25], 0, v[136:137]
	s_add_i32 m0, s43, 0xe000
	s_nop 0
	global_load_lds_dwordx4 v[138:139], off
	s_waitcnt vmcnt(8)
	s_waitcnt lgkmcnt(0)
	s_barrier
	s_setprio 1
	v_mfma_f32_16x16x32_bf16 v[124:127], v[142:145], v[174:177], v[124:127]
	v_mfma_f32_16x16x32_bf16 v[124:127], v[146:149], v[178:181], v[124:127]
	v_mfma_f32_16x16x32_bf16 v[120:123], v[142:145], v[182:185], v[120:123]
	v_mfma_f32_16x16x32_bf16 v[120:123], v[146:149], v[186:189], v[120:123]
	v_mfma_f32_16x16x32_bf16 v[116:119], v[142:145], v[190:193], v[116:119]
	v_mfma_f32_16x16x32_bf16 v[116:119], v[146:149], v[194:197], v[116:119]
	v_mfma_f32_16x16x32_bf16 v[112:115], v[142:145], v[198:201], v[112:115]
	v_mfma_f32_16x16x32_bf16 v[112:115], v[146:149], v[202:205], v[112:115]
	v_mfma_f32_16x16x32_bf16 v[108:111], v[150:153], v[174:177], v[108:111]
	v_mfma_f32_16x16x32_bf16 v[108:111], v[154:157], v[178:181], v[108:111]
	v_mfma_f32_16x16x32_bf16 v[104:107], v[150:153], v[182:185], v[104:107]
	v_mfma_f32_16x16x32_bf16 v[104:107], v[154:157], v[186:189], v[104:107]
	v_mfma_f32_16x16x32_bf16 v[100:103], v[150:153], v[190:193], v[100:103]
	v_mfma_f32_16x16x32_bf16 v[100:103], v[154:157], v[194:197], v[100:103]
	v_mfma_f32_16x16x32_bf16 v[96:99], v[150:153], v[198:201], v[96:99]
	v_mfma_f32_16x16x32_bf16 v[96:99], v[154:157], v[202:205], v[96:99]
	v_mfma_f32_16x16x32_bf16 v[84:87], v[158:161], v[174:177], v[84:87]
	v_mfma_f32_16x16x32_bf16 v[84:87], v[162:165], v[178:181], v[84:87]
	v_mfma_f32_16x16x32_bf16 v[76:79], v[158:161], v[182:185], v[76:79]
	v_mfma_f32_16x16x32_bf16 v[76:79], v[162:165], v[186:189], v[76:79]
	v_mfma_f32_16x16x32_bf16 v[64:67], v[158:161], v[190:193], v[64:67]
	v_mfma_f32_16x16x32_bf16 v[64:67], v[162:165], v[194:197], v[64:67]
	v_mfma_f32_16x16x32_bf16 v[56:59], v[158:161], v[198:201], v[56:59]
	v_mfma_f32_16x16x32_bf16 v[56:59], v[162:165], v[202:205], v[56:59]
	v_mfma_f32_16x16x32_bf16 v[52:55], v[166:169], v[174:177], v[52:55]
	v_mfma_f32_16x16x32_bf16 v[52:55], v[170:173], v[178:181], v[52:55]
	v_mfma_f32_16x16x32_bf16 v[44:47], v[166:169], v[182:185], v[44:47]
	v_mfma_f32_16x16x32_bf16 v[44:47], v[170:173], v[186:189], v[44:47]
	v_mfma_f32_16x16x32_bf16 v[36:39], v[166:169], v[190:193], v[36:39]
	v_mfma_f32_16x16x32_bf16 v[36:39], v[170:173], v[194:197], v[36:39]
	v_mfma_f32_16x16x32_bf16 v[32:35], v[166:169], v[198:201], v[32:35]
	v_mfma_f32_16x16x32_bf16 v[32:35], v[170:173], v[202:205], v[32:35]
	s_setprio 0
	s_barrier
	s_nop 1
	s_add_i32 s2, s2, s41
	v_lshl_add_u64 v[138:139], s[26:27], 0, v[212:213]
	s_mov_b32 m0, s2
	ds_read_b128 v[174:177], v141 offset:16384
	ds_read_b128 v[178:181], v141 offset:17408
	ds_read_b128 v[182:185], v141 offset:18432
	ds_read_b128 v[186:189], v141 offset:19456
	ds_read_b128 v[190:193], v141 offset:20480
	ds_read_b128 v[194:197], v141 offset:21504
	ds_read_b128 v[198:201], v141 offset:22528
	ds_read_b128 v[202:205], v141 offset:23552
	global_load_lds_dwordx4 v[138:139], off
	s_add_i32 m0, s2, 0x2000
	s_add_u32 s2, s26, 0x80000
	v_lshl_add_u64 v[206:207], s[26:27], 0, v[128:129]
	s_addc_u32 s3, s27, 0
	s_add_i32 s66, s66, s41
	global_load_lds_dwordx4 v[206:207], off
	v_lshl_add_u64 v[208:209], s[2:3], 0, v[212:213]
	s_mov_b32 m0, s66
	v_lshl_add_u64 v[210:211], s[28:29], 0, v[130:131]
	global_load_lds_dwordx4 v[208:209], off
	v_lshl_add_u64 v[208:209], s[2:3], 0, v[128:129]
	s_add_i32 m0, s66, 0x2000
	s_nop 0
	global_load_lds_dwordx4 v[208:209], off
	v_lshl_add_u64 v[208:209], s[28:29], 0, v[132:133]
	s_mov_b32 m0, s43
	s_nop 0
	global_load_lds_dwordx4 v[208:209], off
	s_mov_b32 m0, s44
	s_nop 0
	global_load_lds_dwordx4 v[210:211], off
	s_waitcnt vmcnt(8)
	s_waitcnt lgkmcnt(0)
	s_barrier
	s_setprio 1
	v_mfma_f32_16x16x32_bf16 v[92:95], v[142:145], v[174:177], v[92:95]
	v_mfma_f32_16x16x32_bf16 v[92:95], v[146:149], v[178:181], v[92:95]
	v_mfma_f32_16x16x32_bf16 v[88:91], v[142:145], v[182:185], v[88:91]
	v_mfma_f32_16x16x32_bf16 v[88:91], v[146:149], v[186:189], v[88:91]
	v_mfma_f32_16x16x32_bf16 v[80:83], v[142:145], v[190:193], v[80:83]
	v_mfma_f32_16x16x32_bf16 v[80:83], v[146:149], v[194:197], v[80:83]
	v_mfma_f32_16x16x32_bf16 v[72:75], v[142:145], v[198:201], v[72:75]
	v_mfma_f32_16x16x32_bf16 v[72:75], v[146:149], v[202:205], v[72:75]
	v_mfma_f32_16x16x32_bf16 v[68:71], v[150:153], v[174:177], v[68:71]
	v_mfma_f32_16x16x32_bf16 v[68:71], v[154:157], v[178:181], v[68:71]
	v_mfma_f32_16x16x32_bf16 v[60:63], v[150:153], v[182:185], v[60:63]
	v_mfma_f32_16x16x32_bf16 v[60:63], v[154:157], v[186:189], v[60:63]
	v_mfma_f32_16x16x32_bf16 v[48:51], v[150:153], v[190:193], v[48:51]
	v_mfma_f32_16x16x32_bf16 v[48:51], v[154:157], v[194:197], v[48:51]
	v_mfma_f32_16x16x32_bf16 v[40:43], v[150:153], v[198:201], v[40:43]
	v_mfma_f32_16x16x32_bf16 v[40:43], v[154:157], v[202:205], v[40:43]
	v_mfma_f32_16x16x32_bf16 v[28:31], v[158:161], v[174:177], v[28:31]
	v_mfma_f32_16x16x32_bf16 v[28:31], v[162:165], v[178:181], v[28:31]
	v_mfma_f32_16x16x32_bf16 v[24:27], v[158:161], v[182:185], v[24:27]
	v_mfma_f32_16x16x32_bf16 v[24:27], v[162:165], v[186:189], v[24:27]
	v_mfma_f32_16x16x32_bf16 v[20:23], v[158:161], v[190:193], v[20:23]
	v_mfma_f32_16x16x32_bf16 v[20:23], v[162:165], v[194:197], v[20:23]
	v_mfma_f32_16x16x32_bf16 v[16:19], v[158:161], v[198:201], v[16:19]
	v_mfma_f32_16x16x32_bf16 v[16:19], v[162:165], v[202:205], v[16:19]
	v_mfma_f32_16x16x32_bf16 v[12:15], v[166:169], v[174:177], v[12:15]
	v_mfma_f32_16x16x32_bf16 v[12:15], v[170:173], v[178:181], v[12:15]
	v_mfma_f32_16x16x32_bf16 v[8:11], v[166:169], v[182:185], v[8:11]
	v_mfma_f32_16x16x32_bf16 v[8:11], v[170:173], v[186:189], v[8:11]
	v_mfma_f32_16x16x32_bf16 v[4:7], v[166:169], v[190:193], v[4:7]
	v_mfma_f32_16x16x32_bf16 v[4:7], v[170:173], v[194:197], v[4:7]
	v_mfma_f32_16x16x32_bf16 v[0:3], v[166:169], v[198:201], v[0:3]
	v_mfma_f32_16x16x32_bf16 v[0:3], v[170:173], v[202:205], v[0:3]
	s_setprio 0
	s_barrier
	s_nop 1
	s_add_i32 s66, 0, 0x18000
	s_add_i32 s67, 0, 0x1c000
	v_add_u32_e32 v154, s66, v140
	v_add_u32_e32 v170, s67, v140
	ds_read_b128 v[142:145], v154
	ds_read_b128 v[146:149], v154 offset:1024
	ds_read_b128 v[150:153], v154 offset:2048
	ds_read_b128 v[154:157], v154 offset:3072
	ds_read_b128 v[158:161], v170
	ds_read_b128 v[162:165], v170 offset:1024
	ds_read_b128 v[166:169], v170 offset:2048
	ds_read_b128 v[170:173], v170 offset:3072
	s_add_u32 s2, s28, 0x80000
	s_addc_u32 s3, s29, 0
	s_mov_b32 m0, s45
	v_lshl_add_u64 v[214:215], s[2:3], 0, v[132:133]
	ds_read_b128 v[174:177], v141 offset:32768
	ds_read_b128 v[178:181], v141 offset:33792
	ds_read_b128 v[182:185], v141 offset:34816
	ds_read_b128 v[186:189], v141 offset:35840
	ds_read_b128 v[190:193], v141 offset:36864
	ds_read_b128 v[194:197], v141 offset:37888
	ds_read_b128 v[198:201], v141 offset:38912
	ds_read_b128 v[202:205], v141 offset:39936
	global_load_lds_dwordx4 v[214:215], off
	v_lshl_add_u64 v[214:215], s[2:3], 0, v[130:131]
	s_mov_b32 m0, s46
	s_nop 0
	global_load_lds_dwordx4 v[214:215], off
	s_waitcnt vmcnt(8)
	s_waitcnt lgkmcnt(0)
	s_barrier
	s_setprio 1
	v_mfma_f32_16x16x32_bf16 v[124:127], v[142:145], v[174:177], v[124:127]
	v_mfma_f32_16x16x32_bf16 v[124:127], v[146:149], v[178:181], v[124:127]
	v_mfma_f32_16x16x32_bf16 v[120:123], v[142:145], v[182:185], v[120:123]
	v_mfma_f32_16x16x32_bf16 v[120:123], v[146:149], v[186:189], v[120:123]
	v_mfma_f32_16x16x32_bf16 v[116:119], v[142:145], v[190:193], v[116:119]
	v_mfma_f32_16x16x32_bf16 v[116:119], v[146:149], v[194:197], v[116:119]
	v_mfma_f32_16x16x32_bf16 v[112:115], v[142:145], v[198:201], v[112:115]
	v_mfma_f32_16x16x32_bf16 v[112:115], v[146:149], v[202:205], v[112:115]
	v_mfma_f32_16x16x32_bf16 v[108:111], v[150:153], v[174:177], v[108:111]
	v_mfma_f32_16x16x32_bf16 v[108:111], v[154:157], v[178:181], v[108:111]
	v_mfma_f32_16x16x32_bf16 v[104:107], v[150:153], v[182:185], v[104:107]
	v_mfma_f32_16x16x32_bf16 v[104:107], v[154:157], v[186:189], v[104:107]
	v_mfma_f32_16x16x32_bf16 v[100:103], v[150:153], v[190:193], v[100:103]
	v_mfma_f32_16x16x32_bf16 v[100:103], v[154:157], v[194:197], v[100:103]
	v_mfma_f32_16x16x32_bf16 v[96:99], v[150:153], v[198:201], v[96:99]
	v_mfma_f32_16x16x32_bf16 v[96:99], v[154:157], v[202:205], v[96:99]
	v_mfma_f32_16x16x32_bf16 v[84:87], v[158:161], v[174:177], v[84:87]
	v_mfma_f32_16x16x32_bf16 v[84:87], v[162:165], v[178:181], v[84:87]
	v_mfma_f32_16x16x32_bf16 v[76:79], v[158:161], v[182:185], v[76:79]
	v_mfma_f32_16x16x32_bf16 v[76:79], v[162:165], v[186:189], v[76:79]
	v_mfma_f32_16x16x32_bf16 v[64:67], v[158:161], v[190:193], v[64:67]
	v_mfma_f32_16x16x32_bf16 v[64:67], v[162:165], v[194:197], v[64:67]
	v_mfma_f32_16x16x32_bf16 v[56:59], v[158:161], v[198:201], v[56:59]
	v_mfma_f32_16x16x32_bf16 v[56:59], v[162:165], v[202:205], v[56:59]
	v_mfma_f32_16x16x32_bf16 v[52:55], v[166:169], v[174:177], v[52:55]
	v_mfma_f32_16x16x32_bf16 v[52:55], v[170:173], v[178:181], v[52:55]
	v_mfma_f32_16x16x32_bf16 v[44:47], v[166:169], v[182:185], v[44:47]
	v_mfma_f32_16x16x32_bf16 v[44:47], v[170:173], v[186:189], v[44:47]
	v_mfma_f32_16x16x32_bf16 v[36:39], v[166:169], v[190:193], v[36:39]
	v_mfma_f32_16x16x32_bf16 v[36:39], v[170:173], v[194:197], v[36:39]
	v_mfma_f32_16x16x32_bf16 v[32:35], v[166:169], v[198:201], v[32:35]
	v_mfma_f32_16x16x32_bf16 v[32:35], v[170:173], v[202:205], v[32:35]
	s_setprio 0
	s_barrier
	s_nop 1
	s_add_i32 s2, s66, s41
	v_lshl_add_u64 v[138:139], v[138:139], 0, s[72:73]
	s_mov_b32 m0, s2
	ds_read_b128 v[174:177], v141 offset:49152
	ds_read_b128 v[178:181], v141 offset:50176
	ds_read_b128 v[182:185], v141 offset:51200
	ds_read_b128 v[186:189], v141 offset:52224
	ds_read_b128 v[190:193], v141 offset:53248
	ds_read_b128 v[194:197], v141 offset:54272
	ds_read_b128 v[198:201], v141 offset:55296
	ds_read_b128 v[202:205], v141 offset:56320
	global_load_lds_dwordx4 v[138:139], off
	s_add_i32 m0, s2, 0x2000
	s_add_u32 s2, s26, 0x80080
	v_lshl_add_u64 v[138:139], v[206:207], 0, s[72:73]
	s_addc_u32 s3, s27, 0
	s_add_i32 s26, s67, s41
	global_load_lds_dwordx4 v[138:139], off
	v_lshl_add_u64 v[138:139], s[2:3], 0, v[212:213]
	s_mov_b32 m0, s26
	s_nop 0
	global_load_lds_dwordx4 v[138:139], off
	v_lshl_add_u64 v[138:139], s[2:3], 0, v[128:129]
	s_add_i32 m0, s26, 0x2000
	s_nop 0
	global_load_lds_dwordx4 v[138:139], off
	v_lshl_add_u64 v[138:139], v[208:209], 0, s[72:73]
	s_mov_b32 m0, s54
	s_nop 0
	global_load_lds_dwordx4 v[138:139], off
	v_lshl_add_u64 v[138:139], v[210:211], 0, s[72:73]
	s_mov_b32 m0, s55
	s_nop 0
	global_load_lds_dwordx4 v[138:139], off
	s_waitcnt vmcnt(8)
	s_waitcnt lgkmcnt(0)
	s_barrier
	s_setprio 1
	v_mfma_f32_16x16x32_bf16 v[92:95], v[142:145], v[174:177], v[92:95]
	v_mfma_f32_16x16x32_bf16 v[92:95], v[146:149], v[178:181], v[92:95]
	v_mfma_f32_16x16x32_bf16 v[88:91], v[142:145], v[182:185], v[88:91]
	v_mfma_f32_16x16x32_bf16 v[88:91], v[146:149], v[186:189], v[88:91]
	v_mfma_f32_16x16x32_bf16 v[80:83], v[142:145], v[190:193], v[80:83]
	v_mfma_f32_16x16x32_bf16 v[80:83], v[146:149], v[194:197], v[80:83]
	v_mfma_f32_16x16x32_bf16 v[72:75], v[142:145], v[198:201], v[72:75]
	v_mfma_f32_16x16x32_bf16 v[72:75], v[146:149], v[202:205], v[72:75]
	v_mfma_f32_16x16x32_bf16 v[68:71], v[150:153], v[174:177], v[68:71]
	v_mfma_f32_16x16x32_bf16 v[68:71], v[154:157], v[178:181], v[68:71]
	v_mfma_f32_16x16x32_bf16 v[60:63], v[150:153], v[182:185], v[60:63]
	v_mfma_f32_16x16x32_bf16 v[60:63], v[154:157], v[186:189], v[60:63]
	v_mfma_f32_16x16x32_bf16 v[48:51], v[150:153], v[190:193], v[48:51]
	v_mfma_f32_16x16x32_bf16 v[48:51], v[154:157], v[194:197], v[48:51]
	v_mfma_f32_16x16x32_bf16 v[40:43], v[150:153], v[198:201], v[40:43]
	v_mfma_f32_16x16x32_bf16 v[40:43], v[154:157], v[202:205], v[40:43]
	v_mfma_f32_16x16x32_bf16 v[28:31], v[158:161], v[174:177], v[28:31]
	v_mfma_f32_16x16x32_bf16 v[28:31], v[162:165], v[178:181], v[28:31]
	v_mfma_f32_16x16x32_bf16 v[24:27], v[158:161], v[182:185], v[24:27]
	v_mfma_f32_16x16x32_bf16 v[24:27], v[162:165], v[186:189], v[24:27]
	v_mfma_f32_16x16x32_bf16 v[20:23], v[158:161], v[190:193], v[20:23]
	v_mfma_f32_16x16x32_bf16 v[20:23], v[162:165], v[194:197], v[20:23]
	v_mfma_f32_16x16x32_bf16 v[16:19], v[158:161], v[198:201], v[16:19]
	v_mfma_f32_16x16x32_bf16 v[16:19], v[162:165], v[202:205], v[16:19]
	v_mfma_f32_16x16x32_bf16 v[12:15], v[166:169], v[174:177], v[12:15]
	v_mfma_f32_16x16x32_bf16 v[12:15], v[170:173], v[178:181], v[12:15]
	v_mfma_f32_16x16x32_bf16 v[8:11], v[166:169], v[182:185], v[8:11]
	v_mfma_f32_16x16x32_bf16 v[8:11], v[170:173], v[186:189], v[8:11]
	v_mfma_f32_16x16x32_bf16 v[4:7], v[166:169], v[190:193], v[4:7]
	v_mfma_f32_16x16x32_bf16 v[4:7], v[170:173], v[194:197], v[4:7]
	v_mfma_f32_16x16x32_bf16 v[0:3], v[166:169], v[198:201], v[0:3]
	v_mfma_f32_16x16x32_bf16 v[0:3], v[170:173], v[202:205], v[0:3]
	s_setprio 0
	s_barrier
	s_nop 1
	s_add_i32 s2, s17, 2
	s_add_u32 s24, s24, 0x100
	s_addc_u32 s25, s25, 0
	s_add_u32 s19, s19, 0x100
	s_addc_u32 s65, s65, 0
	s_cmp_gt_u32 s17, 29
	s_mov_b32 s17, s2
	s_cbranch_scc1 .LBB0_842

.LBB0_997:
	s_add_u32 s20, s18, 0xfffe0080
	s_addc_u32 s21, s19, -1
	s_add_i32 s63, 0, 0x10000
	s_cmp_eq_u32 s62, 4
	s_cselect_b32 s23, s2, s21
	s_cselect_b32 s22, s3, s20
	s_cselect_b32 s21, s39, s61
	s_cselect_b32 s20, s43, s60
	s_add_i32 s66, 0, 0x14000
	v_add_u32_e32 v152, s63, v142
	v_add_u32_e32 v168, s66, v142
	ds_read_b128 v[138:141], v152
	ds_read_b128 v[144:147], v152 offset:1024
	ds_read_b128 v[148:151], v152 offset:2048
	ds_read_b128 v[152:155], v152 offset:3072
	ds_read_b128 v[156:159], v168
	ds_read_b128 v[160:163], v168 offset:1024
	ds_read_b128 v[164:167], v168 offset:2048
	ds_read_b128 v[168:171], v168 offset:3072
	v_lshl_add_u64 v[204:205], s[18:19], 0, v[134:135]
	s_add_i32 m0, s41, 0xc000
	ds_read_b128 v[172:175], v143
	ds_read_b128 v[176:179], v143 offset:1024
	ds_read_b128 v[180:183], v143 offset:2048
	ds_read_b128 v[184:187], v143 offset:3072
	ds_read_b128 v[188:191], v143 offset:4096
	ds_read_b128 v[192:195], v143 offset:5120
	ds_read_b128 v[196:199], v143 offset:6144
	ds_read_b128 v[200:203], v143 offset:7168
	global_load_lds_dwordx4 v[204:205], off
	v_lshl_add_u64 v[204:205], s[18:19], 0, v[136:137]
	s_add_i32 m0, s41, 0xe000
	s_nop 0
	global_load_lds_dwordx4 v[204:205], off
	s_waitcnt vmcnt(8)
	s_waitcnt lgkmcnt(0)
	s_barrier
	s_setprio 1
	v_mfma_f32_16x16x32_bf16 v[124:127], v[138:141], v[172:175], v[124:127]
	v_mfma_f32_16x16x32_bf16 v[124:127], v[144:147], v[176:179], v[124:127]
	v_mfma_f32_16x16x32_bf16 v[116:119], v[138:141], v[180:183], v[116:119]
	v_mfma_f32_16x16x32_bf16 v[116:119], v[144:147], v[184:187], v[116:119]
	v_mfma_f32_16x16x32_bf16 v[100:103], v[138:141], v[188:191], v[100:103]
	v_mfma_f32_16x16x32_bf16 v[100:103], v[144:147], v[192:195], v[100:103]
	v_mfma_f32_16x16x32_bf16 v[84:87], v[138:141], v[196:199], v[84:87]
	v_mfma_f32_16x16x32_bf16 v[84:87], v[144:147], v[200:203], v[84:87]
	v_mfma_f32_16x16x32_bf16 v[120:123], v[148:151], v[172:175], v[120:123]
	v_mfma_f32_16x16x32_bf16 v[120:123], v[152:155], v[176:179], v[120:123]
	v_mfma_f32_16x16x32_bf16 v[108:111], v[148:151], v[180:183], v[108:111]
	v_mfma_f32_16x16x32_bf16 v[108:111], v[152:155], v[184:187], v[108:111]
	v_mfma_f32_16x16x32_bf16 v[92:95], v[148:151], v[188:191], v[92:95]
	v_mfma_f32_16x16x32_bf16 v[92:95], v[152:155], v[192:195], v[92:95]
	v_mfma_f32_16x16x32_bf16 v[76:79], v[148:151], v[196:199], v[76:79]
	v_mfma_f32_16x16x32_bf16 v[76:79], v[152:155], v[200:203], v[76:79]
	v_mfma_f32_16x16x32_bf16 v[112:115], v[156:159], v[172:175], v[112:115]
	v_mfma_f32_16x16x32_bf16 v[112:115], v[160:163], v[176:179], v[112:115]
	v_mfma_f32_16x16x32_bf16 v[96:99], v[156:159], v[180:183], v[96:99]
	v_mfma_f32_16x16x32_bf16 v[96:99], v[160:163], v[184:187], v[96:99]
	v_mfma_f32_16x16x32_bf16 v[80:83], v[156:159], v[188:191], v[80:83]
	v_mfma_f32_16x16x32_bf16 v[80:83], v[160:163], v[192:195], v[80:83]
	v_mfma_f32_16x16x32_bf16 v[68:71], v[156:159], v[196:199], v[68:71]
	v_mfma_f32_16x16x32_bf16 v[68:71], v[160:163], v[200:203], v[68:71]
	v_mfma_f32_16x16x32_bf16 v[104:107], v[164:167], v[172:175], v[104:107]
	v_mfma_f32_16x16x32_bf16 v[104:107], v[168:171], v[176:179], v[104:107]
	v_mfma_f32_16x16x32_bf16 v[88:91], v[164:167], v[180:183], v[88:91]
	v_mfma_f32_16x16x32_bf16 v[88:91], v[168:171], v[184:187], v[88:91]
	v_mfma_f32_16x16x32_bf16 v[72:75], v[164:167], v[188:191], v[72:75]
	v_mfma_f32_16x16x32_bf16 v[72:75], v[168:171], v[192:195], v[72:75]
	v_mfma_f32_16x16x32_bf16 v[64:67], v[164:167], v[196:199], v[64:67]
	v_mfma_f32_16x16x32_bf16 v[64:67], v[168:171], v[200:203], v[64:67]
	s_setprio 0
	s_barrier
	s_nop 1
	s_add_i32 s63, s63, s33
	v_lshl_add_u64 v[204:205], s[20:21], 0, v[212:213]
	s_mov_b32 m0, s63
	ds_read_b128 v[172:175], v143 offset:16384
	ds_read_b128 v[176:179], v143 offset:17408
	ds_read_b128 v[180:183], v143 offset:18432
	ds_read_b128 v[184:187], v143 offset:19456
	ds_read_b128 v[188:191], v143 offset:20480
	ds_read_b128 v[192:195], v143 offset:21504
	ds_read_b128 v[196:199], v143 offset:22528
	ds_read_b128 v[200:203], v143 offset:23552
	global_load_lds_dwordx4 v[204:205], off
	s_add_i32 m0, s63, 0x2000
	s_add_u32 s64, s20, 0x20000
	v_lshl_add_u64 v[206:207], s[20:21], 0, v[128:129]
	s_addc_u32 s65, s21, 0
	s_add_i32 s63, s66, s33
	global_load_lds_dwordx4 v[206:207], off
	v_lshl_add_u64 v[208:209], s[64:65], 0, v[212:213]
	s_mov_b32 m0, s63
	v_lshl_add_u64 v[210:211], s[22:23], 0, v[130:131]
	global_load_lds_dwordx4 v[208:209], off
	v_lshl_add_u64 v[208:209], s[64:65], 0, v[128:129]
	s_add_i32 m0, s63, 0x2000
	s_nop 0
	global_load_lds_dwordx4 v[208:209], off
	v_lshl_add_u64 v[208:209], s[22:23], 0, v[132:133]
	s_mov_b32 m0, s41
	s_nop 0
	global_load_lds_dwordx4 v[208:209], off
	s_mov_b32 m0, s47
	s_nop 0
	global_load_lds_dwordx4 v[210:211], off
	s_waitcnt vmcnt(8)
	s_waitcnt lgkmcnt(0)
	s_barrier
	s_setprio 1
	v_mfma_f32_16x16x32_bf16 v[60:63], v[138:141], v[172:175], v[60:63]
	v_mfma_f32_16x16x32_bf16 v[60:63], v[144:147], v[176:179], v[60:63]
	v_mfma_f32_16x16x32_bf16 v[52:55], v[138:141], v[180:183], v[52:55]
	v_mfma_f32_16x16x32_bf16 v[52:55], v[144:147], v[184:187], v[52:55]
	v_mfma_f32_16x16x32_bf16 v[36:39], v[138:141], v[188:191], v[36:39]
	v_mfma_f32_16x16x32_bf16 v[36:39], v[144:147], v[192:195], v[36:39]
	v_mfma_f32_16x16x32_bf16 v[20:23], v[138:141], v[196:199], v[20:23]
	v_mfma_f32_16x16x32_bf16 v[20:23], v[144:147], v[200:203], v[20:23]
	v_mfma_f32_16x16x32_bf16 v[56:59], v[148:151], v[172:175], v[56:59]
	v_mfma_f32_16x16x32_bf16 v[56:59], v[152:155], v[176:179], v[56:59]
	v_mfma_f32_16x16x32_bf16 v[44:47], v[148:151], v[180:183], v[44:47]
	v_mfma_f32_16x16x32_bf16 v[44:47], v[152:155], v[184:187], v[44:47]
	v_mfma_f32_16x16x32_bf16 v[28:31], v[148:151], v[188:191], v[28:31]
	v_mfma_f32_16x16x32_bf16 v[28:31], v[152:155], v[192:195], v[28:31]
	v_mfma_f32_16x16x32_bf16 v[12:15], v[148:151], v[196:199], v[12:15]
	v_mfma_f32_16x16x32_bf16 v[12:15], v[152:155], v[200:203], v[12:15]
	v_mfma_f32_16x16x32_bf16 v[48:51], v[156:159], v[172:175], v[48:51]
	v_mfma_f32_16x16x32_bf16 v[48:51], v[160:163], v[176:179], v[48:51]
	v_mfma_f32_16x16x32_bf16 v[32:35], v[156:159], v[180:183], v[32:35]
	v_mfma_f32_16x16x32_bf16 v[32:35], v[160:163], v[184:187], v[32:35]
	v_mfma_f32_16x16x32_bf16 v[16:19], v[156:159], v[188:191], v[16:19]
	v_mfma_f32_16x16x32_bf16 v[16:19], v[160:163], v[192:195], v[16:19]
	v_mfma_f32_16x16x32_bf16 v[4:7], v[156:159], v[196:199], v[4:7]
	v_mfma_f32_16x16x32_bf16 v[4:7], v[160:163], v[200:203], v[4:7]
	v_mfma_f32_16x16x32_bf16 v[40:43], v[164:167], v[172:175], v[40:43]
	v_mfma_f32_16x16x32_bf16 v[40:43], v[168:171], v[176:179], v[40:43]
	v_mfma_f32_16x16x32_bf16 v[24:27], v[164:167], v[180:183], v[24:27]
	v_mfma_f32_16x16x32_bf16 v[24:27], v[168:171], v[184:187], v[24:27]
	v_mfma_f32_16x16x32_bf16 v[8:11], v[164:167], v[188:191], v[8:11]
	v_mfma_f32_16x16x32_bf16 v[8:11], v[168:171], v[192:195], v[8:11]
	v_mfma_f32_16x16x32_bf16 v[0:3], v[164:167], v[196:199], v[0:3]
	v_mfma_f32_16x16x32_bf16 v[0:3], v[168:171], v[200:203], v[0:3]
	s_setprio 0
	s_barrier
	s_nop 1
	s_add_i32 s63, 0, 0x18000
	s_add_i32 s64, 0, 0x1c000
	v_add_u32_e32 v152, s63, v142
	v_add_u32_e32 v168, s64, v142
	ds_read_b128 v[138:141], v152
	ds_read_b128 v[144:147], v152 offset:1024
	ds_read_b128 v[148:151], v152 offset:2048
	ds_read_b128 v[152:155], v152 offset:3072
	ds_read_b128 v[156:159], v168
	ds_read_b128 v[160:163], v168 offset:1024
	ds_read_b128 v[164:167], v168 offset:2048
	ds_read_b128 v[168:171], v168 offset:3072
	s_add_u32 s22, s22, 0x20000
	s_addc_u32 s23, s23, 0
	s_mov_b32 m0, s49
	v_lshl_add_u64 v[214:215], s[22:23], 0, v[132:133]
	ds_read_b128 v[172:175], v143 offset:32768
	ds_read_b128 v[176:179], v143 offset:33792
	ds_read_b128 v[180:183], v143 offset:34816
	ds_read_b128 v[184:187], v143 offset:35840
	ds_read_b128 v[188:191], v143 offset:36864
	ds_read_b128 v[192:195], v143 offset:37888
	ds_read_b128 v[196:199], v143 offset:38912
	ds_read_b128 v[200:203], v143 offset:39936
	global_load_lds_dwordx4 v[214:215], off
	v_lshl_add_u64 v[214:215], s[22:23], 0, v[130:131]
	s_mov_b32 m0, s52
	s_nop 0
	global_load_lds_dwordx4 v[214:215], off
	s_waitcnt vmcnt(8)
	s_waitcnt lgkmcnt(0)
	s_barrier
	s_setprio 1
	v_mfma_f32_16x16x32_bf16 v[124:127], v[138:141], v[172:175], v[124:127]
	v_mfma_f32_16x16x32_bf16 v[124:127], v[144:147], v[176:179], v[124:127]
	v_mfma_f32_16x16x32_bf16 v[116:119], v[138:141], v[180:183], v[116:119]
	v_mfma_f32_16x16x32_bf16 v[116:119], v[144:147], v[184:187], v[116:119]
	v_mfma_f32_16x16x32_bf16 v[100:103], v[138:141], v[188:191], v[100:103]
	v_mfma_f32_16x16x32_bf16 v[100:103], v[144:147], v[192:195], v[100:103]
	v_mfma_f32_16x16x32_bf16 v[84:87], v[138:141], v[196:199], v[84:87]
	v_mfma_f32_16x16x32_bf16 v[84:87], v[144:147], v[200:203], v[84:87]
	v_mfma_f32_16x16x32_bf16 v[120:123], v[148:151], v[172:175], v[120:123]
	v_mfma_f32_16x16x32_bf16 v[120:123], v[152:155], v[176:179], v[120:123]
	v_mfma_f32_16x16x32_bf16 v[108:111], v[148:151], v[180:183], v[108:111]
	v_mfma_f32_16x16x32_bf16 v[108:111], v[152:155], v[184:187], v[108:111]
	v_mfma_f32_16x16x32_bf16 v[92:95], v[148:151], v[188:191], v[92:95]
	v_mfma_f32_16x16x32_bf16 v[92:95], v[152:155], v[192:195], v[92:95]
	v_mfma_f32_16x16x32_bf16 v[76:79], v[148:151], v[196:199], v[76:79]
	v_mfma_f32_16x16x32_bf16 v[76:79], v[152:155], v[200:203], v[76:79]
	v_mfma_f32_16x16x32_bf16 v[112:115], v[156:159], v[172:175], v[112:115]
	v_mfma_f32_16x16x32_bf16 v[112:115], v[160:163], v[176:179], v[112:115]
	v_mfma_f32_16x16x32_bf16 v[96:99], v[156:159], v[180:183], v[96:99]
	v_mfma_f32_16x16x32_bf16 v[96:99], v[160:163], v[184:187], v[96:99]
	v_mfma_f32_16x16x32_bf16 v[80:83], v[156:159], v[188:191], v[80:83]
	v_mfma_f32_16x16x32_bf16 v[80:83], v[160:163], v[192:195], v[80:83]
	v_mfma_f32_16x16x32_bf16 v[68:71], v[156:159], v[196:199], v[68:71]
	v_mfma_f32_16x16x32_bf16 v[68:71], v[160:163], v[200:203], v[68:71]
	v_mfma_f32_16x16x32_bf16 v[104:107], v[164:167], v[172:175], v[104:107]
	v_mfma_f32_16x16x32_bf16 v[104:107], v[168:171], v[176:179], v[104:107]
	v_mfma_f32_16x16x32_bf16 v[88:91], v[164:167], v[180:183], v[88:91]
	v_mfma_f32_16x16x32_bf16 v[88:91], v[168:171], v[184:187], v[88:91]
	v_mfma_f32_16x16x32_bf16 v[72:75], v[164:167], v[188:191], v[72:75]
	v_mfma_f32_16x16x32_bf16 v[72:75], v[168:171], v[192:195], v[72:75]
	v_mfma_f32_16x16x32_bf16 v[64:67], v[164:167], v[196:199], v[64:67]
	v_mfma_f32_16x16x32_bf16 v[64:67], v[168:171], v[200:203], v[64:67]
	s_setprio 0
	s_barrier
	s_nop 1
	s_add_i32 s22, s63, s33
	v_lshl_add_u64 v[204:205], v[204:205], 0, s[72:73]
	s_mov_b32 m0, s22
	ds_read_b128 v[172:175], v143 offset:49152
	ds_read_b128 v[176:179], v143 offset:50176
	ds_read_b128 v[180:183], v143 offset:51200
	ds_read_b128 v[184:187], v143 offset:52224
	ds_read_b128 v[188:191], v143 offset:53248
	ds_read_b128 v[192:195], v143 offset:54272
	ds_read_b128 v[196:199], v143 offset:55296
	ds_read_b128 v[200:203], v143 offset:56320
	global_load_lds_dwordx4 v[204:205], off
	s_add_i32 m0, s22, 0x2000
	s_add_u32 s20, s20, 0x20080
	v_lshl_add_u64 v[204:205], v[206:207], 0, s[72:73]
	s_addc_u32 s21, s21, 0
	s_add_i32 s22, s64, s33
	global_load_lds_dwordx4 v[204:205], off
	v_lshl_add_u64 v[204:205], s[20:21], 0, v[212:213]
	s_mov_b32 m0, s22
	s_nop 0
	global_load_lds_dwordx4 v[204:205], off
	v_lshl_add_u64 v[204:205], s[20:21], 0, v[128:129]
	s_add_i32 m0, s22, 0x2000
	s_nop 0
	global_load_lds_dwordx4 v[204:205], off
	v_lshl_add_u64 v[204:205], v[208:209], 0, s[72:73]
	s_mov_b32 m0, s55
	s_nop 0
	global_load_lds_dwordx4 v[204:205], off
	v_lshl_add_u64 v[204:205], v[210:211], 0, s[72:73]
	s_mov_b32 m0, s56
	s_nop 0
	global_load_lds_dwordx4 v[204:205], off
	s_waitcnt vmcnt(8)
	s_waitcnt lgkmcnt(0)
	s_barrier
	s_setprio 1
	v_mfma_f32_16x16x32_bf16 v[60:63], v[138:141], v[172:175], v[60:63]
	v_mfma_f32_16x16x32_bf16 v[60:63], v[144:147], v[176:179], v[60:63]
	v_mfma_f32_16x16x32_bf16 v[52:55], v[138:141], v[180:183], v[52:55]
	v_mfma_f32_16x16x32_bf16 v[52:55], v[144:147], v[184:187], v[52:55]
	v_mfma_f32_16x16x32_bf16 v[36:39], v[138:141], v[188:191], v[36:39]
	v_mfma_f32_16x16x32_bf16 v[36:39], v[144:147], v[192:195], v[36:39]
	v_mfma_f32_16x16x32_bf16 v[20:23], v[138:141], v[196:199], v[20:23]
	v_mfma_f32_16x16x32_bf16 v[20:23], v[144:147], v[200:203], v[20:23]
	v_mfma_f32_16x16x32_bf16 v[56:59], v[148:151], v[172:175], v[56:59]
	v_mfma_f32_16x16x32_bf16 v[56:59], v[152:155], v[176:179], v[56:59]
	v_mfma_f32_16x16x32_bf16 v[44:47], v[148:151], v[180:183], v[44:47]
	v_mfma_f32_16x16x32_bf16 v[44:47], v[152:155], v[184:187], v[44:47]
	v_mfma_f32_16x16x32_bf16 v[28:31], v[148:151], v[188:191], v[28:31]
	v_mfma_f32_16x16x32_bf16 v[28:31], v[152:155], v[192:195], v[28:31]
	v_mfma_f32_16x16x32_bf16 v[12:15], v[148:151], v[196:199], v[12:15]
	v_mfma_f32_16x16x32_bf16 v[12:15], v[152:155], v[200:203], v[12:15]
	v_mfma_f32_16x16x32_bf16 v[48:51], v[156:159], v[172:175], v[48:51]
	v_mfma_f32_16x16x32_bf16 v[48:51], v[160:163], v[176:179], v[48:51]
	v_mfma_f32_16x16x32_bf16 v[32:35], v[156:159], v[180:183], v[32:35]
	v_mfma_f32_16x16x32_bf16 v[32:35], v[160:163], v[184:187], v[32:35]
	v_mfma_f32_16x16x32_bf16 v[16:19], v[156:159], v[188:191], v[16:19]
	v_mfma_f32_16x16x32_bf16 v[16:19], v[160:163], v[192:195], v[16:19]
	v_mfma_f32_16x16x32_bf16 v[4:7], v[156:159], v[196:199], v[4:7]
	v_mfma_f32_16x16x32_bf16 v[4:7], v[160:163], v[200:203], v[4:7]
	v_mfma_f32_16x16x32_bf16 v[40:43], v[164:167], v[172:175], v[40:43]
	v_mfma_f32_16x16x32_bf16 v[40:43], v[168:171], v[176:179], v[40:43]
	v_mfma_f32_16x16x32_bf16 v[24:27], v[164:167], v[180:183], v[24:27]
	v_mfma_f32_16x16x32_bf16 v[24:27], v[168:171], v[184:187], v[24:27]
	v_mfma_f32_16x16x32_bf16 v[8:11], v[164:167], v[188:191], v[8:11]
	v_mfma_f32_16x16x32_bf16 v[8:11], v[168:171], v[192:195], v[8:11]
	v_mfma_f32_16x16x32_bf16 v[0:3], v[164:167], v[196:199], v[0:3]
	v_mfma_f32_16x16x32_bf16 v[0:3], v[168:171], v[200:203], v[0:3]
	s_setprio 0
	s_barrier
	s_nop 1
	s_add_i32 s62, s62, 2
	s_add_u32 s18, s18, 0x100
	s_addc_u32 s19, s19, 0
	s_add_u32 s60, s60, 0x100
	s_addc_u32 s61, s61, 0
	s_cmp_gt_u32 s62, 5
	s_cbranch_scc0 .LBB0_997
	s_and_b64 vcc, exec, s[16:17]
	s_cbranch_vccz .LBB0_1000
	s_barrier

.LBB0_1012:
	s_ashr_i32 s15, s14, 31
	s_lshl_b64 s[16:17], s[14:15], 17
	s_add_u32 s16, s31, s16
	s_addc_u32 s17, s33, s17
	s_and_b64 s[18:19], s[36:37], exec
	s_cselect_b32 s29, s17, s23
	s_cselect_b32 s28, s16, s22
	s_ashr_i32 s13, s12, 31
	s_lshl_b64 s[18:19], s[12:13], 17
	s_add_u32 s18, s34, s18
	s_addc_u32 s19, s35, s19
	s_and_b64 s[26:27], s[36:37], exec
	s_cselect_b32 s27, s19, s25
	s_cselect_b32 s26, s18, s24
	s_add_i32 s49, 0, 0x10000
	s_add_i32 s15, 0, 0x14000
	v_add_u32_e32 v210, s49, v136
	v_add_u32_e32 v211, s15, v136
	ds_read_b128 v[0:3], v210
	ds_read_b128 v[4:7], v210 offset:1024
	ds_read_b128 v[8:11], v210 offset:2048
	ds_read_b128 v[12:15], v210 offset:3072
	ds_read_b128 v[16:19], v211
	ds_read_b128 v[20:23], v211 offset:1024
	ds_read_b128 v[24:27], v211 offset:2048
	ds_read_b128 v[28:31], v211 offset:3072
	s_add_u32 s52, s22, 0x10080
	s_addc_u32 s53, s23, 0
	s_add_i32 s51, s21, 0xc000
	v_lshl_add_u64 v[64:65], s[52:53], 0, v[132:133]
	s_mov_b32 m0, s51
	s_add_i32 s3, s21, 0xe000
	ds_read_b128 v[32:35], v137
	ds_read_b128 v[36:39], v137 offset:1024
	ds_read_b128 v[40:43], v137 offset:2048
	ds_read_b128 v[44:47], v137 offset:3072
	ds_read_b128 v[48:51], v137 offset:4096
	ds_read_b128 v[52:55], v137 offset:5120
	ds_read_b128 v[56:59], v137 offset:6144
	ds_read_b128 v[60:63], v137 offset:7168
	global_load_lds_dwordx4 v[64:65], off
	v_lshl_add_u64 v[64:65], s[52:53], 0, v[130:131]
	s_mov_b32 m0, s3
	s_nop 0
	global_load_lds_dwordx4 v[64:65], off
	s_waitcnt vmcnt(8)
	s_waitcnt lgkmcnt(0)
	s_barrier
	s_setprio 1
	v_mfma_f32_16x16x32_bf16 v[64:67], v[0:3], v[32:35], 0
	v_mfma_f32_16x16x32_bf16 v[68:71], v[8:11], v[32:35], 0
	v_mfma_f32_16x16x32_bf16 v[72:75], v[0:3], v[40:43], 0
	v_mfma_f32_16x16x32_bf16 v[76:79], v[8:11], v[40:43], 0
	v_mfma_f32_16x16x32_bf16 v[80:83], v[0:3], v[48:51], 0
	v_mfma_f32_16x16x32_bf16 v[84:87], v[8:11], v[48:51], 0
	v_mfma_f32_16x16x32_bf16 v[88:91], v[0:3], v[56:59], 0
	v_mfma_f32_16x16x32_bf16 v[92:95], v[8:11], v[56:59], 0
	v_mfma_f32_16x16x32_bf16 v[64:67], v[4:7], v[36:39], v[64:67]
	v_mfma_f32_16x16x32_bf16 v[72:75], v[4:7], v[44:47], v[72:75]
	v_mfma_f32_16x16x32_bf16 v[80:83], v[4:7], v[52:55], v[80:83]
	v_mfma_f32_16x16x32_bf16 v[88:91], v[4:7], v[60:63], v[88:91]
	v_mfma_f32_16x16x32_bf16 v[68:71], v[12:15], v[36:39], v[68:71]
	v_mfma_f32_16x16x32_bf16 v[76:79], v[12:15], v[44:47], v[76:79]
	v_mfma_f32_16x16x32_bf16 v[84:87], v[12:15], v[52:55], v[84:87]
	v_mfma_f32_16x16x32_bf16 v[92:95], v[12:15], v[60:63], v[92:95]
	v_mfma_f32_16x16x32_bf16 v[96:99], v[16:19], v[32:35], 0
	v_mfma_f32_16x16x32_bf16 v[32:35], v[24:27], v[32:35], 0
	v_mfma_f32_16x16x32_bf16 v[96:99], v[20:23], v[36:39], v[96:99]
	v_mfma_f32_16x16x32_bf16 v[32:35], v[28:31], v[36:39], v[32:35]
	v_mfma_f32_16x16x32_bf16 v[36:39], v[16:19], v[40:43], 0
	v_mfma_f32_16x16x32_bf16 v[40:43], v[24:27], v[40:43], 0
	v_mfma_f32_16x16x32_bf16 v[36:39], v[20:23], v[44:47], v[36:39]
	v_mfma_f32_16x16x32_bf16 v[40:43], v[28:31], v[44:47], v[40:43]
	v_mfma_f32_16x16x32_bf16 v[44:47], v[16:19], v[48:51], 0
	v_mfma_f32_16x16x32_bf16 v[48:51], v[24:27], v[48:51], 0
	v_mfma_f32_16x16x32_bf16 v[44:47], v[20:23], v[52:55], v[44:47]
	v_mfma_f32_16x16x32_bf16 v[48:51], v[28:31], v[52:55], v[48:51]
	v_mfma_f32_16x16x32_bf16 v[52:55], v[16:19], v[56:59], 0
	v_mfma_f32_16x16x32_bf16 v[56:59], v[24:27], v[56:59], 0
	v_mfma_f32_16x16x32_bf16 v[52:55], v[20:23], v[60:63], v[52:55]
	v_mfma_f32_16x16x32_bf16 v[56:59], v[28:31], v[60:63], v[56:59]
	s_setprio 0
	s_barrier
	s_nop 1
	s_add_i32 s49, s49, s38
	v_lshl_add_u64 v[134:135], s[24:25], 0, v[212:213]
	s_mov_b64 s[54:55], 0x100
	s_add_i32 s13, s49, 0x2000
	v_lshl_add_u64 v[138:139], v[134:135], 0, s[54:55]
	s_mov_b32 m0, s49
	v_lshl_add_u64 v[202:203], s[24:25], 0, v[128:129]
	s_add_u32 s52, s24, 0x10100
	ds_read_b128 v[60:63], v137 offset:16384
	ds_read_b128 v[100:103], v137 offset:17408
	ds_read_b128 v[104:107], v137 offset:18432
	ds_read_b128 v[108:111], v137 offset:19456
	ds_read_b128 v[112:115], v137 offset:20480
	ds_read_b128 v[116:119], v137 offset:21504
	ds_read_b128 v[120:123], v137 offset:22528
	ds_read_b128 v[124:127], v137 offset:23552
	global_load_lds_dwordx4 v[138:139], off
	v_lshl_add_u64 v[138:139], v[202:203], 0, s[54:55]
	s_mov_b32 m0, s13
	s_addc_u32 s53, s25, 0
	s_add_i32 s15, s15, s38
	global_load_lds_dwordx4 v[138:139], off
	v_lshl_add_u64 v[138:139], s[52:53], 0, v[212:213]
	s_mov_b32 m0, s15
	s_add_i32 s47, s15, 0x2000
	global_load_lds_dwordx4 v[138:139], off
	v_lshl_add_u64 v[138:139], s[52:53], 0, v[128:129]
	s_mov_b32 m0, s47
	v_lshl_add_u64 v[204:205], s[22:23], 0, v[132:133]
	global_load_lds_dwordx4 v[138:139], off
	v_lshl_add_u64 v[138:139], v[204:205], 0, s[54:55]
	s_mov_b32 m0, s21
	v_lshl_add_u64 v[206:207], s[22:23], 0, v[130:131]
	global_load_lds_dwordx4 v[138:139], off
	v_lshl_add_u64 v[138:139], v[206:207], 0, s[54:55]
	s_mov_b32 m0, s39
	s_nop 0
	global_load_lds_dwordx4 v[138:139], off
	s_waitcnt vmcnt(8)
	s_waitcnt lgkmcnt(0)
	s_barrier
	s_setprio 1
	v_mfma_f32_16x16x32_bf16 v[138:141], v[0:3], v[60:63], 0
	v_mfma_f32_16x16x32_bf16 v[146:149], v[0:3], v[104:107], 0
	v_mfma_f32_16x16x32_bf16 v[154:157], v[0:3], v[112:115], 0
	v_mfma_f32_16x16x32_bf16 v[0:3], v[0:3], v[120:123], 0
	v_mfma_f32_16x16x32_bf16 v[138:141], v[4:7], v[100:103], v[138:141]
	v_mfma_f32_16x16x32_bf16 v[146:149], v[4:7], v[108:111], v[146:149]
	v_mfma_f32_16x16x32_bf16 v[154:157], v[4:7], v[116:119], v[154:157]
	v_mfma_f32_16x16x32_bf16 v[0:3], v[4:7], v[124:127], v[0:3]
	v_mfma_f32_16x16x32_bf16 v[4:7], v[8:11], v[120:123], 0
	v_mfma_f32_16x16x32_bf16 v[142:145], v[8:11], v[60:63], 0
	v_mfma_f32_16x16x32_bf16 v[150:153], v[8:11], v[104:107], 0
	v_mfma_f32_16x16x32_bf16 v[158:161], v[8:11], v[112:115], 0
	v_mfma_f32_16x16x32_bf16 v[4:7], v[12:15], v[124:127], v[4:7]
	v_mfma_f32_16x16x32_bf16 v[142:145], v[12:15], v[100:103], v[142:145]
	v_mfma_f32_16x16x32_bf16 v[150:153], v[12:15], v[108:111], v[150:153]
	v_mfma_f32_16x16x32_bf16 v[158:161], v[12:15], v[116:119], v[158:161]
	v_mfma_f32_16x16x32_bf16 v[8:11], v[16:19], v[60:63], 0
	v_mfma_f32_16x16x32_bf16 v[12:15], v[24:27], v[60:63], 0
	v_mfma_f32_16x16x32_bf16 v[8:11], v[20:23], v[100:103], v[8:11]
	v_mfma_f32_16x16x32_bf16 v[12:15], v[28:31], v[100:103], v[12:15]
	v_mfma_f32_16x16x32_bf16 v[60:63], v[16:19], v[104:107], 0
	v_mfma_f32_16x16x32_bf16 v[100:103], v[24:27], v[104:107], 0
	v_mfma_f32_16x16x32_bf16 v[104:107], v[16:19], v[112:115], 0
	v_mfma_f32_16x16x32_bf16 v[16:19], v[16:19], v[120:123], 0
	v_mfma_f32_16x16x32_bf16 v[60:63], v[20:23], v[108:111], v[60:63]
	v_mfma_f32_16x16x32_bf16 v[100:103], v[28:31], v[108:111], v[100:103]
	v_mfma_f32_16x16x32_bf16 v[104:107], v[20:23], v[116:119], v[104:107]
	v_mfma_f32_16x16x32_bf16 v[108:111], v[24:27], v[112:115], 0
	v_mfma_f32_16x16x32_bf16 v[16:19], v[20:23], v[124:127], v[16:19]
	v_mfma_f32_16x16x32_bf16 v[20:23], v[24:27], v[120:123], 0
	v_mfma_f32_16x16x32_bf16 v[108:111], v[28:31], v[116:119], v[108:111]
	v_mfma_f32_16x16x32_bf16 v[20:23], v[28:31], v[124:127], v[20:23]
	s_setprio 0
	s_barrier
	s_nop 1
	s_add_i32 s50, 0, 0x18000
	s_add_i32 s56, 0, 0x1c000
	v_add_u32_e32 v214, s50, v136
	v_add_u32_e32 v215, s56, v136
	ds_read_b128 v[24:27], v214
	ds_read_b128 v[28:31], v214 offset:1024
	ds_read_b128 v[112:115], v214 offset:2048
	ds_read_b128 v[116:119], v214 offset:3072
	ds_read_b128 v[120:123], v215
	ds_read_b128 v[124:127], v215 offset:1024
	ds_read_b128 v[162:165], v215 offset:2048
	ds_read_b128 v[166:169], v215 offset:3072
	s_add_u32 s52, s22, 0x10100
	s_addc_u32 s53, s23, 0
	s_mov_b32 m0, s40
	v_lshl_add_u64 v[208:209], s[52:53], 0, v[132:133]
	ds_read_b128 v[170:173], v137 offset:32768
	ds_read_b128 v[174:177], v137 offset:33792
	ds_read_b128 v[178:181], v137 offset:34816
	ds_read_b128 v[182:185], v137 offset:35840
	ds_read_b128 v[186:189], v137 offset:36864
	ds_read_b128 v[190:193], v137 offset:37888
	ds_read_b128 v[194:197], v137 offset:38912
	ds_read_b128 v[198:201], v137 offset:39936
	global_load_lds_dwordx4 v[208:209], off
	v_lshl_add_u64 v[208:209], s[52:53], 0, v[130:131]
	s_mov_b32 m0, s41
	s_nop 0
	global_load_lds_dwordx4 v[208:209], off
	s_waitcnt vmcnt(8)
	s_waitcnt lgkmcnt(0)
	s_barrier
	s_setprio 1
	v_mfma_f32_16x16x32_bf16 v[64:67], v[24:27], v[170:173], v[64:67]
	v_mfma_f32_16x16x32_bf16 v[64:67], v[28:31], v[174:177], v[64:67]
	v_mfma_f32_16x16x32_bf16 v[72:75], v[24:27], v[178:181], v[72:75]
	v_mfma_f32_16x16x32_bf16 v[72:75], v[28:31], v[182:185], v[72:75]
	v_mfma_f32_16x16x32_bf16 v[80:83], v[24:27], v[186:189], v[80:83]
	v_mfma_f32_16x16x32_bf16 v[80:83], v[28:31], v[190:193], v[80:83]
	v_mfma_f32_16x16x32_bf16 v[88:91], v[24:27], v[194:197], v[88:91]
	v_mfma_f32_16x16x32_bf16 v[88:91], v[28:31], v[198:201], v[88:91]
	v_mfma_f32_16x16x32_bf16 v[68:71], v[112:115], v[170:173], v[68:71]
	v_mfma_f32_16x16x32_bf16 v[68:71], v[116:119], v[174:177], v[68:71]
	v_mfma_f32_16x16x32_bf16 v[76:79], v[112:115], v[178:181], v[76:79]
	v_mfma_f32_16x16x32_bf16 v[76:79], v[116:119], v[182:185], v[76:79]
	v_mfma_f32_16x16x32_bf16 v[84:87], v[112:115], v[186:189], v[84:87]
	v_mfma_f32_16x16x32_bf16 v[84:87], v[116:119], v[190:193], v[84:87]
	v_mfma_f32_16x16x32_bf16 v[92:95], v[112:115], v[194:197], v[92:95]
	v_mfma_f32_16x16x32_bf16 v[92:95], v[116:119], v[198:201], v[92:95]
	v_mfma_f32_16x16x32_bf16 v[96:99], v[120:123], v[170:173], v[96:99]
	v_mfma_f32_16x16x32_bf16 v[96:99], v[124:127], v[174:177], v[96:99]
	v_mfma_f32_16x16x32_bf16 v[36:39], v[120:123], v[178:181], v[36:39]
	v_mfma_f32_16x16x32_bf16 v[36:39], v[124:127], v[182:185], v[36:39]
	v_mfma_f32_16x16x32_bf16 v[44:47], v[120:123], v[186:189], v[44:47]
	v_mfma_f32_16x16x32_bf16 v[44:47], v[124:127], v[190:193], v[44:47]
	v_mfma_f32_16x16x32_bf16 v[52:55], v[120:123], v[194:197], v[52:55]
	v_mfma_f32_16x16x32_bf16 v[52:55], v[124:127], v[198:201], v[52:55]
	v_mfma_f32_16x16x32_bf16 v[32:35], v[162:165], v[170:173], v[32:35]
	v_mfma_f32_16x16x32_bf16 v[32:35], v[166:169], v[174:177], v[32:35]
	v_mfma_f32_16x16x32_bf16 v[40:43], v[162:165], v[178:181], v[40:43]
	v_mfma_f32_16x16x32_bf16 v[40:43], v[166:169], v[182:185], v[40:43]
	v_mfma_f32_16x16x32_bf16 v[48:51], v[162:165], v[186:189], v[48:51]
	v_mfma_f32_16x16x32_bf16 v[48:51], v[166:169], v[190:193], v[48:51]
	v_mfma_f32_16x16x32_bf16 v[56:59], v[162:165], v[194:197], v[56:59]
	v_mfma_f32_16x16x32_bf16 v[56:59], v[166:169], v[198:201], v[56:59]
	s_setprio 0
	s_barrier
	s_nop 1
	s_add_i32 s52, s50, s38
	s_mov_b64 s[60:61], 0x180
	s_add_i32 s50, s52, 0x2000
	v_lshl_add_u64 v[134:135], v[134:135], 0, s[60:61]
	s_mov_b32 m0, s52
	s_add_u32 s54, s24, 0x10180
	ds_read_b128 v[170:173], v137 offset:49152
	ds_read_b128 v[174:177], v137 offset:50176
	ds_read_b128 v[178:181], v137 offset:51200
	ds_read_b128 v[182:185], v137 offset:52224
	ds_read_b128 v[186:189], v137 offset:53248
	ds_read_b128 v[190:193], v137 offset:54272
	ds_read_b128 v[194:197], v137 offset:55296
	ds_read_b128 v[198:201], v137 offset:56320
	global_load_lds_dwordx4 v[134:135], off
	v_lshl_add_u64 v[134:135], v[202:203], 0, s[60:61]
	s_mov_b32 m0, s50
	s_addc_u32 s55, s25, 0
	s_add_i32 s24, s56, s38
	global_load_lds_dwordx4 v[134:135], off
	v_lshl_add_u64 v[134:135], s[54:55], 0, v[212:213]
	s_mov_b32 m0, s24
	s_add_i32 s25, s24, 0x2000
	global_load_lds_dwordx4 v[134:135], off
	v_lshl_add_u64 v[134:135], s[54:55], 0, v[128:129]
	s_mov_b32 m0, s25
	s_nop 0
	global_load_lds_dwordx4 v[134:135], off
	v_lshl_add_u64 v[134:135], v[204:205], 0, s[60:61]
	s_mov_b32 m0, s44
	s_nop 0
	global_load_lds_dwordx4 v[134:135], off
	v_lshl_add_u64 v[134:135], v[206:207], 0, s[60:61]
	s_mov_b32 m0, s45
	s_nop 0
	global_load_lds_dwordx4 v[134:135], off
	s_waitcnt vmcnt(8)
	s_waitcnt lgkmcnt(0)
	s_barrier
	s_setprio 1
	v_mfma_f32_16x16x32_bf16 v[0:3], v[24:27], v[194:197], v[0:3]
	v_mfma_f32_16x16x32_bf16 v[0:3], v[28:31], v[198:201], v[0:3]
	v_mfma_f32_16x16x32_bf16 v[138:141], v[24:27], v[170:173], v[138:141]
	v_mfma_f32_16x16x32_bf16 v[138:141], v[28:31], v[174:177], v[138:141]
	v_mfma_f32_16x16x32_bf16 v[146:149], v[24:27], v[178:181], v[146:149]
	v_mfma_f32_16x16x32_bf16 v[146:149], v[28:31], v[182:185], v[146:149]
	v_mfma_f32_16x16x32_bf16 v[154:157], v[24:27], v[186:189], v[154:157]
	v_mfma_f32_16x16x32_bf16 v[154:157], v[28:31], v[190:193], v[154:157]
	v_mfma_f32_16x16x32_bf16 v[4:7], v[112:115], v[194:197], v[4:7]
	v_mfma_f32_16x16x32_bf16 v[4:7], v[116:119], v[198:201], v[4:7]
	v_mfma_f32_16x16x32_bf16 v[142:145], v[112:115], v[170:173], v[142:145]
	v_mfma_f32_16x16x32_bf16 v[142:145], v[116:119], v[174:177], v[142:145]
	v_mfma_f32_16x16x32_bf16 v[150:153], v[112:115], v[178:181], v[150:153]
	v_mfma_f32_16x16x32_bf16 v[150:153], v[116:119], v[182:185], v[150:153]
	v_mfma_f32_16x16x32_bf16 v[158:161], v[112:115], v[186:189], v[158:161]
	v_mfma_f32_16x16x32_bf16 v[158:161], v[116:119], v[190:193], v[158:161]
	v_mfma_f32_16x16x32_bf16 v[8:11], v[120:123], v[170:173], v[8:11]
	v_mfma_f32_16x16x32_bf16 v[8:11], v[124:127], v[174:177], v[8:11]
	v_mfma_f32_16x16x32_bf16 v[24:27], v[120:123], v[178:181], v[60:63]
	v_mfma_f32_16x16x32_bf16 v[24:27], v[124:127], v[182:185], v[24:27]
	v_mfma_f32_16x16x32_bf16 v[16:19], v[120:123], v[194:197], v[16:19]
	v_mfma_f32_16x16x32_bf16 v[16:19], v[124:127], v[198:201], v[16:19]
	v_mfma_f32_16x16x32_bf16 v[12:15], v[162:165], v[170:173], v[12:15]
	v_mfma_f32_16x16x32_bf16 v[12:15], v[166:169], v[174:177], v[12:15]
	v_mfma_f32_16x16x32_bf16 v[28:31], v[162:165], v[178:181], v[100:103]
	v_mfma_f32_16x16x32_bf16 v[28:31], v[166:169], v[182:185], v[28:31]
	v_mfma_f32_16x16x32_bf16 v[60:63], v[120:123], v[186:189], v[104:107]
	v_mfma_f32_16x16x32_bf16 v[60:63], v[124:127], v[190:193], v[60:63]
	v_mfma_f32_16x16x32_bf16 v[100:103], v[162:165], v[186:189], v[108:111]
	v_mfma_f32_16x16x32_bf16 v[100:103], v[166:169], v[190:193], v[100:103]
	v_mfma_f32_16x16x32_bf16 v[20:23], v[162:165], v[194:197], v[20:23]
	v_mfma_f32_16x16x32_bf16 v[20:23], v[166:169], v[198:201], v[20:23]
	s_setprio 0
	s_barrier
	s_nop 1
	ds_read_b128 v[104:107], v210
	ds_read_b128 v[108:111], v210 offset:1024
	ds_read_b128 v[112:115], v210 offset:2048
	ds_read_b128 v[116:119], v210 offset:3072
	ds_read_b128 v[120:123], v211
	ds_read_b128 v[124:127], v211 offset:1024
	ds_read_b128 v[162:165], v211 offset:2048
	ds_read_b128 v[166:169], v211 offset:3072
	s_add_u32 s22, s22, 0x10180
	s_addc_u32 s23, s23, 0
	s_mov_b32 m0, s51
	v_lshl_add_u64 v[134:135], s[22:23], 0, v[132:133]
	ds_read_b128 v[170:173], v137
	ds_read_b128 v[174:177], v137 offset:1024
	ds_read_b128 v[178:181], v137 offset:2048
	ds_read_b128 v[182:185], v137 offset:3072
	ds_read_b128 v[186:189], v137 offset:4096
	ds_read_b128 v[190:193], v137 offset:5120
	ds_read_b128 v[194:197], v137 offset:6144
	ds_read_b128 v[198:201], v137 offset:7168
	global_load_lds_dwordx4 v[134:135], off
	v_lshl_add_u64 v[134:135], s[22:23], 0, v[130:131]
	s_mov_b32 m0, s3
	s_nop 0
	global_load_lds_dwordx4 v[134:135], off
	s_waitcnt vmcnt(8)
	s_waitcnt lgkmcnt(0)
	s_barrier
	s_setprio 1
	v_mfma_f32_16x16x32_bf16 v[64:67], v[104:107], v[170:173], v[64:67]
	v_mfma_f32_16x16x32_bf16 v[64:67], v[108:111], v[174:177], v[64:67]
	v_mfma_f32_16x16x32_bf16 v[72:75], v[104:107], v[178:181], v[72:75]
	v_mfma_f32_16x16x32_bf16 v[72:75], v[108:111], v[182:185], v[72:75]
	v_mfma_f32_16x16x32_bf16 v[80:83], v[104:107], v[186:189], v[80:83]
	v_mfma_f32_16x16x32_bf16 v[80:83], v[108:111], v[190:193], v[80:83]
	v_mfma_f32_16x16x32_bf16 v[88:91], v[104:107], v[194:197], v[88:91]
	v_mfma_f32_16x16x32_bf16 v[202:205], v[108:111], v[198:201], v[88:91]
	v_mfma_f32_16x16x32_bf16 v[68:71], v[112:115], v[170:173], v[68:71]
	v_mfma_f32_16x16x32_bf16 v[68:71], v[116:119], v[174:177], v[68:71]
	v_mfma_f32_16x16x32_bf16 v[76:79], v[112:115], v[178:181], v[76:79]
	v_mfma_f32_16x16x32_bf16 v[76:79], v[116:119], v[182:185], v[76:79]
	v_mfma_f32_16x16x32_bf16 v[84:87], v[112:115], v[186:189], v[84:87]
	v_mfma_f32_16x16x32_bf16 v[84:87], v[116:119], v[190:193], v[84:87]
	v_mfma_f32_16x16x32_bf16 v[88:91], v[112:115], v[194:197], v[92:95]
	v_mfma_f32_16x16x32_bf16 v[92:95], v[116:119], v[198:201], v[88:91]
	v_mfma_f32_16x16x32_bf16 v[48:51], v[162:165], v[186:189], v[48:51]
	v_mfma_f32_16x16x32_bf16 v[88:91], v[120:123], v[170:173], v[96:99]
	v_mfma_f32_16x16x32_bf16 v[206:209], v[124:127], v[174:177], v[88:91]
	v_mfma_f32_16x16x32_bf16 v[36:39], v[120:123], v[178:181], v[36:39]
	v_mfma_f32_16x16x32_bf16 v[36:39], v[124:127], v[182:185], v[36:39]
	v_mfma_f32_16x16x32_bf16 v[32:35], v[162:165], v[170:173], v[32:35]
	v_mfma_f32_16x16x32_bf16 v[32:35], v[166:169], v[174:177], v[32:35]
	v_mfma_f32_16x16x32_bf16 v[40:43], v[162:165], v[178:181], v[40:43]
	v_mfma_f32_16x16x32_bf16 v[40:43], v[166:169], v[182:185], v[40:43]
	v_mfma_f32_16x16x32_bf16 v[44:47], v[120:123], v[186:189], v[44:47]
	v_mfma_f32_16x16x32_bf16 v[44:47], v[124:127], v[190:193], v[44:47]
	v_mfma_f32_16x16x32_bf16 v[170:173], v[166:169], v[190:193], v[48:51]
	v_mfma_f32_16x16x32_bf16 v[48:51], v[120:123], v[194:197], v[52:55]
	v_mfma_f32_16x16x32_bf16 v[52:55], v[124:127], v[198:201], v[48:51]
	v_mfma_f32_16x16x32_bf16 v[48:51], v[162:165], v[194:197], v[56:59]
	v_mfma_f32_16x16x32_bf16 v[174:177], v[166:169], v[198:201], v[48:51]
	s_setprio 0
	s_barrier
	s_nop 1
	s_mov_b32 m0, s49
	v_lshl_add_u64 v[134:135], s[26:27], 0, v[212:213]
	s_add_u32 s22, s26, 0x10000
	s_nop 0
	ds_read_b128 v[48:51], v137 offset:16384
	ds_read_b128 v[56:59], v137 offset:17408
	ds_read_b128 v[88:91], v137 offset:18432
	ds_read_b128 v[96:99], v137 offset:19456
	ds_read_b128 v[178:181], v137 offset:20480
	ds_read_b128 v[182:185], v137 offset:21504
	ds_read_b128 v[186:189], v137 offset:22528
	ds_read_b128 v[190:193], v137 offset:23552
	global_load_lds_dwordx4 v[134:135], off
	v_lshl_add_u64 v[210:211], s[26:27], 0, v[128:129]
	s_mov_b32 m0, s13
	s_addc_u32 s23, s27, 0
	global_load_lds_dwordx4 v[210:211], off
	v_lshl_add_u64 v[194:195], s[22:23], 0, v[212:213]
	s_mov_b32 m0, s15
	v_lshl_add_u64 v[226:227], s[28:29], 0, v[132:133]
	global_load_lds_dwordx4 v[194:195], off
	v_lshl_add_u64 v[194:195], s[22:23], 0, v[128:129]
	s_mov_b32 m0, s47
	v_lshl_add_u64 v[234:235], s[28:29], 0, v[130:131]
	global_load_lds_dwordx4 v[194:195], off
	s_mov_b32 m0, s21
	s_nop 0
	global_load_lds_dwordx4 v[226:227], off
	s_mov_b32 m0, s39
	s_nop 0
	global_load_lds_dwordx4 v[234:235], off
	s_waitcnt vmcnt(8)
	s_waitcnt lgkmcnt(0)
	s_barrier
	s_setprio 1
	v_mfma_f32_16x16x32_bf16 v[0:3], v[104:107], v[186:189], v[0:3]
	v_mfma_f32_16x16x32_bf16 v[0:3], v[108:111], v[190:193], v[0:3]
	v_mfma_f32_16x16x32_bf16 v[138:141], v[104:107], v[48:51], v[138:141]
	v_mfma_f32_16x16x32_bf16 v[138:141], v[108:111], v[56:59], v[138:141]
	v_mfma_f32_16x16x32_bf16 v[146:149], v[104:107], v[88:91], v[146:149]
	v_mfma_f32_16x16x32_bf16 v[146:149], v[108:111], v[96:99], v[146:149]
	v_mfma_f32_16x16x32_bf16 v[154:157], v[104:107], v[178:181], v[154:157]
	v_mfma_f32_16x16x32_bf16 v[154:157], v[108:111], v[182:185], v[154:157]
	v_mfma_f32_16x16x32_bf16 v[4:7], v[112:115], v[186:189], v[4:7]
	v_mfma_f32_16x16x32_bf16 v[4:7], v[116:119], v[190:193], v[4:7]
	v_mfma_f32_16x16x32_bf16 v[142:145], v[112:115], v[48:51], v[142:145]
	v_mfma_f32_16x16x32_bf16 v[142:145], v[116:119], v[56:59], v[142:145]
	v_mfma_f32_16x16x32_bf16 v[150:153], v[112:115], v[88:91], v[150:153]
	v_mfma_f32_16x16x32_bf16 v[150:153], v[116:119], v[96:99], v[150:153]
	v_mfma_f32_16x16x32_bf16 v[158:161], v[112:115], v[178:181], v[158:161]
	v_mfma_f32_16x16x32_bf16 v[158:161], v[116:119], v[182:185], v[158:161]
	v_mfma_f32_16x16x32_bf16 v[12:15], v[162:165], v[48:51], v[12:15]
	v_mfma_f32_16x16x32_bf16 v[194:197], v[166:169], v[56:59], v[12:15]
	v_mfma_f32_16x16x32_bf16 v[12:15], v[120:123], v[88:91], v[24:27]
	v_mfma_f32_16x16x32_bf16 v[24:27], v[124:127], v[96:99], v[12:15]
	v_mfma_f32_16x16x32_bf16 v[12:15], v[162:165], v[88:91], v[28:31]
	v_mfma_f32_16x16x32_bf16 v[198:201], v[166:169], v[96:99], v[12:15]
	v_mfma_f32_16x16x32_bf16 v[12:15], v[120:123], v[178:181], v[60:63]
	v_mfma_f32_16x16x32_bf16 v[218:221], v[124:127], v[182:185], v[12:15]
	v_mfma_f32_16x16x32_bf16 v[12:15], v[162:165], v[178:181], v[100:103]
	v_mfma_f32_16x16x32_bf16 v[178:181], v[166:169], v[182:185], v[12:15]
	v_mfma_f32_16x16x32_bf16 v[8:11], v[120:123], v[48:51], v[8:11]
	v_mfma_f32_16x16x32_bf16 v[8:11], v[124:127], v[56:59], v[8:11]
	v_mfma_f32_16x16x32_bf16 v[12:15], v[120:123], v[186:189], v[16:19]
	v_mfma_f32_16x16x32_bf16 v[182:185], v[124:127], v[190:193], v[12:15]
	v_mfma_f32_16x16x32_bf16 v[12:15], v[162:165], v[186:189], v[20:23]
	v_mfma_f32_16x16x32_bf16 v[162:165], v[166:169], v[190:193], v[12:15]
	s_setprio 0
	s_barrier
	s_nop 1
	s_nop 4
	ds_read_b128 v[12:15], v214
	ds_read_b128 v[16:19], v214 offset:1024
	ds_read_b128 v[166:169], v214 offset:2048
	ds_read_b128 v[186:189], v214 offset:3072
	ds_read_b128 v[190:193], v215
	ds_read_b128 v[222:225], v215 offset:1024
	ds_read_b128 v[238:241], v215 offset:2048
	ds_read_b128 v[242:245], v215 offset:3072
	s_add_u32 s22, s28, 0x10000
	s_addc_u32 s23, s29, 0
	s_mov_b32 m0, s40
	v_lshl_add_u64 v[48:49], s[22:23], 0, v[132:133]
	ds_read_b128 v[20:23], v137 offset:32768
	ds_read_b128 v[28:31], v137 offset:33792
	ds_read_b128 v[60:63], v137 offset:34816
	ds_read_b128 v[100:103], v137 offset:35840
	ds_read_b128 v[246:249], v137 offset:36864
	ds_read_b128 v[250:253], v137 offset:37888
	ds_read_b128 v[230:233], v137 offset:38912
	ds_read_b128 v[214:217], v137 offset:39936
	global_load_lds_dwordx4 v[48:49], off
	v_lshl_add_u64 v[48:49], s[22:23], 0, v[130:131]
	s_mov_b32 m0, s41
	s_nop 0
	global_load_lds_dwordx4 v[48:49], off
	s_waitcnt vmcnt(8)
	s_waitcnt lgkmcnt(0)
	s_barrier
	s_setprio 1
	v_mfma_f32_16x16x32_bf16 v[48:51], v[12:15], v[20:23], v[64:67]
	v_mfma_f32_16x16x32_bf16 v[120:123], v[16:19], v[28:31], v[48:51]
	v_mfma_f32_16x16x32_bf16 v[48:51], v[166:169], v[20:23], v[68:71]
	v_mfma_f32_16x16x32_bf16 v[112:115], v[186:189], v[28:31], v[48:51]
	v_mfma_f32_16x16x32_bf16 v[48:51], v[12:15], v[60:63], v[72:75]
	v_mfma_f32_16x16x32_bf16 v[104:107], v[16:19], v[100:103], v[48:51]
	v_mfma_f32_16x16x32_bf16 v[48:51], v[166:169], v[60:63], v[76:79]
	v_mfma_f32_16x16x32_bf16 v[96:99], v[186:189], v[100:103], v[48:51]
	v_mfma_f32_16x16x32_bf16 v[48:51], v[12:15], v[246:249], v[80:83]
	v_mfma_f32_16x16x32_bf16 v[88:91], v[16:19], v[250:253], v[48:51]
	v_mfma_f32_16x16x32_bf16 v[48:51], v[166:169], v[246:249], v[84:87]
	v_mfma_f32_16x16x32_bf16 v[80:83], v[186:189], v[250:253], v[48:51]
	v_mfma_f32_16x16x32_bf16 v[48:51], v[12:15], v[230:233], v[202:205]
	v_mfma_f32_16x16x32_bf16 v[56:59], v[16:19], v[214:217], v[48:51]
	v_mfma_f32_16x16x32_bf16 v[48:51], v[166:169], v[230:233], v[92:95]
	v_mfma_f32_16x16x32_bf16 v[48:51], v[186:189], v[214:217], v[48:51]
	v_mfma_f32_16x16x32_bf16 v[64:67], v[190:193], v[20:23], v[206:209]
	v_mfma_f32_16x16x32_bf16 v[124:127], v[222:225], v[28:31], v[64:67]
	v_mfma_f32_16x16x32_bf16 v[20:23], v[238:241], v[20:23], v[32:35]
	v_mfma_f32_16x16x32_bf16 v[116:119], v[242:245], v[28:31], v[20:23]
	v_mfma_f32_16x16x32_bf16 v[20:23], v[190:193], v[60:63], v[36:39]
	v_mfma_f32_16x16x32_bf16 v[108:111], v[222:225], v[100:103], v[20:23]
	v_mfma_f32_16x16x32_bf16 v[20:23], v[238:241], v[60:63], v[40:43]
	v_mfma_f32_16x16x32_bf16 v[100:103], v[242:245], v[100:103], v[20:23]
	v_mfma_f32_16x16x32_bf16 v[20:23], v[190:193], v[246:249], v[44:47]
	v_mfma_f32_16x16x32_bf16 v[92:95], v[222:225], v[250:253], v[20:23]
	v_mfma_f32_16x16x32_bf16 v[20:23], v[238:241], v[246:249], v[170:173]
	v_mfma_f32_16x16x32_bf16 v[84:87], v[242:245], v[250:253], v[20:23]
	v_mfma_f32_16x16x32_bf16 v[20:23], v[190:193], v[230:233], v[52:55]
	v_mfma_f32_16x16x32_bf16 v[60:63], v[222:225], v[214:217], v[20:23]
	v_mfma_f32_16x16x32_bf16 v[20:23], v[238:241], v[230:233], v[174:177]
	v_mfma_f32_16x16x32_bf16 v[52:55], v[242:245], v[214:217], v[20:23]
	s_setprio 0
	s_barrier
	s_nop 1
	s_mov_b32 m0, s52
	s_nop 2
	v_lshl_add_u64 v[20:21], v[134:135], 0, s[72:73]
	s_add_u32 s22, s26, 0x10080
	ds_read_b128 v[32:35], v137 offset:49152
	ds_read_b128 v[40:43], v137 offset:50176
	ds_read_b128 v[170:173], v137 offset:51200
	ds_read_b128 v[174:177], v137 offset:52224
	ds_read_b128 v[202:205], v137 offset:53248
	ds_read_b128 v[206:209], v137 offset:54272
	ds_read_b128 v[214:217], v137 offset:55296
	ds_read_b128 v[230:233], v137 offset:56320
	global_load_lds_dwordx4 v[20:21], off
	v_lshl_add_u64 v[20:21], v[210:211], 0, s[72:73]
	s_mov_b32 m0, s50
	s_addc_u32 s23, s27, 0
	global_load_lds_dwordx4 v[20:21], off
	v_lshl_add_u64 v[20:21], s[22:23], 0, v[212:213]
	s_mov_b32 m0, s24
	s_nop 0
	global_load_lds_dwordx4 v[20:21], off
	v_lshl_add_u64 v[20:21], s[22:23], 0, v[128:129]
	s_mov_b32 m0, s25
	s_nop 0
	global_load_lds_dwordx4 v[20:21], off
	v_lshl_add_u64 v[20:21], v[226:227], 0, s[72:73]
	s_mov_b32 m0, s44
	s_nop 0
	global_load_lds_dwordx4 v[20:21], off
	v_lshl_add_u64 v[20:21], v[234:235], 0, s[72:73]
	s_mov_b32 m0, s45
	s_nop 0
	global_load_lds_dwordx4 v[20:21], off
	s_waitcnt vmcnt(8)
	s_waitcnt lgkmcnt(0)
	s_barrier
	s_setprio 1
	v_mfma_f32_16x16x32_bf16 v[20:23], v[12:15], v[32:35], v[138:141]
	v_mfma_f32_16x16x32_bf16 v[76:79], v[16:19], v[40:43], v[20:23]
	v_mfma_f32_16x16x32_bf16 v[20:23], v[166:169], v[32:35], v[142:145]
	v_mfma_f32_16x16x32_bf16 v[68:71], v[186:189], v[40:43], v[20:23]
	v_mfma_f32_16x16x32_bf16 v[20:23], v[12:15], v[170:173], v[146:149]
	v_mfma_f32_16x16x32_bf16 v[44:47], v[16:19], v[174:177], v[20:23]
	v_mfma_f32_16x16x32_bf16 v[20:23], v[166:169], v[170:173], v[150:153]
	v_mfma_f32_16x16x32_bf16 v[36:39], v[186:189], v[174:177], v[20:23]
	v_mfma_f32_16x16x32_bf16 v[20:23], v[12:15], v[202:205], v[154:157]
	v_mfma_f32_16x16x32_bf16 v[28:31], v[16:19], v[206:209], v[20:23]
	v_mfma_f32_16x16x32_bf16 v[0:3], v[12:15], v[214:217], v[0:3]
	v_mfma_f32_16x16x32_bf16 v[12:15], v[16:19], v[230:233], v[0:3]
	v_mfma_f32_16x16x32_bf16 v[20:23], v[166:169], v[202:205], v[158:161]
	v_mfma_f32_16x16x32_bf16 v[20:23], v[186:189], v[206:209], v[20:23]
	v_mfma_f32_16x16x32_bf16 v[0:3], v[166:169], v[214:217], v[4:7]
	v_mfma_f32_16x16x32_bf16 v[4:7], v[186:189], v[230:233], v[0:3]
	v_mfma_f32_16x16x32_bf16 v[0:3], v[190:193], v[32:35], v[8:11]
	v_mfma_f32_16x16x32_bf16 v[72:75], v[222:225], v[40:43], v[0:3]
	v_mfma_f32_16x16x32_bf16 v[0:3], v[238:241], v[32:35], v[194:197]
	v_mfma_f32_16x16x32_bf16 v[64:67], v[242:245], v[40:43], v[0:3]
	v_mfma_f32_16x16x32_bf16 v[0:3], v[190:193], v[170:173], v[24:27]
	v_mfma_f32_16x16x32_bf16 v[40:43], v[222:225], v[174:177], v[0:3]
	v_mfma_f32_16x16x32_bf16 v[0:3], v[238:241], v[170:173], v[198:201]
	v_mfma_f32_16x16x32_bf16 v[32:35], v[242:245], v[174:177], v[0:3]
	v_mfma_f32_16x16x32_bf16 v[0:3], v[190:193], v[202:205], v[218:221]
	v_mfma_f32_16x16x32_bf16 v[24:27], v[222:225], v[206:209], v[0:3]
	v_mfma_f32_16x16x32_bf16 v[0:3], v[238:241], v[202:205], v[178:181]
	v_mfma_f32_16x16x32_bf16 v[16:19], v[242:245], v[206:209], v[0:3]
	v_mfma_f32_16x16x32_bf16 v[0:3], v[190:193], v[214:217], v[182:185]
	v_mfma_f32_16x16x32_bf16 v[8:11], v[222:225], v[230:233], v[0:3]
	v_mfma_f32_16x16x32_bf16 v[0:3], v[238:241], v[214:217], v[162:165]
	v_mfma_f32_16x16x32_bf16 v[0:3], v[242:245], v[230:233], v[0:3]
	s_setprio 0
	s_barrier
	s_nop 1
	s_andn2_b64 vcc, exec, s[8:9]
	s_cbranch_vccnz .LBB0_1014
	s_barrier

.LBB0_1239:
	s_add_i32 s2, s34, 2
	s_add_u32 s3, s74, s30
	s_addc_u32 s35, s75, s31
	s_add_u32 s3, s3, 0x100
	s_addc_u32 s35, s35, 0
	s_add_u32 s39, s9, s30
	s_addc_u32 s63, s17, s31
	s_cmp_eq_u32 s45, s34
	s_cselect_b32 s89, s11, s35
	s_cselect_b32 s88, s10, s3
	s_cselect_b32 s35, s13, s63
	s_cselect_b32 s34, s12, s39
	s_add_i32 s3, 0, 0x10000
	s_add_i32 s39, 0, 0x14000
	v_add_u32_e32 v136, s3, v220
	v_add_u32_e32 v160, s39, v220
	ds_read_b128 v[108:111], v136
	ds_read_b128 v[120:123], v136 offset:1024
	ds_read_b128 v[132:135], v136 offset:2048
	ds_read_b128 v[136:139], v136 offset:3072
	ds_read_b128 v[140:143], v160
	ds_read_b128 v[144:147], v160 offset:1024
	ds_read_b128 v[148:151], v160 offset:2048
	ds_read_b128 v[160:163], v160 offset:3072
	v_lshl_add_u64 v[196:197], v[96:97], 0, s[30:31]
	s_add_i32 m0, s15, 0xc000
	ds_read_b128 v[164:167], v223
	ds_read_b128 v[168:171], v223 offset:1024
	ds_read_b128 v[172:175], v223 offset:2048
	ds_read_b128 v[176:179], v223 offset:3072
	ds_read_b128 v[180:183], v223 offset:4096
	ds_read_b128 v[184:187], v223 offset:5120
	ds_read_b128 v[188:191], v223 offset:6144
	ds_read_b128 v[192:195], v223 offset:7168
	global_load_lds_dwordx4 v[196:197], off
	v_lshl_add_u64 v[196:197], v[98:99], 0, s[30:31]
	s_add_i32 m0, s15, 0xe000
	s_nop 0
	global_load_lds_dwordx4 v[196:197], off
	s_waitcnt vmcnt(8)
	s_waitcnt lgkmcnt(0)
	s_barrier
	s_setprio 1
	v_mfma_f32_16x16x32_bf16 v[156:159], v[108:111], v[164:167], v[156:159]
	v_mfma_f32_16x16x32_bf16 v[156:159], v[120:123], v[168:171], v[156:159]
	v_mfma_f32_16x16x32_bf16 v[128:131], v[108:111], v[172:175], v[128:131]
	v_mfma_f32_16x16x32_bf16 v[128:131], v[120:123], v[176:179], v[128:131]
	v_mfma_f32_16x16x32_bf16 v[116:119], v[108:111], v[180:183], v[116:119]
	v_mfma_f32_16x16x32_bf16 v[116:119], v[120:123], v[184:187], v[116:119]
	v_mfma_f32_16x16x32_bf16 v[104:107], v[108:111], v[188:191], v[104:107]
	v_mfma_f32_16x16x32_bf16 v[104:107], v[120:123], v[192:195], v[104:107]
	v_mfma_f32_16x16x32_bf16 v[152:155], v[132:135], v[164:167], v[152:155]
	v_mfma_f32_16x16x32_bf16 v[152:155], v[136:139], v[168:171], v[152:155]
	v_mfma_f32_16x16x32_bf16 v[124:127], v[132:135], v[172:175], v[124:127]
	v_mfma_f32_16x16x32_bf16 v[124:127], v[136:139], v[176:179], v[124:127]
	v_mfma_f32_16x16x32_bf16 v[112:115], v[132:135], v[180:183], v[112:115]
	v_mfma_f32_16x16x32_bf16 v[112:115], v[136:139], v[184:187], v[112:115]
	v_mfma_f32_16x16x32_bf16 v[100:103], v[132:135], v[188:191], v[100:103]
	v_mfma_f32_16x16x32_bf16 v[100:103], v[136:139], v[192:195], v[100:103]
	v_mfma_f32_16x16x32_bf16 v[92:95], v[140:143], v[164:167], v[92:95]
	v_mfma_f32_16x16x32_bf16 v[92:95], v[144:147], v[168:171], v[92:95]
	v_mfma_f32_16x16x32_bf16 v[84:87], v[140:143], v[172:175], v[84:87]
	v_mfma_f32_16x16x32_bf16 v[84:87], v[144:147], v[176:179], v[84:87]
	v_mfma_f32_16x16x32_bf16 v[76:79], v[140:143], v[180:183], v[76:79]
	v_mfma_f32_16x16x32_bf16 v[76:79], v[144:147], v[184:187], v[76:79]
	v_mfma_f32_16x16x32_bf16 v[68:71], v[140:143], v[188:191], v[68:71]
	v_mfma_f32_16x16x32_bf16 v[68:71], v[144:147], v[192:195], v[68:71]
	v_mfma_f32_16x16x32_bf16 v[88:91], v[148:151], v[164:167], v[88:91]
	v_mfma_f32_16x16x32_bf16 v[88:91], v[160:163], v[168:171], v[88:91]
	v_mfma_f32_16x16x32_bf16 v[80:83], v[148:151], v[172:175], v[80:83]
	v_mfma_f32_16x16x32_bf16 v[80:83], v[160:163], v[176:179], v[80:83]
	v_mfma_f32_16x16x32_bf16 v[72:75], v[148:151], v[180:183], v[72:75]
	v_mfma_f32_16x16x32_bf16 v[72:75], v[160:163], v[184:187], v[72:75]
	v_mfma_f32_16x16x32_bf16 v[64:67], v[148:151], v[188:191], v[64:67]
	v_mfma_f32_16x16x32_bf16 v[64:67], v[160:163], v[192:195], v[64:67]
	s_setprio 0
	s_barrier
	s_nop 1
	s_add_i32 s3, s3, s64
	v_lshl_add_u64 v[196:197], s[34:35], 0, v[212:213]
	s_mov_b32 m0, s3
	ds_read_b128 v[164:167], v223 offset:16384
	ds_read_b128 v[168:171], v223 offset:17408
	ds_read_b128 v[172:175], v223 offset:18432
	ds_read_b128 v[176:179], v223 offset:19456
	ds_read_b128 v[180:183], v223 offset:20480
	ds_read_b128 v[184:187], v223 offset:21504
	ds_read_b128 v[188:191], v223 offset:22528
	ds_read_b128 v[192:195], v223 offset:23552
	global_load_lds_dwordx4 v[196:197], off
	s_add_i32 m0, s3, 0x2000
	s_add_u32 vcc_lo, s34, 0x80000
	v_lshl_add_u64 v[198:199], s[34:35], 0, v[208:209]
	s_addc_u32 vcc_hi, s35, 0
	s_add_i32 s3, s39, s64
	global_load_lds_dwordx4 v[198:199], off
	v_lshl_add_u64 v[200:201], vcc, 0, v[212:213]
	s_mov_b32 m0, s3
	v_lshl_add_u64 v[202:203], s[88:89], 0, v[206:207]
	global_load_lds_dwordx4 v[200:201], off
	v_lshl_add_u64 v[200:201], vcc, 0, v[208:209]
	s_add_i32 m0, s3, 0x2000
	s_nop 0
	global_load_lds_dwordx4 v[200:201], off
	v_lshl_add_u64 v[200:201], s[88:89], 0, v[204:205]
	s_mov_b32 m0, s15
	s_nop 0
	global_load_lds_dwordx4 v[200:201], off
	s_mov_b32 m0, s43
	s_nop 0
	global_load_lds_dwordx4 v[202:203], off
	s_waitcnt vmcnt(8)
	s_waitcnt lgkmcnt(0)
	s_barrier
	s_setprio 1
	v_mfma_f32_16x16x32_bf16 v[60:63], v[108:111], v[164:167], v[60:63]
	v_mfma_f32_16x16x32_bf16 v[60:63], v[120:123], v[168:171], v[60:63]
	v_mfma_f32_16x16x32_bf16 v[52:55], v[108:111], v[172:175], v[52:55]
	v_mfma_f32_16x16x32_bf16 v[52:55], v[120:123], v[176:179], v[52:55]
	v_mfma_f32_16x16x32_bf16 v[44:47], v[108:111], v[180:183], v[44:47]
	v_mfma_f32_16x16x32_bf16 v[44:47], v[120:123], v[184:187], v[44:47]
	v_mfma_f32_16x16x32_bf16 v[36:39], v[108:111], v[188:191], v[36:39]
	v_mfma_f32_16x16x32_bf16 v[36:39], v[120:123], v[192:195], v[36:39]
	v_mfma_f32_16x16x32_bf16 v[56:59], v[132:135], v[164:167], v[56:59]
	v_mfma_f32_16x16x32_bf16 v[56:59], v[136:139], v[168:171], v[56:59]
	v_mfma_f32_16x16x32_bf16 v[48:51], v[132:135], v[172:175], v[48:51]
	v_mfma_f32_16x16x32_bf16 v[48:51], v[136:139], v[176:179], v[48:51]
	v_mfma_f32_16x16x32_bf16 v[40:43], v[132:135], v[180:183], v[40:43]
	v_mfma_f32_16x16x32_bf16 v[40:43], v[136:139], v[184:187], v[40:43]
	v_mfma_f32_16x16x32_bf16 v[32:35], v[132:135], v[188:191], v[32:35]
	v_mfma_f32_16x16x32_bf16 v[32:35], v[136:139], v[192:195], v[32:35]
	v_mfma_f32_16x16x32_bf16 v[28:31], v[140:143], v[164:167], v[28:31]
	v_mfma_f32_16x16x32_bf16 v[28:31], v[144:147], v[168:171], v[28:31]
	v_mfma_f32_16x16x32_bf16 v[20:23], v[140:143], v[172:175], v[20:23]
	v_mfma_f32_16x16x32_bf16 v[20:23], v[144:147], v[176:179], v[20:23]
	v_mfma_f32_16x16x32_bf16 v[12:15], v[140:143], v[180:183], v[12:15]
	v_mfma_f32_16x16x32_bf16 v[12:15], v[144:147], v[184:187], v[12:15]
	v_mfma_f32_16x16x32_bf16 v[4:7], v[140:143], v[188:191], v[4:7]
	v_mfma_f32_16x16x32_bf16 v[4:7], v[144:147], v[192:195], v[4:7]
	v_mfma_f32_16x16x32_bf16 v[24:27], v[148:151], v[164:167], v[24:27]
	v_mfma_f32_16x16x32_bf16 v[24:27], v[160:163], v[168:171], v[24:27]
	v_mfma_f32_16x16x32_bf16 v[16:19], v[148:151], v[172:175], v[16:19]
	v_mfma_f32_16x16x32_bf16 v[16:19], v[160:163], v[176:179], v[16:19]
	v_mfma_f32_16x16x32_bf16 v[8:11], v[148:151], v[180:183], v[8:11]
	v_mfma_f32_16x16x32_bf16 v[8:11], v[160:163], v[184:187], v[8:11]
	v_mfma_f32_16x16x32_bf16 v[0:3], v[148:151], v[188:191], v[0:3]
	v_mfma_f32_16x16x32_bf16 v[0:3], v[160:163], v[192:195], v[0:3]
	s_setprio 0
	s_barrier
	s_nop 1
	s_add_i32 s3, 0, 0x18000
	s_add_i32 s39, 0, 0x1c000
	v_add_u32_e32 v136, s3, v220
	v_add_u32_e32 v160, s39, v220
	ds_read_b128 v[108:111], v136
	ds_read_b128 v[120:123], v136 offset:1024
	ds_read_b128 v[132:135], v136 offset:2048
	ds_read_b128 v[136:139], v136 offset:3072
	ds_read_b128 v[140:143], v160
	ds_read_b128 v[144:147], v160 offset:1024
	ds_read_b128 v[148:151], v160 offset:2048
	ds_read_b128 v[160:163], v160 offset:3072
	s_add_u32 s88, s88, 0x80000
	s_addc_u32 s89, s89, 0
	s_mov_b32 m0, s69
	v_lshl_add_u64 v[214:215], s[88:89], 0, v[204:205]
	ds_read_b128 v[164:167], v223 offset:32768
	ds_read_b128 v[168:171], v223 offset:33792
	ds_read_b128 v[172:175], v223 offset:34816
	ds_read_b128 v[176:179], v223 offset:35840
	ds_read_b128 v[180:183], v223 offset:36864
	ds_read_b128 v[184:187], v223 offset:37888
	ds_read_b128 v[188:191], v223 offset:38912
	ds_read_b128 v[192:195], v223 offset:39936
	global_load_lds_dwordx4 v[214:215], off
	v_lshl_add_u64 v[214:215], s[88:89], 0, v[206:207]
	s_mov_b32 m0, s70
	s_nop 0
	global_load_lds_dwordx4 v[214:215], off
	s_waitcnt vmcnt(8)
	s_waitcnt lgkmcnt(0)
	s_barrier
	s_setprio 1
	v_mfma_f32_16x16x32_bf16 v[156:159], v[108:111], v[164:167], v[156:159]
	v_mfma_f32_16x16x32_bf16 v[156:159], v[120:123], v[168:171], v[156:159]
	v_mfma_f32_16x16x32_bf16 v[128:131], v[108:111], v[172:175], v[128:131]
	v_mfma_f32_16x16x32_bf16 v[128:131], v[120:123], v[176:179], v[128:131]
	v_mfma_f32_16x16x32_bf16 v[116:119], v[108:111], v[180:183], v[116:119]
	v_mfma_f32_16x16x32_bf16 v[116:119], v[120:123], v[184:187], v[116:119]
	v_mfma_f32_16x16x32_bf16 v[104:107], v[108:111], v[188:191], v[104:107]
	v_mfma_f32_16x16x32_bf16 v[104:107], v[120:123], v[192:195], v[104:107]
	v_mfma_f32_16x16x32_bf16 v[152:155], v[132:135], v[164:167], v[152:155]
	v_mfma_f32_16x16x32_bf16 v[152:155], v[136:139], v[168:171], v[152:155]
	v_mfma_f32_16x16x32_bf16 v[124:127], v[132:135], v[172:175], v[124:127]
	v_mfma_f32_16x16x32_bf16 v[124:127], v[136:139], v[176:179], v[124:127]
	v_mfma_f32_16x16x32_bf16 v[112:115], v[132:135], v[180:183], v[112:115]
	v_mfma_f32_16x16x32_bf16 v[112:115], v[136:139], v[184:187], v[112:115]
	v_mfma_f32_16x16x32_bf16 v[100:103], v[132:135], v[188:191], v[100:103]
	v_mfma_f32_16x16x32_bf16 v[100:103], v[136:139], v[192:195], v[100:103]
	v_mfma_f32_16x16x32_bf16 v[92:95], v[140:143], v[164:167], v[92:95]
	v_mfma_f32_16x16x32_bf16 v[92:95], v[144:147], v[168:171], v[92:95]
	v_mfma_f32_16x16x32_bf16 v[84:87], v[140:143], v[172:175], v[84:87]
	v_mfma_f32_16x16x32_bf16 v[84:87], v[144:147], v[176:179], v[84:87]
	v_mfma_f32_16x16x32_bf16 v[76:79], v[140:143], v[180:183], v[76:79]
	v_mfma_f32_16x16x32_bf16 v[76:79], v[144:147], v[184:187], v[76:79]
	v_mfma_f32_16x16x32_bf16 v[68:71], v[140:143], v[188:191], v[68:71]
	v_mfma_f32_16x16x32_bf16 v[68:71], v[144:147], v[192:195], v[68:71]
	v_mfma_f32_16x16x32_bf16 v[88:91], v[148:151], v[164:167], v[88:91]
	v_mfma_f32_16x16x32_bf16 v[88:91], v[160:163], v[168:171], v[88:91]
	v_mfma_f32_16x16x32_bf16 v[80:83], v[148:151], v[172:175], v[80:83]
	v_mfma_f32_16x16x32_bf16 v[80:83], v[160:163], v[176:179], v[80:83]
	v_mfma_f32_16x16x32_bf16 v[72:75], v[148:151], v[180:183], v[72:75]
	v_mfma_f32_16x16x32_bf16 v[72:75], v[160:163], v[184:187], v[72:75]
	v_mfma_f32_16x16x32_bf16 v[64:67], v[148:151], v[188:191], v[64:67]
	v_mfma_f32_16x16x32_bf16 v[64:67], v[160:163], v[192:195], v[64:67]
	s_setprio 0
	s_barrier
	s_nop 1
	s_add_i32 s3, s3, s64
	v_lshl_add_u64 v[196:197], v[196:197], 0, s[72:73]
	s_mov_b32 m0, s3
	ds_read_b128 v[164:167], v223 offset:49152
	ds_read_b128 v[168:171], v223 offset:50176
	ds_read_b128 v[172:175], v223 offset:51200
	ds_read_b128 v[176:179], v223 offset:52224
	ds_read_b128 v[180:183], v223 offset:53248
	ds_read_b128 v[184:187], v223 offset:54272
	ds_read_b128 v[188:191], v223 offset:55296
	ds_read_b128 v[192:195], v223 offset:56320
	global_load_lds_dwordx4 v[196:197], off
	s_add_i32 m0, s3, 0x2000
	s_add_u32 s34, s34, 0x80080
	v_lshl_add_u64 v[196:197], v[198:199], 0, s[72:73]
	s_addc_u32 s35, s35, 0
	s_add_i32 s3, s39, s64
	global_load_lds_dwordx4 v[196:197], off
	v_lshl_add_u64 v[196:197], s[34:35], 0, v[212:213]
	s_mov_b32 m0, s3
	s_nop 0
	global_load_lds_dwordx4 v[196:197], off
	v_lshl_add_u64 v[196:197], s[34:35], 0, v[208:209]
	s_add_i32 m0, s3, 0x2000
	s_nop 0
	global_load_lds_dwordx4 v[196:197], off
	v_lshl_add_u64 v[196:197], v[200:201], 0, s[72:73]
	s_mov_b32 m0, s83
	s_nop 0
	global_load_lds_dwordx4 v[196:197], off
	v_lshl_add_u64 v[196:197], v[202:203], 0, s[72:73]
	s_mov_b32 m0, s84
	s_nop 0
	global_load_lds_dwordx4 v[196:197], off
	s_waitcnt vmcnt(8)
	s_waitcnt lgkmcnt(0)
	s_barrier
	s_setprio 1
	v_mfma_f32_16x16x32_bf16 v[60:63], v[108:111], v[164:167], v[60:63]
	v_mfma_f32_16x16x32_bf16 v[60:63], v[120:123], v[168:171], v[60:63]
	v_mfma_f32_16x16x32_bf16 v[52:55], v[108:111], v[172:175], v[52:55]
	v_mfma_f32_16x16x32_bf16 v[52:55], v[120:123], v[176:179], v[52:55]
	v_mfma_f32_16x16x32_bf16 v[44:47], v[108:111], v[180:183], v[44:47]
	v_mfma_f32_16x16x32_bf16 v[44:47], v[120:123], v[184:187], v[44:47]
	v_mfma_f32_16x16x32_bf16 v[36:39], v[108:111], v[188:191], v[36:39]
	v_mfma_f32_16x16x32_bf16 v[36:39], v[120:123], v[192:195], v[36:39]
	v_mfma_f32_16x16x32_bf16 v[56:59], v[132:135], v[164:167], v[56:59]
	v_mfma_f32_16x16x32_bf16 v[56:59], v[136:139], v[168:171], v[56:59]
	v_mfma_f32_16x16x32_bf16 v[48:51], v[132:135], v[172:175], v[48:51]
	v_mfma_f32_16x16x32_bf16 v[48:51], v[136:139], v[176:179], v[48:51]
	v_mfma_f32_16x16x32_bf16 v[40:43], v[132:135], v[180:183], v[40:43]
	v_mfma_f32_16x16x32_bf16 v[40:43], v[136:139], v[184:187], v[40:43]
	v_mfma_f32_16x16x32_bf16 v[32:35], v[132:135], v[188:191], v[32:35]
	v_mfma_f32_16x16x32_bf16 v[32:35], v[136:139], v[192:195], v[32:35]
	v_mfma_f32_16x16x32_bf16 v[28:31], v[140:143], v[164:167], v[28:31]
	v_mfma_f32_16x16x32_bf16 v[28:31], v[144:147], v[168:171], v[28:31]
	v_mfma_f32_16x16x32_bf16 v[20:23], v[140:143], v[172:175], v[20:23]
	v_mfma_f32_16x16x32_bf16 v[20:23], v[144:147], v[176:179], v[20:23]
	v_mfma_f32_16x16x32_bf16 v[12:15], v[140:143], v[180:183], v[12:15]
	v_mfma_f32_16x16x32_bf16 v[12:15], v[144:147], v[184:187], v[12:15]
	v_mfma_f32_16x16x32_bf16 v[4:7], v[140:143], v[188:191], v[4:7]
	v_mfma_f32_16x16x32_bf16 v[4:7], v[144:147], v[192:195], v[4:7]
	v_mfma_f32_16x16x32_bf16 v[24:27], v[148:151], v[164:167], v[24:27]
	v_mfma_f32_16x16x32_bf16 v[24:27], v[160:163], v[168:171], v[24:27]
	v_mfma_f32_16x16x32_bf16 v[16:19], v[148:151], v[172:175], v[16:19]
	v_mfma_f32_16x16x32_bf16 v[16:19], v[160:163], v[176:179], v[16:19]
	v_mfma_f32_16x16x32_bf16 v[8:11], v[148:151], v[180:183], v[8:11]
	v_mfma_f32_16x16x32_bf16 v[8:11], v[160:163], v[184:187], v[8:11]
	v_mfma_f32_16x16x32_bf16 v[0:3], v[148:151], v[188:191], v[0:3]
	v_mfma_f32_16x16x32_bf16 v[0:3], v[160:163], v[192:195], v[0:3]
	s_setprio 0
	s_barrier
	s_nop 1
	s_add_u32 s30, s30, 0x100
	s_addc_u32 s31, s31, 0
	s_cmp_ge_i32 s2, s19
	s_mov_b32 s34, s2
	s_cbranch_scc1 .LBB0_1246

.LBB0_1413:
	s_lshl_b32 s2, s9, 7
	s_add_u32 s3, s74, s2
	s_addc_u32 s24, s75, 0
	s_add_u32 s20, s3, 0x100
	s_addc_u32 s21, s24, 0
	s_add_u32 s2, s14, s2
	s_addc_u32 s22, s15, 0
	s_add_u32 s2, s2, 0x100
	s_addc_u32 s25, s22, 0
	s_cmp_eq_u32 s9, 30
	s_cselect_b32 s23, s5, s21
	s_cselect_b32 s22, s59, s20
	s_cselect_b32 s21, s57, s25
	s_cselect_b32 s20, s30, s2
	s_add_i32 s25, 0, 0x10000
	s_add_i32 s26, 0, 0x14000
	v_add_u32_e32 v28, s25, v226
	v_add_u32_e32 v44, s26, v226
	ds_read_b128 v[16:19], v28
	ds_read_b128 v[20:23], v28 offset:1024
	ds_read_b128 v[24:27], v28 offset:2048
	ds_read_b128 v[28:31], v28 offset:3072
	ds_read_b128 v[32:35], v44
	ds_read_b128 v[36:39], v44 offset:1024
	ds_read_b128 v[40:43], v44 offset:2048
	ds_read_b128 v[44:47], v44 offset:3072
	s_add_u32 s2, s3, 0x80080
	s_addc_u32 s3, s24, 0
	v_lshl_add_u64 v[152:153], s[2:3], 0, v[218:219]
	s_add_i32 m0, s11, 0xc000
	ds_read_b128 v[48:51], v227
	ds_read_b128 v[52:55], v227 offset:1024
	ds_read_b128 v[56:59], v227 offset:2048
	ds_read_b128 v[60:63], v227 offset:3072
	ds_read_b128 v[136:139], v227 offset:4096
	ds_read_b128 v[140:143], v227 offset:5120
	ds_read_b128 v[144:147], v227 offset:6144
	ds_read_b128 v[148:151], v227 offset:7168
	global_load_lds_dwordx4 v[152:153], off
	v_lshl_add_u64 v[152:153], s[2:3], 0, v[222:223]
	s_add_i32 m0, s11, 0xe000
	s_nop 0
	global_load_lds_dwordx4 v[152:153], off
	s_waitcnt vmcnt(8)
	s_waitcnt lgkmcnt(0)
	s_barrier
	s_setprio 1
	v_mfma_f32_16x16x32_bf16 v[152:155], v[16:19], v[48:51], v[164:167]
	v_mfma_f32_16x16x32_bf16 v[152:155], v[20:23], v[52:55], v[152:155]
	v_mfma_f32_16x16x32_bf16 v[160:163], v[16:19], v[56:59], v[160:163]
	v_mfma_f32_16x16x32_bf16 v[160:163], v[20:23], v[60:63], v[160:163]
	v_mfma_f32_16x16x32_bf16 v[108:111], v[16:19], v[136:139], v[108:111]
	v_mfma_f32_16x16x32_bf16 v[108:111], v[20:23], v[140:143], v[108:111]
	v_mfma_f32_16x16x32_bf16 v[164:167], v[16:19], v[144:147], v[168:171]
	v_mfma_f32_16x16x32_bf16 v[168:171], v[20:23], v[148:151], v[164:167]
	v_mfma_f32_16x16x32_bf16 v[64:67], v[24:27], v[48:51], v[64:67]
	v_mfma_f32_16x16x32_bf16 v[64:67], v[28:31], v[52:55], v[64:67]
	v_mfma_f32_16x16x32_bf16 v[156:159], v[24:27], v[56:59], v[156:159]
	v_mfma_f32_16x16x32_bf16 v[156:159], v[28:31], v[60:63], v[156:159]
	v_mfma_f32_16x16x32_bf16 v[104:107], v[24:27], v[136:139], v[104:107]
	v_mfma_f32_16x16x32_bf16 v[104:107], v[28:31], v[140:143], v[104:107]
	v_mfma_f32_16x16x32_bf16 v[68:71], v[24:27], v[144:147], v[68:71]
	v_mfma_f32_16x16x32_bf16 v[68:71], v[28:31], v[148:151], v[68:71]
	v_mfma_f32_16x16x32_bf16 v[88:91], v[32:35], v[48:51], v[88:91]
	v_mfma_f32_16x16x32_bf16 v[88:91], v[36:39], v[52:55], v[88:91]
	v_mfma_f32_16x16x32_bf16 v[48:51], v[40:43], v[48:51], v[72:75]
	v_mfma_f32_16x16x32_bf16 v[48:51], v[44:47], v[52:55], v[48:51]
	v_mfma_f32_16x16x32_bf16 v[72:75], v[40:43], v[136:139], v[96:99]
	v_mfma_f32_16x16x32_bf16 v[96:99], v[44:47], v[140:143], v[72:75]
	v_mfma_f32_16x16x32_bf16 v[72:75], v[32:35], v[144:147], v[92:95]
	v_mfma_f32_16x16x32_bf16 v[92:95], v[36:39], v[148:151], v[72:75]
	v_mfma_f32_16x16x32_bf16 v[52:55], v[32:35], v[56:59], v[132:135]
	v_mfma_f32_16x16x32_bf16 v[52:55], v[36:39], v[60:63], v[52:55]
	v_mfma_f32_16x16x32_bf16 v[56:59], v[40:43], v[56:59], v[128:131]
	v_mfma_f32_16x16x32_bf16 v[56:59], v[44:47], v[60:63], v[56:59]
	v_mfma_f32_16x16x32_bf16 v[72:75], v[40:43], v[144:147], v[76:79]
	v_mfma_f32_16x16x32_bf16 v[76:79], v[44:47], v[148:151], v[72:75]
	v_mfma_f32_16x16x32_bf16 v[60:63], v[32:35], v[136:139], v[100:103]
	v_mfma_f32_16x16x32_bf16 v[60:63], v[36:39], v[140:143], v[60:63]
	s_setprio 0
	s_barrier
	s_nop 1
	s_add_i32 s2, s25, s79
	v_lshl_add_u64 v[214:215], s[20:21], 0, v[220:221]
	s_mov_b32 m0, s2
	ds_read_b128 v[72:75], v227 offset:16384
	ds_read_b128 v[100:103], v227 offset:17408
	ds_read_b128 v[128:131], v227 offset:18432
	ds_read_b128 v[132:135], v227 offset:19456
	ds_read_b128 v[136:139], v227 offset:20480
	ds_read_b128 v[140:143], v227 offset:21504
	ds_read_b128 v[144:147], v227 offset:22528
	ds_read_b128 v[148:151], v227 offset:23552
	global_load_lds_dwordx4 v[214:215], off
	s_add_i32 m0, s2, 0x2000
	s_add_u32 s2, s20, 0x80000
	v_lshl_add_u64 v[216:217], s[20:21], 0, v[224:225]
	s_addc_u32 s3, s21, 0
	s_add_i32 s24, s26, s79
	global_load_lds_dwordx4 v[216:217], off
	v_lshl_add_u64 v[164:165], s[2:3], 0, v[220:221]
	s_mov_b32 m0, s24
	v_lshl_add_u64 v[230:231], s[22:23], 0, v[218:219]
	global_load_lds_dwordx4 v[164:165], off
	v_lshl_add_u64 v[164:165], s[2:3], 0, v[224:225]
	s_add_i32 m0, s24, 0x2000
	v_lshl_add_u64 v[232:233], s[22:23], 0, v[222:223]
	global_load_lds_dwordx4 v[164:165], off
	s_mov_b32 m0, s11
	s_nop 0
	global_load_lds_dwordx4 v[230:231], off
	s_mov_b32 m0, s88
	s_nop 0
	global_load_lds_dwordx4 v[232:233], off
	s_waitcnt vmcnt(8)
	s_waitcnt lgkmcnt(0)
	s_barrier
	s_setprio 1
	v_mfma_f32_16x16x32_bf16 v[80:83], v[16:19], v[72:75], v[80:83]
	v_mfma_f32_16x16x32_bf16 v[80:83], v[20:23], v[100:103], v[80:83]
	v_mfma_f32_16x16x32_bf16 v[12:15], v[16:19], v[128:131], v[12:15]
	v_mfma_f32_16x16x32_bf16 v[12:15], v[20:23], v[132:135], v[12:15]
	v_mfma_f32_16x16x32_bf16 v[124:127], v[16:19], v[136:139], v[124:127]
	v_mfma_f32_16x16x32_bf16 v[124:127], v[20:23], v[140:143], v[124:127]
	v_mfma_f32_16x16x32_bf16 v[8:11], v[24:27], v[128:131], v[8:11]
	v_mfma_f32_16x16x32_bf16 v[8:11], v[28:31], v[132:135], v[8:11]
	v_mfma_f32_16x16x32_bf16 v[120:123], v[24:27], v[136:139], v[120:123]
	v_mfma_f32_16x16x32_bf16 v[120:123], v[28:31], v[140:143], v[120:123]
	v_mfma_f32_16x16x32_bf16 v[16:19], v[16:19], v[144:147], v[84:87]
	v_mfma_f32_16x16x32_bf16 v[16:19], v[20:23], v[148:151], v[16:19]
	v_mfma_f32_16x16x32_bf16 v[164:167], v[24:27], v[72:75], v[196:199]
	v_mfma_f32_16x16x32_bf16 v[176:179], v[28:31], v[100:103], v[164:167]
	v_mfma_f32_16x16x32_bf16 v[20:23], v[24:27], v[144:147], v[200:203]
	v_mfma_f32_16x16x32_bf16 v[20:23], v[28:31], v[148:151], v[20:23]
	v_mfma_f32_16x16x32_bf16 v[24:27], v[32:35], v[72:75], v[172:175]
	v_mfma_f32_16x16x32_bf16 v[24:27], v[36:39], v[100:103], v[24:27]
	v_mfma_f32_16x16x32_bf16 v[4:7], v[32:35], v[128:131], v[4:7]
	v_mfma_f32_16x16x32_bf16 v[4:7], v[36:39], v[132:135], v[4:7]
	v_mfma_f32_16x16x32_bf16 v[28:31], v[40:43], v[72:75], v[188:191]
	v_mfma_f32_16x16x32_bf16 v[28:31], v[44:47], v[100:103], v[28:31]
	v_mfma_f32_16x16x32_bf16 v[72:75], v[32:35], v[136:139], v[116:119]
	v_mfma_f32_16x16x32_bf16 v[116:119], v[36:39], v[140:143], v[72:75]
	v_mfma_f32_16x16x32_bf16 v[0:3], v[40:43], v[128:131], v[0:3]
	v_mfma_f32_16x16x32_bf16 v[0:3], v[44:47], v[132:135], v[0:3]
	v_mfma_f32_16x16x32_bf16 v[72:75], v[40:43], v[136:139], v[112:115]
	v_mfma_f32_16x16x32_bf16 v[112:115], v[44:47], v[140:143], v[72:75]
	v_mfma_f32_16x16x32_bf16 v[32:35], v[32:35], v[144:147], v[180:183]
	v_mfma_f32_16x16x32_bf16 v[32:35], v[36:39], v[148:151], v[32:35]
	v_mfma_f32_16x16x32_bf16 v[36:39], v[40:43], v[144:147], v[192:195]
	v_mfma_f32_16x16x32_bf16 v[36:39], v[44:47], v[148:151], v[36:39]
	s_setprio 0
	s_barrier
	s_nop 1
	s_add_i32 s24, 0, 0x18000
	v_add_u32_e32 v72, s24, v226
	s_add_i32 s25, 0, 0x1c000
	ds_read_b128 v[40:43], v72
	ds_read_b128 v[44:47], v72 offset:1024
	ds_read_b128 v[136:139], v72 offset:2048
	ds_read_b128 v[140:143], v72 offset:3072
	v_add_u32_e32 v72, s25, v226
	ds_read_b128 v[144:147], v72
	ds_read_b128 v[148:151], v72 offset:1024
	ds_read_b128 v[184:187], v72 offset:2048
	ds_read_b128 v[192:195], v72 offset:3072
	s_add_u32 s2, s22, 0x80000
	s_addc_u32 s3, s23, 0
	s_mov_b32 m0, s89
	v_lshl_add_u64 v[132:133], s[2:3], 0, v[218:219]
	ds_read_b128 v[72:75], v227 offset:32768
	ds_read_b128 v[84:87], v227 offset:33792
	ds_read_b128 v[100:103], v227 offset:34816
	ds_read_b128 v[128:131], v227 offset:35840
	ds_read_b128 v[172:175], v227 offset:36864
	ds_read_b128 v[180:183], v227 offset:37888
	ds_read_b128 v[188:191], v227 offset:38912
	ds_read_b128 v[196:199], v227 offset:39936
	global_load_lds_dwordx4 v[132:133], off
	v_lshl_add_u64 v[132:133], s[2:3], 0, v[222:223]
	s_mov_b32 m0, s76
	s_nop 0
	global_load_lds_dwordx4 v[132:133], off
	s_waitcnt vmcnt(8)
	s_waitcnt lgkmcnt(0)
	s_barrier
	s_setprio 1
	v_mfma_f32_16x16x32_bf16 v[132:135], v[40:43], v[72:75], v[152:155]
	v_mfma_f32_16x16x32_bf16 v[164:167], v[44:47], v[84:87], v[132:135]
	v_mfma_f32_16x16x32_bf16 v[108:111], v[40:43], v[172:175], v[108:111]
	v_mfma_f32_16x16x32_bf16 v[108:111], v[44:47], v[180:183], v[108:111]
	v_mfma_f32_16x16x32_bf16 v[132:135], v[40:43], v[100:103], v[160:163]
	v_mfma_f32_16x16x32_bf16 v[160:163], v[44:47], v[128:131], v[132:135]
	v_mfma_f32_16x16x32_bf16 v[132:135], v[136:139], v[100:103], v[156:159]
	v_mfma_f32_16x16x32_bf16 v[156:159], v[140:143], v[128:131], v[132:135]
	v_mfma_f32_16x16x32_bf16 v[132:135], v[40:43], v[188:191], v[168:171]
	v_mfma_f32_16x16x32_bf16 v[168:171], v[44:47], v[196:199], v[132:135]
	v_mfma_f32_16x16x32_bf16 v[64:67], v[136:139], v[72:75], v[64:67]
	v_mfma_f32_16x16x32_bf16 v[64:67], v[140:143], v[84:87], v[64:67]
	v_mfma_f32_16x16x32_bf16 v[104:107], v[136:139], v[172:175], v[104:107]
	v_mfma_f32_16x16x32_bf16 v[104:107], v[140:143], v[180:183], v[104:107]
	v_mfma_f32_16x16x32_bf16 v[68:71], v[136:139], v[188:191], v[68:71]
	v_mfma_f32_16x16x32_bf16 v[68:71], v[140:143], v[196:199], v[68:71]
	v_mfma_f32_16x16x32_bf16 v[48:51], v[184:187], v[72:75], v[48:51]
	v_mfma_f32_16x16x32_bf16 v[88:91], v[144:147], v[72:75], v[88:91]
	v_mfma_f32_16x16x32_bf16 v[88:91], v[148:151], v[84:87], v[88:91]
	v_mfma_f32_16x16x32_bf16 v[72:75], v[192:195], v[84:87], v[48:51]
	v_mfma_f32_16x16x32_bf16 v[48:51], v[144:147], v[100:103], v[52:55]
	v_mfma_f32_16x16x32_bf16 v[132:135], v[148:151], v[128:131], v[48:51]
	v_mfma_f32_16x16x32_bf16 v[48:51], v[184:187], v[100:103], v[56:59]
	v_mfma_f32_16x16x32_bf16 v[128:131], v[192:195], v[128:131], v[48:51]
	v_mfma_f32_16x16x32_bf16 v[48:51], v[144:147], v[172:175], v[60:63]
	v_mfma_f32_16x16x32_bf16 v[100:103], v[148:151], v[180:183], v[48:51]
	v_mfma_f32_16x16x32_bf16 v[48:51], v[184:187], v[172:175], v[96:99]
	v_mfma_f32_16x16x32_bf16 v[96:99], v[192:195], v[180:183], v[48:51]
	v_mfma_f32_16x16x32_bf16 v[48:51], v[144:147], v[188:191], v[92:95]
	v_mfma_f32_16x16x32_bf16 v[92:95], v[148:151], v[196:199], v[48:51]
	v_mfma_f32_16x16x32_bf16 v[48:51], v[184:187], v[188:191], v[76:79]
	v_mfma_f32_16x16x32_bf16 v[76:79], v[192:195], v[196:199], v[48:51]
	s_setprio 0
	s_barrier
	s_nop 1
	s_add_i32 s2, s24, s79
	v_lshl_add_u64 v[84:85], v[214:215], 0, s[72:73]
	s_mov_b32 m0, s2
	s_nop 0
	ds_read_b128 v[48:51], v227 offset:49152
	ds_read_b128 v[52:55], v227 offset:50176
	ds_read_b128 v[56:59], v227 offset:51200
	ds_read_b128 v[60:63], v227 offset:52224
	ds_read_b128 v[152:155], v227 offset:53248
	ds_read_b128 v[180:183], v227 offset:54272
	ds_read_b128 v[204:207], v227 offset:55296
	ds_read_b128 v[208:211], v227 offset:56320
	global_load_lds_dwordx4 v[84:85], off
	s_add_i32 m0, s2, 0x2000
	s_add_u32 s2, s20, 0x80080
	v_lshl_add_u64 v[84:85], v[216:217], 0, s[72:73]
	s_addc_u32 s3, s21, 0
	s_add_i32 s20, s25, s79
	global_load_lds_dwordx4 v[84:85], off
	v_lshl_add_u64 v[84:85], s[2:3], 0, v[220:221]
	s_mov_b32 m0, s20
	s_nop 0
	global_load_lds_dwordx4 v[84:85], off
	v_lshl_add_u64 v[84:85], s[2:3], 0, v[224:225]
	s_add_i32 m0, s20, 0x2000
	s_nop 0
	global_load_lds_dwordx4 v[84:85], off
	v_lshl_add_u64 v[84:85], v[230:231], 0, s[72:73]
	s_mov_b32 m0, s67
	s_nop 0
	global_load_lds_dwordx4 v[84:85], off
	v_lshl_add_u64 v[84:85], v[232:233], 0, s[72:73]
	s_mov_b32 m0, s84
	s_nop 0
	global_load_lds_dwordx4 v[84:85], off
	s_waitcnt vmcnt(8)
	s_waitcnt lgkmcnt(0)
	s_barrier
	s_setprio 1
	v_mfma_f32_16x16x32_bf16 v[84:87], v[136:139], v[48:51], v[176:179]
	v_mfma_f32_16x16x32_bf16 v[196:199], v[140:143], v[52:55], v[84:87]
	v_mfma_f32_16x16x32_bf16 v[12:15], v[40:43], v[56:59], v[12:15]
	v_mfma_f32_16x16x32_bf16 v[12:15], v[44:47], v[60:63], v[12:15]
	v_mfma_f32_16x16x32_bf16 v[84:87], v[40:43], v[152:155], v[124:127]
	v_mfma_f32_16x16x32_bf16 v[124:127], v[44:47], v[180:183], v[84:87]
	v_mfma_f32_16x16x32_bf16 v[84:87], v[136:139], v[152:155], v[120:123]
	v_mfma_f32_16x16x32_bf16 v[120:123], v[140:143], v[180:183], v[84:87]
	v_mfma_f32_16x16x32_bf16 v[16:19], v[40:43], v[204:207], v[16:19]
	v_mfma_f32_16x16x32_bf16 v[84:87], v[44:47], v[208:211], v[16:19]
	v_mfma_f32_16x16x32_bf16 v[80:83], v[40:43], v[48:51], v[80:83]
	v_mfma_f32_16x16x32_bf16 v[80:83], v[44:47], v[52:55], v[80:83]
	v_mfma_f32_16x16x32_bf16 v[8:11], v[136:139], v[56:59], v[8:11]
	v_mfma_f32_16x16x32_bf16 v[8:11], v[140:143], v[60:63], v[8:11]
	v_mfma_f32_16x16x32_bf16 v[16:19], v[136:139], v[204:207], v[20:23]
	v_mfma_f32_16x16x32_bf16 v[200:203], v[140:143], v[208:211], v[16:19]
	v_mfma_f32_16x16x32_bf16 v[4:7], v[144:147], v[56:59], v[4:7]
	v_mfma_f32_16x16x32_bf16 v[4:7], v[148:151], v[60:63], v[4:7]
	v_mfma_f32_16x16x32_bf16 v[16:19], v[144:147], v[48:51], v[24:27]
	v_mfma_f32_16x16x32_bf16 v[172:175], v[148:151], v[52:55], v[16:19]
	v_mfma_f32_16x16x32_bf16 v[16:19], v[184:187], v[48:51], v[28:31]
	v_mfma_f32_16x16x32_bf16 v[188:191], v[192:195], v[52:55], v[16:19]
	v_mfma_f32_16x16x32_bf16 v[16:19], v[144:147], v[152:155], v[116:119]
	v_mfma_f32_16x16x32_bf16 v[116:119], v[148:151], v[180:183], v[16:19]
	v_mfma_f32_16x16x32_bf16 v[16:19], v[184:187], v[152:155], v[112:115]
	v_mfma_f32_16x16x32_bf16 v[112:115], v[192:195], v[180:183], v[16:19]
	v_mfma_f32_16x16x32_bf16 v[16:19], v[144:147], v[204:207], v[32:35]
	v_mfma_f32_16x16x32_bf16 v[180:183], v[148:151], v[208:211], v[16:19]
	v_mfma_f32_16x16x32_bf16 v[0:3], v[184:187], v[56:59], v[0:3]
	v_mfma_f32_16x16x32_bf16 v[0:3], v[192:195], v[60:63], v[0:3]
	v_mfma_f32_16x16x32_bf16 v[16:19], v[184:187], v[204:207], v[36:39]
	v_mfma_f32_16x16x32_bf16 v[192:195], v[192:195], v[208:211], v[16:19]
	s_setprio 0
	s_barrier
	s_nop 1
	s_add_i32 s2, s9, 2
	s_cmp_gt_u32 s9, 29
	s_mov_b32 s9, s2
	s_cbranch_scc1 .LBB0_1436

.LBB0_1660:
	s_add_i32 s2, s28, 2
	s_add_u32 s3, s12, s26
	s_addc_u32 s29, s13, s27
	s_add_u32 s3, s3, 0x100
	s_addc_u32 s29, s29, 0
	s_add_u32 s55, s15, s26
	s_addc_u32 s63, s41, s27
	s_cmp_eq_u32 s40, s28
	s_cselect_b32 s31, s75, s29
	s_cselect_b32 s30, s74, s3
	s_cselect_b32 s29, s9, s63
	s_cselect_b32 s28, s8, s55
	s_add_i32 s3, 0, 0x10000
	s_add_i32 s55, 0, 0x14000
	v_add_u32_e32 v112, s3, v238
	v_add_u32_e32 v160, s55, v238
	ds_read_b128 v[76:79], v112
	ds_read_b128 v[88:91], v112 offset:1024
	ds_read_b128 v[100:103], v112 offset:2048
	ds_read_b128 v[112:115], v112 offset:3072
	ds_read_b128 v[124:127], v160
	ds_read_b128 v[136:139], v160 offset:1024
	ds_read_b128 v[148:151], v160 offset:2048
	ds_read_b128 v[160:163], v160 offset:3072
	v_lshl_add_u64 v[196:197], v[68:69], 0, s[26:27]
	s_add_i32 m0, s11, 0xc000
	ds_read_b128 v[164:167], v241
	ds_read_b128 v[168:171], v241 offset:1024
	ds_read_b128 v[172:175], v241 offset:2048
	ds_read_b128 v[176:179], v241 offset:3072
	ds_read_b128 v[180:183], v241 offset:4096
	ds_read_b128 v[184:187], v241 offset:5120
	ds_read_b128 v[188:191], v241 offset:6144
	ds_read_b128 v[192:195], v241 offset:7168
	global_load_lds_dwordx4 v[196:197], off
	v_lshl_add_u64 v[196:197], v[70:71], 0, s[26:27]
	s_add_i32 m0, s11, 0xe000
	s_nop 0
	global_load_lds_dwordx4 v[196:197], off
	s_waitcnt vmcnt(8)
	s_waitcnt lgkmcnt(0)
	s_barrier
	s_setprio 1
	v_mfma_f32_16x16x32_bf16 v[156:159], v[76:79], v[164:167], v[156:159]
	v_mfma_f32_16x16x32_bf16 v[156:159], v[88:91], v[168:171], v[156:159]
	v_mfma_f32_16x16x32_bf16 v[144:147], v[76:79], v[172:175], v[144:147]
	v_mfma_f32_16x16x32_bf16 v[144:147], v[88:91], v[176:179], v[144:147]
	v_mfma_f32_16x16x32_bf16 v[132:135], v[76:79], v[180:183], v[132:135]
	v_mfma_f32_16x16x32_bf16 v[132:135], v[88:91], v[184:187], v[132:135]
	v_mfma_f32_16x16x32_bf16 v[120:123], v[76:79], v[188:191], v[120:123]
	v_mfma_f32_16x16x32_bf16 v[120:123], v[88:91], v[192:195], v[120:123]
	v_mfma_f32_16x16x32_bf16 v[152:155], v[100:103], v[164:167], v[152:155]
	v_mfma_f32_16x16x32_bf16 v[152:155], v[112:115], v[168:171], v[152:155]
	v_mfma_f32_16x16x32_bf16 v[140:143], v[100:103], v[172:175], v[140:143]
	v_mfma_f32_16x16x32_bf16 v[140:143], v[112:115], v[176:179], v[140:143]
	v_mfma_f32_16x16x32_bf16 v[128:131], v[100:103], v[180:183], v[128:131]
	v_mfma_f32_16x16x32_bf16 v[128:131], v[112:115], v[184:187], v[128:131]
	v_mfma_f32_16x16x32_bf16 v[116:119], v[100:103], v[188:191], v[116:119]
	v_mfma_f32_16x16x32_bf16 v[116:119], v[112:115], v[192:195], v[116:119]
	v_mfma_f32_16x16x32_bf16 v[108:111], v[124:127], v[164:167], v[108:111]
	v_mfma_f32_16x16x32_bf16 v[108:111], v[136:139], v[168:171], v[108:111]
	v_mfma_f32_16x16x32_bf16 v[96:99], v[124:127], v[172:175], v[96:99]
	v_mfma_f32_16x16x32_bf16 v[96:99], v[136:139], v[176:179], v[96:99]
	v_mfma_f32_16x16x32_bf16 v[84:87], v[124:127], v[180:183], v[84:87]
	v_mfma_f32_16x16x32_bf16 v[84:87], v[136:139], v[184:187], v[84:87]
	v_mfma_f32_16x16x32_bf16 v[72:75], v[124:127], v[188:191], v[72:75]
	v_mfma_f32_16x16x32_bf16 v[72:75], v[136:139], v[192:195], v[72:75]
	v_mfma_f32_16x16x32_bf16 v[104:107], v[148:151], v[164:167], v[104:107]
	v_mfma_f32_16x16x32_bf16 v[104:107], v[160:163], v[168:171], v[104:107]
	v_mfma_f32_16x16x32_bf16 v[92:95], v[148:151], v[172:175], v[92:95]
	v_mfma_f32_16x16x32_bf16 v[92:95], v[160:163], v[176:179], v[92:95]
	v_mfma_f32_16x16x32_bf16 v[80:83], v[148:151], v[180:183], v[80:83]
	v_mfma_f32_16x16x32_bf16 v[80:83], v[160:163], v[184:187], v[80:83]
	v_mfma_f32_16x16x32_bf16 v[64:67], v[148:151], v[188:191], v[64:67]
	v_mfma_f32_16x16x32_bf16 v[64:67], v[160:163], v[192:195], v[64:67]
	s_setprio 0
	s_barrier
	s_nop 1
	s_add_i32 s3, s3, s33
	v_lshl_add_u64 v[196:197], s[28:29], 0, v[210:211]
	s_mov_b32 m0, s3
	ds_read_b128 v[164:167], v241 offset:16384
	ds_read_b128 v[168:171], v241 offset:17408
	ds_read_b128 v[172:175], v241 offset:18432
	ds_read_b128 v[176:179], v241 offset:19456
	ds_read_b128 v[180:183], v241 offset:20480
	ds_read_b128 v[184:187], v241 offset:21504
	ds_read_b128 v[188:191], v241 offset:22528
	ds_read_b128 v[192:195], v241 offset:23552
	global_load_lds_dwordx4 v[196:197], off
	s_add_i32 m0, s3, 0x2000
	s_add_u32 vcc_lo, s28, 0x160000
	v_lshl_add_u64 v[198:199], s[28:29], 0, v[220:221]
	s_addc_u32 vcc_hi, s29, 0
	s_add_i32 s3, s55, s33
	global_load_lds_dwordx4 v[198:199], off
	v_lshl_add_u64 v[200:201], vcc, 0, v[210:211]
	s_mov_b32 m0, s3
	v_lshl_add_u64 v[202:203], s[30:31], 0, v[218:219]
	global_load_lds_dwordx4 v[200:201], off
	v_lshl_add_u64 v[200:201], vcc, 0, v[220:221]
	s_add_i32 m0, s3, 0x2000
	s_nop 0
	global_load_lds_dwordx4 v[200:201], off
	v_lshl_add_u64 v[200:201], s[30:31], 0, v[208:209]
	s_mov_b32 m0, s11
	s_nop 0
	global_load_lds_dwordx4 v[200:201], off
	s_mov_b32 m0, s65
	s_nop 0
	global_load_lds_dwordx4 v[202:203], off
	s_waitcnt vmcnt(8)
	s_waitcnt lgkmcnt(0)
	s_barrier
	s_setprio 1
	v_mfma_f32_16x16x32_bf16 v[60:63], v[76:79], v[164:167], v[60:63]
	v_mfma_f32_16x16x32_bf16 v[60:63], v[88:91], v[168:171], v[60:63]
	v_mfma_f32_16x16x32_bf16 v[52:55], v[76:79], v[172:175], v[52:55]
	v_mfma_f32_16x16x32_bf16 v[52:55], v[88:91], v[176:179], v[52:55]
	v_mfma_f32_16x16x32_bf16 v[44:47], v[76:79], v[180:183], v[44:47]
	v_mfma_f32_16x16x32_bf16 v[44:47], v[88:91], v[184:187], v[44:47]
	v_mfma_f32_16x16x32_bf16 v[36:39], v[76:79], v[188:191], v[36:39]
	v_mfma_f32_16x16x32_bf16 v[36:39], v[88:91], v[192:195], v[36:39]
	v_mfma_f32_16x16x32_bf16 v[56:59], v[100:103], v[164:167], v[56:59]
	v_mfma_f32_16x16x32_bf16 v[56:59], v[112:115], v[168:171], v[56:59]
	v_mfma_f32_16x16x32_bf16 v[48:51], v[100:103], v[172:175], v[48:51]
	v_mfma_f32_16x16x32_bf16 v[48:51], v[112:115], v[176:179], v[48:51]
	v_mfma_f32_16x16x32_bf16 v[40:43], v[100:103], v[180:183], v[40:43]
	v_mfma_f32_16x16x32_bf16 v[40:43], v[112:115], v[184:187], v[40:43]
	v_mfma_f32_16x16x32_bf16 v[32:35], v[100:103], v[188:191], v[32:35]
	v_mfma_f32_16x16x32_bf16 v[32:35], v[112:115], v[192:195], v[32:35]
	v_mfma_f32_16x16x32_bf16 v[28:31], v[124:127], v[164:167], v[28:31]
	v_mfma_f32_16x16x32_bf16 v[28:31], v[136:139], v[168:171], v[28:31]
	v_mfma_f32_16x16x32_bf16 v[20:23], v[124:127], v[172:175], v[20:23]
	v_mfma_f32_16x16x32_bf16 v[20:23], v[136:139], v[176:179], v[20:23]
	v_mfma_f32_16x16x32_bf16 v[12:15], v[124:127], v[180:183], v[12:15]
	v_mfma_f32_16x16x32_bf16 v[12:15], v[136:139], v[184:187], v[12:15]
	v_mfma_f32_16x16x32_bf16 v[4:7], v[124:127], v[188:191], v[4:7]
	v_mfma_f32_16x16x32_bf16 v[4:7], v[136:139], v[192:195], v[4:7]
	v_mfma_f32_16x16x32_bf16 v[24:27], v[148:151], v[164:167], v[24:27]
	v_mfma_f32_16x16x32_bf16 v[24:27], v[160:163], v[168:171], v[24:27]
	v_mfma_f32_16x16x32_bf16 v[16:19], v[148:151], v[172:175], v[16:19]
	v_mfma_f32_16x16x32_bf16 v[16:19], v[160:163], v[176:179], v[16:19]
	v_mfma_f32_16x16x32_bf16 v[8:11], v[148:151], v[180:183], v[8:11]
	v_mfma_f32_16x16x32_bf16 v[8:11], v[160:163], v[184:187], v[8:11]
	v_mfma_f32_16x16x32_bf16 v[0:3], v[148:151], v[188:191], v[0:3]
	v_mfma_f32_16x16x32_bf16 v[0:3], v[160:163], v[192:195], v[0:3]
	s_setprio 0
	s_barrier
	s_nop 1
	s_add_i32 s3, 0, 0x18000
	s_add_i32 s55, 0, 0x1c000
	v_add_u32_e32 v112, s3, v238
	v_add_u32_e32 v160, s55, v238
	ds_read_b128 v[76:79], v112
	ds_read_b128 v[88:91], v112 offset:1024
	ds_read_b128 v[100:103], v112 offset:2048
	ds_read_b128 v[112:115], v112 offset:3072
	ds_read_b128 v[124:127], v160
	ds_read_b128 v[136:139], v160 offset:1024
	ds_read_b128 v[148:151], v160 offset:2048
	ds_read_b128 v[160:163], v160 offset:3072
	s_add_u32 s30, s30, 0x160000
	s_addc_u32 s31, s31, 0
	s_mov_b32 m0, s34
	v_lshl_add_u64 v[204:205], s[30:31], 0, v[208:209]
	ds_read_b128 v[164:167], v241 offset:32768
	ds_read_b128 v[168:171], v241 offset:33792
	ds_read_b128 v[172:175], v241 offset:34816
	ds_read_b128 v[176:179], v241 offset:35840
	ds_read_b128 v[180:183], v241 offset:36864
	ds_read_b128 v[184:187], v241 offset:37888
	ds_read_b128 v[188:191], v241 offset:38912
	ds_read_b128 v[192:195], v241 offset:39936
	global_load_lds_dwordx4 v[204:205], off
	v_lshl_add_u64 v[204:205], s[30:31], 0, v[218:219]
	s_mov_b32 m0, s67
	s_nop 0
	global_load_lds_dwordx4 v[204:205], off
	s_waitcnt vmcnt(8)
	s_waitcnt lgkmcnt(0)
	s_barrier
	s_setprio 1
	v_mfma_f32_16x16x32_bf16 v[156:159], v[76:79], v[164:167], v[156:159]
	v_mfma_f32_16x16x32_bf16 v[156:159], v[88:91], v[168:171], v[156:159]
	v_mfma_f32_16x16x32_bf16 v[144:147], v[76:79], v[172:175], v[144:147]
	v_mfma_f32_16x16x32_bf16 v[144:147], v[88:91], v[176:179], v[144:147]
	v_mfma_f32_16x16x32_bf16 v[132:135], v[76:79], v[180:183], v[132:135]
	v_mfma_f32_16x16x32_bf16 v[132:135], v[88:91], v[184:187], v[132:135]
	v_mfma_f32_16x16x32_bf16 v[120:123], v[76:79], v[188:191], v[120:123]
	v_mfma_f32_16x16x32_bf16 v[120:123], v[88:91], v[192:195], v[120:123]
	v_mfma_f32_16x16x32_bf16 v[152:155], v[100:103], v[164:167], v[152:155]
	v_mfma_f32_16x16x32_bf16 v[152:155], v[112:115], v[168:171], v[152:155]
	v_mfma_f32_16x16x32_bf16 v[140:143], v[100:103], v[172:175], v[140:143]
	v_mfma_f32_16x16x32_bf16 v[140:143], v[112:115], v[176:179], v[140:143]
	v_mfma_f32_16x16x32_bf16 v[128:131], v[100:103], v[180:183], v[128:131]
	v_mfma_f32_16x16x32_bf16 v[128:131], v[112:115], v[184:187], v[128:131]
	v_mfma_f32_16x16x32_bf16 v[116:119], v[100:103], v[188:191], v[116:119]
	v_mfma_f32_16x16x32_bf16 v[116:119], v[112:115], v[192:195], v[116:119]
	v_mfma_f32_16x16x32_bf16 v[108:111], v[124:127], v[164:167], v[108:111]
	v_mfma_f32_16x16x32_bf16 v[108:111], v[136:139], v[168:171], v[108:111]
	v_mfma_f32_16x16x32_bf16 v[96:99], v[124:127], v[172:175], v[96:99]
	v_mfma_f32_16x16x32_bf16 v[96:99], v[136:139], v[176:179], v[96:99]
	v_mfma_f32_16x16x32_bf16 v[84:87], v[124:127], v[180:183], v[84:87]
	v_mfma_f32_16x16x32_bf16 v[84:87], v[136:139], v[184:187], v[84:87]
	v_mfma_f32_16x16x32_bf16 v[72:75], v[124:127], v[188:191], v[72:75]
	v_mfma_f32_16x16x32_bf16 v[72:75], v[136:139], v[192:195], v[72:75]
	v_mfma_f32_16x16x32_bf16 v[104:107], v[148:151], v[164:167], v[104:107]
	v_mfma_f32_16x16x32_bf16 v[104:107], v[160:163], v[168:171], v[104:107]
	v_mfma_f32_16x16x32_bf16 v[92:95], v[148:151], v[172:175], v[92:95]
	v_mfma_f32_16x16x32_bf16 v[92:95], v[160:163], v[176:179], v[92:95]
	v_mfma_f32_16x16x32_bf16 v[80:83], v[148:151], v[180:183], v[80:83]
	v_mfma_f32_16x16x32_bf16 v[80:83], v[160:163], v[184:187], v[80:83]
	v_mfma_f32_16x16x32_bf16 v[64:67], v[148:151], v[188:191], v[64:67]
	v_mfma_f32_16x16x32_bf16 v[64:67], v[160:163], v[192:195], v[64:67]
	s_setprio 0
	s_barrier
	s_nop 1
	s_add_i32 s3, s3, s33
	v_lshl_add_u64 v[196:197], v[196:197], 0, s[72:73]
	s_mov_b32 m0, s3
	ds_read_b128 v[164:167], v241 offset:49152
	ds_read_b128 v[168:171], v241 offset:50176
	ds_read_b128 v[172:175], v241 offset:51200
	ds_read_b128 v[176:179], v241 offset:52224
	ds_read_b128 v[180:183], v241 offset:53248
	ds_read_b128 v[184:187], v241 offset:54272
	ds_read_b128 v[188:191], v241 offset:55296
	ds_read_b128 v[192:195], v241 offset:56320
	global_load_lds_dwordx4 v[196:197], off
	s_add_i32 m0, s3, 0x2000
	s_add_u32 s28, s28, 0x160080
	v_lshl_add_u64 v[196:197], v[198:199], 0, s[72:73]
	s_addc_u32 s29, s29, 0
	s_add_i32 s3, s55, s33
	global_load_lds_dwordx4 v[196:197], off
	v_lshl_add_u64 v[196:197], s[28:29], 0, v[210:211]
	s_mov_b32 m0, s3
	s_nop 0
	global_load_lds_dwordx4 v[196:197], off
	v_lshl_add_u64 v[196:197], s[28:29], 0, v[220:221]
	s_add_i32 m0, s3, 0x2000
	s_nop 0
	global_load_lds_dwordx4 v[196:197], off
	v_lshl_add_u64 v[196:197], v[200:201], 0, s[72:73]
	s_mov_b32 m0, s81
	s_nop 0
	global_load_lds_dwordx4 v[196:197], off
	v_lshl_add_u64 v[196:197], v[202:203], 0, s[72:73]
	s_mov_b32 m0, s82
	s_nop 0
	global_load_lds_dwordx4 v[196:197], off
	s_waitcnt vmcnt(8)
	s_waitcnt lgkmcnt(0)
	s_barrier
	s_setprio 1
	v_mfma_f32_16x16x32_bf16 v[60:63], v[76:79], v[164:167], v[60:63]
	v_mfma_f32_16x16x32_bf16 v[60:63], v[88:91], v[168:171], v[60:63]
	v_mfma_f32_16x16x32_bf16 v[52:55], v[76:79], v[172:175], v[52:55]
	v_mfma_f32_16x16x32_bf16 v[52:55], v[88:91], v[176:179], v[52:55]
	v_mfma_f32_16x16x32_bf16 v[44:47], v[76:79], v[180:183], v[44:47]
	v_mfma_f32_16x16x32_bf16 v[44:47], v[88:91], v[184:187], v[44:47]
	v_mfma_f32_16x16x32_bf16 v[36:39], v[76:79], v[188:191], v[36:39]
	v_mfma_f32_16x16x32_bf16 v[36:39], v[88:91], v[192:195], v[36:39]
	v_mfma_f32_16x16x32_bf16 v[56:59], v[100:103], v[164:167], v[56:59]
	v_mfma_f32_16x16x32_bf16 v[56:59], v[112:115], v[168:171], v[56:59]
	v_mfma_f32_16x16x32_bf16 v[48:51], v[100:103], v[172:175], v[48:51]
	v_mfma_f32_16x16x32_bf16 v[48:51], v[112:115], v[176:179], v[48:51]
	v_mfma_f32_16x16x32_bf16 v[40:43], v[100:103], v[180:183], v[40:43]
	v_mfma_f32_16x16x32_bf16 v[40:43], v[112:115], v[184:187], v[40:43]
	v_mfma_f32_16x16x32_bf16 v[32:35], v[100:103], v[188:191], v[32:35]
	v_mfma_f32_16x16x32_bf16 v[32:35], v[112:115], v[192:195], v[32:35]
	v_mfma_f32_16x16x32_bf16 v[28:31], v[124:127], v[164:167], v[28:31]
	v_mfma_f32_16x16x32_bf16 v[28:31], v[136:139], v[168:171], v[28:31]
	v_mfma_f32_16x16x32_bf16 v[20:23], v[124:127], v[172:175], v[20:23]
	v_mfma_f32_16x16x32_bf16 v[20:23], v[136:139], v[176:179], v[20:23]
	v_mfma_f32_16x16x32_bf16 v[12:15], v[124:127], v[180:183], v[12:15]
	v_mfma_f32_16x16x32_bf16 v[12:15], v[136:139], v[184:187], v[12:15]
	v_mfma_f32_16x16x32_bf16 v[4:7], v[124:127], v[188:191], v[4:7]
	v_mfma_f32_16x16x32_bf16 v[4:7], v[136:139], v[192:195], v[4:7]
	v_mfma_f32_16x16x32_bf16 v[24:27], v[148:151], v[164:167], v[24:27]
	v_mfma_f32_16x16x32_bf16 v[24:27], v[160:163], v[168:171], v[24:27]
	v_mfma_f32_16x16x32_bf16 v[16:19], v[148:151], v[172:175], v[16:19]
	v_mfma_f32_16x16x32_bf16 v[16:19], v[160:163], v[176:179], v[16:19]
	v_mfma_f32_16x16x32_bf16 v[8:11], v[148:151], v[180:183], v[8:11]
	v_mfma_f32_16x16x32_bf16 v[8:11], v[160:163], v[184:187], v[8:11]
	v_mfma_f32_16x16x32_bf16 v[0:3], v[148:151], v[188:191], v[0:3]
	v_mfma_f32_16x16x32_bf16 v[0:3], v[160:163], v[192:195], v[0:3]
	s_setprio 0
	s_barrier
	s_nop 1
	s_add_u32 s26, s26, 0x100
	s_addc_u32 s27, s27, 0
	s_cmp_ge_i32 s2, s17
	s_mov_b32 s28, s2
	s_cbranch_scc1 .LBB0_1669
